# S5 pass-1 merged unrolled loop with 8-quad rolling load window; pass-2 epilogue chained MFMA accumulator and folded gelu constants; final RMSNorm phase rewritten with batch-of-4 row prefetch and count
# speedup vs baseline: 1.0186x; 1.0078x over previous
.LBB0_154:
	s_and_b32 s15, s54, 0xffffe000
	v_or_b32_e32 v0, s15, v197
	v_ashrrev_i32_e32 v1, 31, v0
	s_lshr_b32 s3, s66, 3
	s_bfe_u32 s50, s65, 0x30003
	v_lshlrev_b64 v[64:65], 11, v[0:1]
	v_lshlrev_b32_e32 v0, 1, v146
	s_and_b32 s52, s3, 7
	v_lshl_or_b32 v0, s50, 8, v0
	v_lshl_or_b32 v148, s52, 5, v0
	v_add_u32_e32 v0, s2, v201
	s_lshl_b32 s51, s50, 19
	s_lshl_b32 s53, s52, 16
	v_ashrrev_i32_e32 v1, 31, v0
	s_or_b32 s51, s51, s53
	v_lshlrev_b64 v[0:1], 15, v[0:1]
	v_or_b32_e32 v180, s51, v144
	v_mov_b32_e32 v181, v145
	v_lshl_add_u64 v[66:67], v[0:1], 0, v[64:65]
	v_mov_b32_e32 v16, 0
	s_mov_b32 s3, 16
	v_or_b32_e32 v66, v66, v148
	v_mov_b64_e32 v[68:69], v[180:181]
	v_mov_b32_e32 v17, v16
	v_mov_b32_e32 v18, v16
	v_mov_b32_e32 v19, v16
	v_mov_b32_e32 v20, v16
	v_mov_b32_e32 v21, v16
	v_mov_b32_e32 v22, v16
	v_mov_b32_e32 v23, v16
	v_mov_b32_e32 v24, v16
	v_mov_b32_e32 v25, v16
	v_mov_b32_e32 v26, v16
	v_mov_b32_e32 v27, v16
	v_mov_b32_e32 v28, v16
	v_mov_b32_e32 v29, v16
	v_mov_b32_e32 v30, v16
	v_mov_b32_e32 v31, v16
	v_mov_b32_e32 v0, v16
	v_mov_b32_e32 v1, v16
	v_mov_b32_e32 v2, v16
	v_mov_b32_e32 v3, v16
	v_mov_b32_e32 v4, v16
	v_mov_b32_e32 v5, v16
	v_mov_b32_e32 v6, v16
	v_mov_b32_e32 v7, v16
	v_mov_b32_e32 v8, v16
	v_mov_b32_e32 v9, v16
	v_mov_b32_e32 v10, v16
	v_mov_b32_e32 v11, v16
	v_mov_b32_e32 v12, v16
	v_mov_b32_e32 v13, v16
	v_mov_b32_e32 v14, v16
	v_mov_b32_e32 v15, v16
	v_mov_b32_e32 v48, v16
	v_mov_b32_e32 v49, v16
	v_mov_b32_e32 v50, v16
	v_mov_b32_e32 v51, v16
	v_mov_b32_e32 v52, v16
	v_mov_b32_e32 v53, v16
	v_mov_b32_e32 v54, v16
	v_mov_b32_e32 v55, v16
	v_mov_b32_e32 v56, v16
	v_mov_b32_e32 v57, v16
	v_mov_b32_e32 v58, v16
	v_mov_b32_e32 v59, v16
	v_mov_b32_e32 v60, v16
	v_mov_b32_e32 v61, v16
	v_mov_b32_e32 v62, v16
	v_mov_b32_e32 v63, v16
	v_mov_b32_e32 v32, v16
	v_mov_b32_e32 v33, v16
	v_mov_b32_e32 v34, v16
	v_mov_b32_e32 v35, v16
	v_mov_b32_e32 v36, v16
	v_mov_b32_e32 v37, v16
	v_mov_b32_e32 v38, v16
	v_mov_b32_e32 v39, v16
	v_mov_b32_e32 v40, v16
	v_mov_b32_e32 v41, v16
	v_mov_b32_e32 v42, v16
	v_mov_b32_e32 v43, v16
	v_mov_b32_e32 v44, v16
	v_mov_b32_e32 v45, v16
	v_mov_b32_e32 v46, v16
	v_mov_b32_e32 v47, v16
	s_mov_b32 s98, s58
	s_mov_b32 s99, 0
	v_lshl_add_u64 v[244:245], s[62:63], 0, v[66:67]
	v_lshl_add_u64 v[244:245], v[244:245], 0, s[98:99]
	v_add_u32_e32 v66, s2, v202
	v_ashrrev_i32_e32 v67, 31, v66
	v_lshlrev_b64 v[66:67], 15, v[66:67]
	v_lshl_add_u64 v[64:65], v[66:67], 0, v[64:65]
	v_mov_b32_e32 v80, 0
	v_lshl_add_u64 v[182:183], v[64:65], 0, v[148:149]
	s_mov_b32 s2, 16
	v_mov_b32_e32 v81, v80
	v_mov_b32_e32 v82, v80
	v_mov_b32_e32 v83, v80
	v_mov_b32_e32 v84, v80
	v_mov_b32_e32 v85, v80
	v_mov_b32_e32 v86, v80
	v_mov_b32_e32 v87, v80
	v_mov_b32_e32 v88, v80
	v_mov_b32_e32 v89, v80
	v_mov_b32_e32 v90, v80
	v_mov_b32_e32 v91, v80
	v_mov_b32_e32 v92, v80
	v_mov_b32_e32 v93, v80
	v_mov_b32_e32 v94, v80
	v_mov_b32_e32 v95, v80
	v_mov_b32_e32 v64, v80
	v_mov_b32_e32 v65, v80
	v_mov_b32_e32 v66, v80
	v_mov_b32_e32 v67, v80
	v_mov_b32_e32 v68, v80
	v_mov_b32_e32 v69, v80
	v_mov_b32_e32 v70, v80
	v_mov_b32_e32 v71, v80
	v_mov_b32_e32 v72, v80
	v_mov_b32_e32 v73, v80
	v_mov_b32_e32 v74, v80
	v_mov_b32_e32 v75, v80
	v_mov_b32_e32 v76, v80
	v_mov_b32_e32 v77, v80
	v_mov_b32_e32 v78, v80
	v_mov_b32_e32 v79, v80
	v_mov_b32_e32 v112, v80
	v_mov_b32_e32 v113, v80
	v_mov_b32_e32 v114, v80
	v_mov_b32_e32 v115, v80
	v_mov_b32_e32 v116, v80
	v_mov_b32_e32 v117, v80
	v_mov_b32_e32 v118, v80
	v_mov_b32_e32 v119, v80
	v_mov_b32_e32 v120, v80
	v_mov_b32_e32 v121, v80
	v_mov_b32_e32 v122, v80
	v_mov_b32_e32 v123, v80
	v_mov_b32_e32 v124, v80
	v_mov_b32_e32 v125, v80
	v_mov_b32_e32 v126, v80
	v_mov_b32_e32 v127, v80
	v_mov_b32_e32 v96, v80
	v_mov_b32_e32 v97, v80
	v_mov_b32_e32 v98, v80
	v_mov_b32_e32 v99, v80
	v_mov_b32_e32 v100, v80
	v_mov_b32_e32 v101, v80
	v_mov_b32_e32 v102, v80
	v_mov_b32_e32 v103, v80
	v_mov_b32_e32 v104, v80
	v_mov_b32_e32 v105, v80
	v_mov_b32_e32 v106, v80
	v_mov_b32_e32 v107, v80
	v_mov_b32_e32 v108, v80
	v_mov_b32_e32 v109, v80
	v_mov_b32_e32 v110, v80
	v_mov_b32_e32 v111, v80
	v_lshl_add_u64 v[246:247], s[62:63], 0, v[182:183]
	v_lshl_add_u64 v[246:247], v[246:247], 0, s[98:99]
	s_mov_b32 s100, s57
	s_mov_b32 s101, 0
	v_lshl_add_u64 v[242:243], s[62:63], 0, v[180:181]
	v_lshl_add_u64 v[242:243], v[242:243], 0, s[100:101]
	global_load_dwordx4 v[190:193], v[244:245], off offset:-4096
	global_load_dwordx4 v[212:215], v[246:247], off offset:-4096
	global_load_dwordx4 v[216:219], v[242:243], off offset:-4096
	global_load_dwordx4 v[220:223], v[242:243], off offset:-3072
	global_load_dwordx4 v[224:227], v[242:243], off offset:-2048
	global_load_dwordx4 v[228:231], v[242:243], off offset:-1024
	global_load_dwordx4 v[232:235], v[244:245], off offset:-2048
	global_load_dwordx4 v[236:239], v[246:247], off offset:-2048
	s_waitcnt vmcnt(5)
	v_mfma_f32_32x32x16_bf16 v[16:31], v[190:193], v[216:219], v[16:31]
	v_mfma_f32_32x32x16_bf16 v[80:95], v[212:215], v[216:219], v[80:95]
	global_load_dwordx4 v[216:219], v[242:243], off
	s_waitcnt vmcnt(5)
	v_mfma_f32_32x32x16_bf16 v[0:15], v[190:193], v[220:223], v[0:15]
	v_mfma_f32_32x32x16_bf16 v[64:79], v[212:215], v[220:223], v[64:79]
	global_load_dwordx4 v[220:223], v[242:243], off offset:1024
	s_waitcnt vmcnt(5)
	v_mfma_f32_32x32x16_bf16 v[48:63], v[190:193], v[224:227], v[48:63]
	v_mfma_f32_32x32x16_bf16 v[112:127], v[212:215], v[224:227], v[112:127]
	global_load_dwordx4 v[224:227], v[242:243], off offset:2048
	s_waitcnt vmcnt(5)
	v_mfma_f32_32x32x16_bf16 v[32:47], v[190:193], v[228:231], v[32:47]
	v_mfma_f32_32x32x16_bf16 v[96:111], v[212:215], v[228:231], v[96:111]
	global_load_dwordx4 v[228:231], v[242:243], off offset:3072
	global_load_dwordx4 v[190:193], v[244:245], off
	global_load_dwordx4 v[212:215], v[246:247], off
	s_waitcnt vmcnt(5)
	v_mfma_f32_32x32x16_bf16 v[16:31], v[232:235], v[216:219], v[16:31]
	v_mfma_f32_32x32x16_bf16 v[80:95], v[236:239], v[216:219], v[80:95]
	v_lshl_add_u64 v[242:243], v[242:243], 0, s[48:49]
	global_load_dwordx4 v[216:219], v[242:243], off offset:-4096
	s_waitcnt vmcnt(5)
	v_mfma_f32_32x32x16_bf16 v[0:15], v[232:235], v[220:223], v[0:15]
	v_mfma_f32_32x32x16_bf16 v[64:79], v[236:239], v[220:223], v[64:79]
	global_load_dwordx4 v[220:223], v[242:243], off offset:-3072
	s_waitcnt vmcnt(5)
	v_mfma_f32_32x32x16_bf16 v[48:63], v[232:235], v[224:227], v[48:63]
	v_mfma_f32_32x32x16_bf16 v[112:127], v[236:239], v[224:227], v[112:127]
	global_load_dwordx4 v[224:227], v[242:243], off offset:-2048
	s_waitcnt vmcnt(5)
	v_mfma_f32_32x32x16_bf16 v[32:47], v[232:235], v[228:231], v[32:47]
	v_mfma_f32_32x32x16_bf16 v[96:111], v[236:239], v[228:231], v[96:111]
	global_load_dwordx4 v[228:231], v[242:243], off offset:-1024
	global_load_dwordx4 v[232:235], v[244:245], off offset:2048
	global_load_dwordx4 v[236:239], v[246:247], off offset:2048
	s_waitcnt vmcnt(5)
	v_mfma_f32_32x32x16_bf16 v[16:31], v[190:193], v[216:219], v[16:31]
	v_mfma_f32_32x32x16_bf16 v[80:95], v[212:215], v[216:219], v[80:95]
	global_load_dwordx4 v[216:219], v[242:243], off
	s_waitcnt vmcnt(5)
	v_mfma_f32_32x32x16_bf16 v[0:15], v[190:193], v[220:223], v[0:15]
	v_mfma_f32_32x32x16_bf16 v[64:79], v[212:215], v[220:223], v[64:79]
	global_load_dwordx4 v[220:223], v[242:243], off offset:1024
	s_waitcnt vmcnt(5)
	v_mfma_f32_32x32x16_bf16 v[48:63], v[190:193], v[224:227], v[48:63]
	v_mfma_f32_32x32x16_bf16 v[112:127], v[212:215], v[224:227], v[112:127]
	global_load_dwordx4 v[224:227], v[242:243], off offset:2048
	s_waitcnt vmcnt(5)
	v_mfma_f32_32x32x16_bf16 v[32:47], v[190:193], v[228:231], v[32:47]
	v_mfma_f32_32x32x16_bf16 v[96:111], v[212:215], v[228:231], v[96:111]
	global_load_dwordx4 v[228:231], v[242:243], off offset:3072
	v_lshl_add_u64 v[244:245], v[244:245], 0, s[48:49]
	global_load_dwordx4 v[190:193], v[244:245], off offset:-4096
	v_lshl_add_u64 v[246:247], v[246:247], 0, s[48:49]
	global_load_dwordx4 v[212:215], v[246:247], off offset:-4096
	s_waitcnt vmcnt(5)
	v_mfma_f32_32x32x16_bf16 v[16:31], v[232:235], v[216:219], v[16:31]
	v_mfma_f32_32x32x16_bf16 v[80:95], v[236:239], v[216:219], v[80:95]
	v_lshl_add_u64 v[242:243], v[242:243], 0, s[48:49]
	global_load_dwordx4 v[216:219], v[242:243], off offset:-4096
	s_waitcnt vmcnt(5)
	v_mfma_f32_32x32x16_bf16 v[0:15], v[232:235], v[220:223], v[0:15]
	v_mfma_f32_32x32x16_bf16 v[64:79], v[236:239], v[220:223], v[64:79]
	global_load_dwordx4 v[220:223], v[242:243], off offset:-3072
	s_waitcnt vmcnt(5)
	v_mfma_f32_32x32x16_bf16 v[48:63], v[232:235], v[224:227], v[48:63]
	v_mfma_f32_32x32x16_bf16 v[112:127], v[236:239], v[224:227], v[112:127]
	global_load_dwordx4 v[224:227], v[242:243], off offset:-2048
	s_waitcnt vmcnt(5)
	v_mfma_f32_32x32x16_bf16 v[32:47], v[232:235], v[228:231], v[32:47]
	v_mfma_f32_32x32x16_bf16 v[96:111], v[236:239], v[228:231], v[96:111]
	global_load_dwordx4 v[228:231], v[242:243], off offset:-1024
	global_load_dwordx4 v[232:235], v[244:245], off offset:-2048
	global_load_dwordx4 v[236:239], v[246:247], off offset:-2048
	s_waitcnt vmcnt(5)
	v_mfma_f32_32x32x16_bf16 v[16:31], v[190:193], v[216:219], v[16:31]
	v_mfma_f32_32x32x16_bf16 v[80:95], v[212:215], v[216:219], v[80:95]
	global_load_dwordx4 v[216:219], v[242:243], off
	s_waitcnt vmcnt(5)
	v_mfma_f32_32x32x16_bf16 v[0:15], v[190:193], v[220:223], v[0:15]
	v_mfma_f32_32x32x16_bf16 v[64:79], v[212:215], v[220:223], v[64:79]
	global_load_dwordx4 v[220:223], v[242:243], off offset:1024
	s_waitcnt vmcnt(5)
	v_mfma_f32_32x32x16_bf16 v[48:63], v[190:193], v[224:227], v[48:63]
	v_mfma_f32_32x32x16_bf16 v[112:127], v[212:215], v[224:227], v[112:127]
	global_load_dwordx4 v[224:227], v[242:243], off offset:2048
	s_waitcnt vmcnt(5)
	v_mfma_f32_32x32x16_bf16 v[32:47], v[190:193], v[228:231], v[32:47]
	v_mfma_f32_32x32x16_bf16 v[96:111], v[212:215], v[228:231], v[96:111]
	global_load_dwordx4 v[228:231], v[242:243], off offset:3072
	global_load_dwordx4 v[190:193], v[244:245], off
	global_load_dwordx4 v[212:215], v[246:247], off
	s_waitcnt vmcnt(5)
	v_mfma_f32_32x32x16_bf16 v[16:31], v[232:235], v[216:219], v[16:31]
	v_mfma_f32_32x32x16_bf16 v[80:95], v[236:239], v[216:219], v[80:95]
	v_lshl_add_u64 v[242:243], v[242:243], 0, s[48:49]
	global_load_dwordx4 v[216:219], v[242:243], off offset:-4096
	s_waitcnt vmcnt(5)
	v_mfma_f32_32x32x16_bf16 v[0:15], v[232:235], v[220:223], v[0:15]
	v_mfma_f32_32x32x16_bf16 v[64:79], v[236:239], v[220:223], v[64:79]
	global_load_dwordx4 v[220:223], v[242:243], off offset:-3072
	s_waitcnt vmcnt(5)
	v_mfma_f32_32x32x16_bf16 v[48:63], v[232:235], v[224:227], v[48:63]
	v_mfma_f32_32x32x16_bf16 v[112:127], v[236:239], v[224:227], v[112:127]
	global_load_dwordx4 v[224:227], v[242:243], off offset:-2048
	s_waitcnt vmcnt(5)
	v_mfma_f32_32x32x16_bf16 v[32:47], v[232:235], v[228:231], v[32:47]
	v_mfma_f32_32x32x16_bf16 v[96:111], v[236:239], v[228:231], v[96:111]
	global_load_dwordx4 v[228:231], v[242:243], off offset:-1024
	global_load_dwordx4 v[232:235], v[244:245], off offset:2048
	global_load_dwordx4 v[236:239], v[246:247], off offset:2048
	s_waitcnt vmcnt(5)
	v_mfma_f32_32x32x16_bf16 v[16:31], v[190:193], v[216:219], v[16:31]
	v_mfma_f32_32x32x16_bf16 v[80:95], v[212:215], v[216:219], v[80:95]
	global_load_dwordx4 v[216:219], v[242:243], off
	s_waitcnt vmcnt(5)
	v_mfma_f32_32x32x16_bf16 v[0:15], v[190:193], v[220:223], v[0:15]
	v_mfma_f32_32x32x16_bf16 v[64:79], v[212:215], v[220:223], v[64:79]
	global_load_dwordx4 v[220:223], v[242:243], off offset:1024
	s_waitcnt vmcnt(5)
	v_mfma_f32_32x32x16_bf16 v[48:63], v[190:193], v[224:227], v[48:63]
	v_mfma_f32_32x32x16_bf16 v[112:127], v[212:215], v[224:227], v[112:127]
	global_load_dwordx4 v[224:227], v[242:243], off offset:2048
	s_waitcnt vmcnt(5)
	v_mfma_f32_32x32x16_bf16 v[32:47], v[190:193], v[228:231], v[32:47]
	v_mfma_f32_32x32x16_bf16 v[96:111], v[212:215], v[228:231], v[96:111]
	global_load_dwordx4 v[228:231], v[242:243], off offset:3072
	v_lshl_add_u64 v[244:245], v[244:245], 0, s[48:49]
	global_load_dwordx4 v[190:193], v[244:245], off offset:-4096
	v_lshl_add_u64 v[246:247], v[246:247], 0, s[48:49]
	global_load_dwordx4 v[212:215], v[246:247], off offset:-4096
	s_waitcnt vmcnt(5)
	v_mfma_f32_32x32x16_bf16 v[16:31], v[232:235], v[216:219], v[16:31]
	v_mfma_f32_32x32x16_bf16 v[80:95], v[236:239], v[216:219], v[80:95]
	v_lshl_add_u64 v[242:243], v[242:243], 0, s[48:49]
	global_load_dwordx4 v[216:219], v[242:243], off offset:-4096
	s_waitcnt vmcnt(5)
	v_mfma_f32_32x32x16_bf16 v[0:15], v[232:235], v[220:223], v[0:15]
	v_mfma_f32_32x32x16_bf16 v[64:79], v[236:239], v[220:223], v[64:79]
	global_load_dwordx4 v[220:223], v[242:243], off offset:-3072
	s_waitcnt vmcnt(5)
	v_mfma_f32_32x32x16_bf16 v[48:63], v[232:235], v[224:227], v[48:63]
	v_mfma_f32_32x32x16_bf16 v[112:127], v[236:239], v[224:227], v[112:127]
	global_load_dwordx4 v[224:227], v[242:243], off offset:-2048
	s_waitcnt vmcnt(5)
	v_mfma_f32_32x32x16_bf16 v[32:47], v[232:235], v[228:231], v[32:47]
	v_mfma_f32_32x32x16_bf16 v[96:111], v[236:239], v[228:231], v[96:111]
	global_load_dwordx4 v[228:231], v[242:243], off offset:-1024
	global_load_dwordx4 v[232:235], v[244:245], off offset:-2048
	global_load_dwordx4 v[236:239], v[246:247], off offset:-2048
	s_waitcnt vmcnt(5)
	v_mfma_f32_32x32x16_bf16 v[16:31], v[190:193], v[216:219], v[16:31]
	v_mfma_f32_32x32x16_bf16 v[80:95], v[212:215], v[216:219], v[80:95]
	global_load_dwordx4 v[216:219], v[242:243], off
	s_waitcnt vmcnt(5)
	v_mfma_f32_32x32x16_bf16 v[0:15], v[190:193], v[220:223], v[0:15]
	v_mfma_f32_32x32x16_bf16 v[64:79], v[212:215], v[220:223], v[64:79]
	global_load_dwordx4 v[220:223], v[242:243], off offset:1024
	s_waitcnt vmcnt(5)
	v_mfma_f32_32x32x16_bf16 v[48:63], v[190:193], v[224:227], v[48:63]
	v_mfma_f32_32x32x16_bf16 v[112:127], v[212:215], v[224:227], v[112:127]
	global_load_dwordx4 v[224:227], v[242:243], off offset:2048
	s_waitcnt vmcnt(5)
	v_mfma_f32_32x32x16_bf16 v[32:47], v[190:193], v[228:231], v[32:47]
	v_mfma_f32_32x32x16_bf16 v[96:111], v[212:215], v[228:231], v[96:111]
	global_load_dwordx4 v[228:231], v[242:243], off offset:3072
	global_load_dwordx4 v[190:193], v[244:245], off
	global_load_dwordx4 v[212:215], v[246:247], off
	s_waitcnt vmcnt(5)
	v_mfma_f32_32x32x16_bf16 v[16:31], v[232:235], v[216:219], v[16:31]
	v_mfma_f32_32x32x16_bf16 v[80:95], v[236:239], v[216:219], v[80:95]
	v_lshl_add_u64 v[242:243], v[242:243], 0, s[48:49]
	global_load_dwordx4 v[216:219], v[242:243], off offset:-4096
	s_waitcnt vmcnt(5)
	v_mfma_f32_32x32x16_bf16 v[0:15], v[232:235], v[220:223], v[0:15]
	v_mfma_f32_32x32x16_bf16 v[64:79], v[236:239], v[220:223], v[64:79]
	global_load_dwordx4 v[220:223], v[242:243], off offset:-3072
	s_waitcnt vmcnt(5)
	v_mfma_f32_32x32x16_bf16 v[48:63], v[232:235], v[224:227], v[48:63]
	v_mfma_f32_32x32x16_bf16 v[112:127], v[236:239], v[224:227], v[112:127]
	global_load_dwordx4 v[224:227], v[242:243], off offset:-2048
	s_waitcnt vmcnt(5)
	v_mfma_f32_32x32x16_bf16 v[32:47], v[232:235], v[228:231], v[32:47]
	v_mfma_f32_32x32x16_bf16 v[96:111], v[236:239], v[228:231], v[96:111]
	global_load_dwordx4 v[228:231], v[242:243], off offset:-1024
	global_load_dwordx4 v[232:235], v[244:245], off offset:2048
	global_load_dwordx4 v[236:239], v[246:247], off offset:2048
	s_waitcnt vmcnt(5)
	v_mfma_f32_32x32x16_bf16 v[16:31], v[190:193], v[216:219], v[16:31]
	v_mfma_f32_32x32x16_bf16 v[80:95], v[212:215], v[216:219], v[80:95]
	global_load_dwordx4 v[216:219], v[242:243], off
	s_waitcnt vmcnt(5)
	v_mfma_f32_32x32x16_bf16 v[0:15], v[190:193], v[220:223], v[0:15]
	v_mfma_f32_32x32x16_bf16 v[64:79], v[212:215], v[220:223], v[64:79]
	global_load_dwordx4 v[220:223], v[242:243], off offset:1024
	s_waitcnt vmcnt(5)
	v_mfma_f32_32x32x16_bf16 v[48:63], v[190:193], v[224:227], v[48:63]
	v_mfma_f32_32x32x16_bf16 v[112:127], v[212:215], v[224:227], v[112:127]
	global_load_dwordx4 v[224:227], v[242:243], off offset:2048
	s_waitcnt vmcnt(5)
	v_mfma_f32_32x32x16_bf16 v[32:47], v[190:193], v[228:231], v[32:47]
	v_mfma_f32_32x32x16_bf16 v[96:111], v[212:215], v[228:231], v[96:111]
	global_load_dwordx4 v[228:231], v[242:243], off offset:3072
	v_lshl_add_u64 v[244:245], v[244:245], 0, s[48:49]
	global_load_dwordx4 v[190:193], v[244:245], off offset:-4096
	v_lshl_add_u64 v[246:247], v[246:247], 0, s[48:49]
	global_load_dwordx4 v[212:215], v[246:247], off offset:-4096
	s_waitcnt vmcnt(5)
	v_mfma_f32_32x32x16_bf16 v[16:31], v[232:235], v[216:219], v[16:31]
	v_mfma_f32_32x32x16_bf16 v[80:95], v[236:239], v[216:219], v[80:95]
	v_lshl_add_u64 v[242:243], v[242:243], 0, s[48:49]
	global_load_dwordx4 v[216:219], v[242:243], off offset:-4096
	s_waitcnt vmcnt(5)
	v_mfma_f32_32x32x16_bf16 v[0:15], v[232:235], v[220:223], v[0:15]
	v_mfma_f32_32x32x16_bf16 v[64:79], v[236:239], v[220:223], v[64:79]
	global_load_dwordx4 v[220:223], v[242:243], off offset:-3072
	s_waitcnt vmcnt(5)
	v_mfma_f32_32x32x16_bf16 v[48:63], v[232:235], v[224:227], v[48:63]
	v_mfma_f32_32x32x16_bf16 v[112:127], v[236:239], v[224:227], v[112:127]
	global_load_dwordx4 v[224:227], v[242:243], off offset:-2048
	s_waitcnt vmcnt(5)
	v_mfma_f32_32x32x16_bf16 v[32:47], v[232:235], v[228:231], v[32:47]
	v_mfma_f32_32x32x16_bf16 v[96:111], v[236:239], v[228:231], v[96:111]
	global_load_dwordx4 v[228:231], v[242:243], off offset:-1024
	global_load_dwordx4 v[232:235], v[244:245], off offset:-2048
	global_load_dwordx4 v[236:239], v[246:247], off offset:-2048
	s_waitcnt vmcnt(5)
	v_mfma_f32_32x32x16_bf16 v[16:31], v[190:193], v[216:219], v[16:31]
	v_mfma_f32_32x32x16_bf16 v[80:95], v[212:215], v[216:219], v[80:95]
	global_load_dwordx4 v[216:219], v[242:243], off
	s_waitcnt vmcnt(5)
	v_mfma_f32_32x32x16_bf16 v[0:15], v[190:193], v[220:223], v[0:15]
	v_mfma_f32_32x32x16_bf16 v[64:79], v[212:215], v[220:223], v[64:79]
	global_load_dwordx4 v[220:223], v[242:243], off offset:1024
	s_waitcnt vmcnt(5)
	v_mfma_f32_32x32x16_bf16 v[48:63], v[190:193], v[224:227], v[48:63]
	v_mfma_f32_32x32x16_bf16 v[112:127], v[212:215], v[224:227], v[112:127]
	global_load_dwordx4 v[224:227], v[242:243], off offset:2048
	s_waitcnt vmcnt(5)
	v_mfma_f32_32x32x16_bf16 v[32:47], v[190:193], v[228:231], v[32:47]
	v_mfma_f32_32x32x16_bf16 v[96:111], v[212:215], v[228:231], v[96:111]
	global_load_dwordx4 v[228:231], v[242:243], off offset:3072
	global_load_dwordx4 v[190:193], v[244:245], off
	global_load_dwordx4 v[212:215], v[246:247], off
	s_waitcnt vmcnt(5)
	v_mfma_f32_32x32x16_bf16 v[16:31], v[232:235], v[216:219], v[16:31]
	v_mfma_f32_32x32x16_bf16 v[80:95], v[236:239], v[216:219], v[80:95]
	v_lshl_add_u64 v[242:243], v[242:243], 0, s[48:49]
	global_load_dwordx4 v[216:219], v[242:243], off offset:-4096
	s_waitcnt vmcnt(5)
	v_mfma_f32_32x32x16_bf16 v[0:15], v[232:235], v[220:223], v[0:15]
	v_mfma_f32_32x32x16_bf16 v[64:79], v[236:239], v[220:223], v[64:79]
	global_load_dwordx4 v[220:223], v[242:243], off offset:-3072
	s_waitcnt vmcnt(5)
	v_mfma_f32_32x32x16_bf16 v[48:63], v[232:235], v[224:227], v[48:63]
	v_mfma_f32_32x32x16_bf16 v[112:127], v[236:239], v[224:227], v[112:127]
	global_load_dwordx4 v[224:227], v[242:243], off offset:-2048
	s_waitcnt vmcnt(5)
	v_mfma_f32_32x32x16_bf16 v[32:47], v[232:235], v[228:231], v[32:47]
	v_mfma_f32_32x32x16_bf16 v[96:111], v[236:239], v[228:231], v[96:111]
	global_load_dwordx4 v[228:231], v[242:243], off offset:-1024
	global_load_dwordx4 v[232:235], v[244:245], off offset:2048
	global_load_dwordx4 v[236:239], v[246:247], off offset:2048
	s_waitcnt vmcnt(5)
	v_mfma_f32_32x32x16_bf16 v[16:31], v[190:193], v[216:219], v[16:31]
	v_mfma_f32_32x32x16_bf16 v[80:95], v[212:215], v[216:219], v[80:95]
	global_load_dwordx4 v[216:219], v[242:243], off
	s_waitcnt vmcnt(5)
	v_mfma_f32_32x32x16_bf16 v[0:15], v[190:193], v[220:223], v[0:15]
	v_mfma_f32_32x32x16_bf16 v[64:79], v[212:215], v[220:223], v[64:79]
	global_load_dwordx4 v[220:223], v[242:243], off offset:1024
	s_waitcnt vmcnt(5)
	v_mfma_f32_32x32x16_bf16 v[48:63], v[190:193], v[224:227], v[48:63]
	v_mfma_f32_32x32x16_bf16 v[112:127], v[212:215], v[224:227], v[112:127]
	global_load_dwordx4 v[224:227], v[242:243], off offset:2048
	s_waitcnt vmcnt(5)
	v_mfma_f32_32x32x16_bf16 v[32:47], v[190:193], v[228:231], v[32:47]
	v_mfma_f32_32x32x16_bf16 v[96:111], v[212:215], v[228:231], v[96:111]
	global_load_dwordx4 v[228:231], v[242:243], off offset:3072
	s_waitcnt vmcnt(3)
	v_mfma_f32_32x32x16_bf16 v[16:31], v[232:235], v[216:219], v[16:31]
	v_mfma_f32_32x32x16_bf16 v[80:95], v[236:239], v[216:219], v[80:95]
	s_waitcnt vmcnt(2)
	v_mfma_f32_32x32x16_bf16 v[0:15], v[232:235], v[220:223], v[0:15]
	v_mfma_f32_32x32x16_bf16 v[64:79], v[236:239], v[220:223], v[64:79]
	s_waitcnt vmcnt(1)
	v_mfma_f32_32x32x16_bf16 v[48:63], v[232:235], v[224:227], v[48:63]
	v_mfma_f32_32x32x16_bf16 v[112:127], v[236:239], v[224:227], v[112:127]
	s_waitcnt vmcnt(0)
	v_mfma_f32_32x32x16_bf16 v[32:47], v[232:235], v[228:231], v[32:47]
	v_mfma_f32_32x32x16_bf16 v[96:111], v[236:239], v[228:231], v[96:111]
	v_mov_b32_e32 v182, v173
	v_mov_b32_e32 v183, v175
	v_mov_b32_e32 v180, v172
	v_mov_b32_e32 v181, v174
	v_pk_mul_f32 v[212:213], v[182:183], v[182:183]
	v_pk_add_f32 v[190:191], v[180:181], v[180:181]
	v_pk_fma_f32 v[212:213], v[180:181], v[180:181], v[212:213] neg_lo:[0,0,1] neg_hi:[0,0,1]
	v_pk_mul_f32 v[190:191], v[182:183], v[190:191]
	v_pk_add_f32 v[214:215], v[212:213], v[212:213]
	v_pk_mul_f32 v[192:193], v[190:191], v[190:191]
	v_pk_mul_f32 v[190:191], v[190:191], v[214:215]
	v_pk_fma_f32 v[192:193], v[212:213], v[212:213], v[192:193] neg_lo:[0,0,1] neg_hi:[0,0,1]
	v_pk_mul_f32 v[212:213], v[190:191], v[190:191]
	s_andn2_b64 vcc, exec, s[26:27]
	v_pk_fma_f32 v[212:213], v[192:193], v[192:193], v[212:213] neg_lo:[0,0,1] neg_hi:[0,0,1]
	v_pk_add_f32 v[192:193], v[192:193], v[192:193]
	s_nop 0
	v_pk_mul_f32 v[192:193], v[190:191], v[192:193]
	s_nop 0
	v_pk_mul_f32 v[190:191], v[192:193], v[192:193]
	s_nop 0
	v_pk_fma_f32 v[190:191], v[212:213], v[212:213], v[190:191] neg_lo:[0,0,1] neg_hi:[0,0,1]
	v_pk_add_f32 v[212:213], v[212:213], v[212:213]
	s_nop 0
	v_pk_mul_f32 v[192:193], v[192:193], v[212:213]
	s_nop 0
	v_pk_mul_f32 v[212:213], v[192:193], v[186:187] op_sel_hi:[0,1]
	v_pk_fma_f32 v[214:215], v[190:191], v[186:187], v[212:213] op_sel:[0,0,1] op_sel_hi:[1,1,0] neg_lo:[0,0,1] neg_hi:[0,0,1]
	v_pk_fma_f32 v[186:187], v[190:191], v[186:187], v[212:213] op_sel:[0,0,1] op_sel_hi:[0,1,0]
	v_mov_b32_e32 v215, v187
	v_pk_mul_f32 v[186:187], v[192:193], v[188:189] op_sel:[1,0]
	s_nop 0
	v_pk_fma_f32 v[212:213], v[190:191], v[188:189], v[186:187] op_sel:[1,0,1] op_sel_hi:[1,1,0] neg_lo:[0,0,1] neg_hi:[0,0,1]
	v_pk_fma_f32 v[186:187], v[190:191], v[188:189], v[186:187] op_sel:[1,0,1] op_sel_hi:[1,1,0]
	s_nop 0
	v_mov_b32_e32 v213, v187
	v_mov_b32_e32 v186, v0
	v_mov_b32_e32 v187, v32
	v_pk_add_f32 v[186:187], v[212:213], v[186:187]
	v_mov_b32_e32 v32, v1
	v_pk_mul_f32 v[188:189], v[192:193], v[186:187] op_sel:[1,0]
	s_nop 0
	v_pk_fma_f32 v[212:213], v[190:191], v[186:187], v[188:189] op_sel:[1,0,1] op_sel_hi:[1,1,0] neg_lo:[0,0,1] neg_hi:[0,0,1]
	v_pk_fma_f32 v[186:187], v[190:191], v[186:187], v[188:189] op_sel:[1,0,1] op_sel_hi:[1,1,0]
	s_nop 0
	v_mov_b32_e32 v213, v187
	v_pk_add_f32 v[0:1], v[32:33], v[212:213]
	s_nop 0
	v_pk_mul_f32 v[32:33], v[192:193], v[0:1] op_sel:[1,0]
	s_nop 0
	v_pk_fma_f32 v[186:187], v[190:191], v[0:1], v[32:33] op_sel:[1,0,1] op_sel_hi:[1,1,0] neg_lo:[0,0,1] neg_hi:[0,0,1]
	v_pk_fma_f32 v[0:1], v[190:191], v[0:1], v[32:33] op_sel:[1,0,1] op_sel_hi:[1,1,0]
	s_nop 0
	v_mov_b32_e32 v187, v1
	v_mov_b32_e32 v0, v2
	v_mov_b32_e32 v1, v34
	v_pk_add_f32 v[32:33], v[0:1], v[186:187]
	v_mov_b32_e32 v0, v16
	v_mov_b32_e32 v1, v48
	v_pk_add_f32 v[0:1], v[214:215], v[0:1]
	v_mov_b32_e32 v48, v17
	v_pk_mul_f32 v[186:187], v[192:193], v[0:1] op_sel_hi:[0,1]
	v_pk_fma_f32 v[188:189], v[190:191], v[0:1], v[186:187] op_sel:[0,0,1] op_sel_hi:[1,1,0] neg_lo:[0,0,1] neg_hi:[0,0,1]
	v_pk_fma_f32 v[0:1], v[190:191], v[0:1], v[186:187] op_sel:[0,0,1] op_sel_hi:[0,1,0]
	v_mov_b32_e32 v189, v1
	v_pk_add_f32 v[0:1], v[48:49], v[188:189]
	v_mov_b32_e32 v34, v3
	v_pk_mul_f32 v[16:17], v[192:193], v[0:1] op_sel_hi:[0,1]
	v_pk_fma_f32 v[48:49], v[190:191], v[0:1], v[16:17] op_sel:[0,0,1] op_sel_hi:[1,1,0] neg_lo:[0,0,1] neg_hi:[0,0,1]
	v_pk_fma_f32 v[0:1], v[190:191], v[0:1], v[16:17] op_sel:[0,0,1] op_sel_hi:[0,1,0]
	v_mov_b32_e32 v49, v1
	v_mov_b32_e32 v0, v18
	v_mov_b32_e32 v1, v50
	v_pk_add_f32 v[0:1], v[0:1], v[48:49]
	v_mov_b32_e32 v50, v19
	v_pk_mul_f32 v[16:17], v[192:193], v[0:1] op_sel_hi:[0,1]
	v_pk_fma_f32 v[48:49], v[190:191], v[0:1], v[16:17] op_sel:[0,0,1] op_sel_hi:[1,1,0] neg_lo:[0,0,1] neg_hi:[0,0,1]
	v_pk_fma_f32 v[0:1], v[190:191], v[0:1], v[16:17] op_sel:[0,0,1] op_sel_hi:[0,1,0]
	v_mov_b32_e32 v49, v1
	v_pk_add_f32 v[18:19], v[50:51], v[48:49]
	v_pk_mul_f32 v[50:51], v[192:193], v[32:33] op_sel:[1,0]
	v_mov_b32_e32 v0, v190
	v_mov_b32_e32 v1, v192
	v_mul_f32_e32 v2, v192, v19
	v_pk_fma_f32 v[186:187], v[190:191], v[32:33], v[50:51] op_sel:[1,0,1] op_sel_hi:[1,1,0] neg_lo:[0,0,1] neg_hi:[0,0,1]
	v_pk_fma_f32 v[32:33], v[190:191], v[32:33], v[50:51] op_sel:[1,0,1] op_sel_hi:[1,1,0]
	v_pk_fma_f32 v[48:49], v[0:1], v[18:19], v[2:3] op_sel_hi:[1,1,0] neg_lo:[0,0,1] neg_hi:[0,0,1]
	v_mov_b32_e32 v16, v192
	v_mov_b32_e32 v17, v190
	v_mul_f32_e32 v2, v192, v18
	v_mov_b32_e32 v187, v33
	v_pk_fma_f32 v[18:19], v[16:17], v[18:19], v[2:3] op_sel_hi:[1,1,0]
	v_pk_add_f32 v[2:3], v[34:35], v[186:187]
	v_mov_b32_e32 v49, v19
	v_pk_mul_f32 v[32:33], v[192:193], v[2:3] op_sel:[1,0]
	s_nop 0
	v_pk_fma_f32 v[34:35], v[190:191], v[2:3], v[32:33] op_sel:[1,0,1] op_sel_hi:[1,1,0] neg_lo:[0,0,1] neg_hi:[0,0,1]
	v_pk_fma_f32 v[2:3], v[190:191], v[2:3], v[32:33] op_sel:[1,0,1] op_sel_hi:[1,1,0]
	s_nop 0
	v_mov_b32_e32 v35, v3
	v_mov_b32_e32 v2, v4
	v_mov_b32_e32 v3, v36
	v_pk_add_f32 v[2:3], v[2:3], v[34:35]
	v_mov_b32_e32 v36, v5
	v_pk_mul_f32 v[32:33], v[192:193], v[2:3] op_sel:[1,0]
	s_nop 0
	v_pk_fma_f32 v[34:35], v[190:191], v[2:3], v[32:33] op_sel:[1,0,1] op_sel_hi:[1,1,0] neg_lo:[0,0,1] neg_hi:[0,0,1]
	v_pk_fma_f32 v[2:3], v[190:191], v[2:3], v[32:33] op_sel:[1,0,1] op_sel_hi:[1,1,0]
	s_nop 0
	v_mov_b32_e32 v35, v3
	v_pk_add_f32 v[2:3], v[36:37], v[34:35]
	s_nop 0
	v_pk_mul_f32 v[4:5], v[192:193], v[2:3] op_sel:[1,0]
	s_nop 0
	v_pk_fma_f32 v[32:33], v[190:191], v[2:3], v[4:5] op_sel:[1,0,1] op_sel_hi:[1,1,0] neg_lo:[0,0,1] neg_hi:[0,0,1]
	v_pk_fma_f32 v[2:3], v[190:191], v[2:3], v[4:5] op_sel:[1,0,1] op_sel_hi:[1,1,0]
	s_nop 0
	v_mov_b32_e32 v33, v3
	v_mov_b32_e32 v2, v20
	v_mov_b32_e32 v3, v52
	v_pk_add_f32 v[2:3], v[2:3], v[48:49]
	v_mov_b32_e32 v52, v21
	v_pk_mul_f32 v[4:5], v[192:193], v[2:3] op_sel_hi:[0,1]
	v_pk_fma_f32 v[18:19], v[190:191], v[2:3], v[4:5] op_sel:[0,0,1] op_sel_hi:[1,1,0] neg_lo:[0,0,1] neg_hi:[0,0,1]
	v_pk_fma_f32 v[2:3], v[190:191], v[2:3], v[4:5] op_sel:[0,0,1] op_sel_hi:[0,1,0]
	v_mov_b32_e32 v19, v3
	v_pk_add_f32 v[2:3], v[52:53], v[18:19]
	s_nop 0
	v_pk_mul_f32 v[4:5], v[192:193], v[2:3] op_sel_hi:[0,1]
	v_pk_fma_f32 v[18:19], v[190:191], v[2:3], v[4:5] op_sel:[0,0,1] op_sel_hi:[1,1,0] neg_lo:[0,0,1] neg_hi:[0,0,1]
	v_pk_fma_f32 v[2:3], v[190:191], v[2:3], v[4:5] op_sel:[0,0,1] op_sel_hi:[0,1,0]
	v_mov_b32_e32 v19, v3
	v_mov_b32_e32 v2, v22
	v_mov_b32_e32 v3, v54
	v_pk_add_f32 v[2:3], v[2:3], v[18:19]
	v_mov_b32_e32 v54, v23
	v_pk_mul_f32 v[4:5], v[192:193], v[2:3] op_sel_hi:[0,1]
	v_pk_fma_f32 v[18:19], v[190:191], v[2:3], v[4:5] op_sel:[0,0,1] op_sel_hi:[1,1,0] neg_lo:[0,0,1] neg_hi:[0,0,1]
	v_pk_fma_f32 v[2:3], v[190:191], v[2:3], v[4:5] op_sel:[0,0,1] op_sel_hi:[0,1,0]
	v_mov_b32_e32 v4, v6
	v_mov_b32_e32 v5, v38
	v_mov_b32_e32 v19, v3
	v_pk_add_f32 v[4:5], v[4:5], v[32:33]
	v_pk_add_f32 v[2:3], v[54:55], v[18:19]
	v_pk_mul_f32 v[18:19], v[192:193], v[4:5] op_sel:[1,0]
	v_mov_b32_e32 v38, v7
	v_pk_fma_f32 v[20:21], v[190:191], v[4:5], v[18:19] op_sel:[1,0,1] op_sel_hi:[1,1,0] neg_lo:[0,0,1] neg_hi:[0,0,1]
	v_pk_fma_f32 v[4:5], v[190:191], v[4:5], v[18:19] op_sel:[1,0,1] op_sel_hi:[1,1,0]
	s_nop 0
	v_mov_b32_e32 v21, v5
	v_pk_add_f32 v[4:5], v[38:39], v[20:21]
	s_nop 0
	v_pk_mul_f32 v[6:7], v[192:193], v[4:5] op_sel:[1,0]
	s_nop 0
	v_pk_fma_f32 v[18:19], v[190:191], v[4:5], v[6:7] op_sel:[1,0,1] op_sel_hi:[1,1,0] neg_lo:[0,0,1] neg_hi:[0,0,1]
	v_pk_fma_f32 v[4:5], v[190:191], v[4:5], v[6:7] op_sel:[1,0,1] op_sel_hi:[1,1,0]
	s_nop 0
	v_mov_b32_e32 v19, v5
	v_mov_b32_e32 v4, v8
	v_mov_b32_e32 v5, v40
	v_pk_add_f32 v[4:5], v[4:5], v[18:19]
	v_mov_b32_e32 v40, v9
	v_pk_mul_f32 v[6:7], v[192:193], v[4:5] op_sel:[1,0]
	s_nop 0
	v_pk_fma_f32 v[18:19], v[190:191], v[4:5], v[6:7] op_sel:[1,0,1] op_sel_hi:[1,1,0] neg_lo:[0,0,1] neg_hi:[0,0,1]
	v_pk_fma_f32 v[4:5], v[190:191], v[4:5], v[6:7] op_sel:[1,0,1] op_sel_hi:[1,1,0]
	v_mov_b32_e32 v6, v191
	v_mov_b32_e32 v19, v5
	v_pk_add_f32 v[4:5], v[40:41], v[18:19]
	v_mov_b32_e32 v7, v193
	v_mul_f32_e32 v8, v193, v5
	v_mov_b32_e32 v18, v193
	v_mov_b32_e32 v19, v191
	v_mul_f32_e32 v20, v193, v4
	v_pk_fma_f32 v[8:9], v[6:7], v[4:5], v[8:9] op_sel_hi:[1,1,0] neg_lo:[0,0,1] neg_hi:[0,0,1]
	v_pk_fma_f32 v[4:5], v[18:19], v[4:5], v[20:21] op_sel_hi:[1,1,0]
	v_pk_mul_f32 v[20:21], v[192:193], v[2:3] op_sel_hi:[0,1]
	v_pk_fma_f32 v[22:23], v[190:191], v[2:3], v[20:21] op_sel:[0,0,1] op_sel_hi:[1,1,0] neg_lo:[0,0,1] neg_hi:[0,0,1]
	v_pk_fma_f32 v[2:3], v[190:191], v[2:3], v[20:21] op_sel:[0,0,1] op_sel_hi:[0,1,0]
	v_mov_b32_e32 v23, v3
	v_mov_b32_e32 v2, v24
	v_mov_b32_e32 v3, v56
	v_pk_add_f32 v[2:3], v[2:3], v[22:23]
	v_mov_b32_e32 v56, v25
	v_pk_mul_f32 v[20:21], v[192:193], v[2:3] op_sel_hi:[0,1]
	v_pk_fma_f32 v[22:23], v[190:191], v[2:3], v[20:21] op_sel:[0,0,1] op_sel_hi:[1,1,0] neg_lo:[0,0,1] neg_hi:[0,0,1]
	v_pk_fma_f32 v[2:3], v[190:191], v[2:3], v[20:21] op_sel:[0,0,1] op_sel_hi:[0,1,0]
	v_mov_b32_e32 v23, v3
	v_pk_add_f32 v[2:3], v[56:57], v[22:23]
	v_mov_b32_e32 v9, v5
	v_pk_mul_f32 v[20:21], v[192:193], v[2:3] op_sel_hi:[0,1]
	v_pk_fma_f32 v[22:23], v[190:191], v[2:3], v[20:21] op_sel:[0,0,1] op_sel_hi:[1,1,0] neg_lo:[0,0,1] neg_hi:[0,0,1]
	v_pk_fma_f32 v[2:3], v[190:191], v[2:3], v[20:21] op_sel:[0,0,1] op_sel_hi:[0,1,0]
	v_mov_b32_e32 v23, v3
	v_mov_b32_e32 v2, v26
	v_mov_b32_e32 v3, v58
	v_pk_add_f32 v[2:3], v[2:3], v[22:23]
	v_mov_b32_e32 v58, v27
	v_pk_mul_f32 v[20:21], v[192:193], v[2:3] op_sel_hi:[0,1]
	v_pk_fma_f32 v[22:23], v[190:191], v[2:3], v[20:21] op_sel:[0,0,1] op_sel_hi:[1,1,0] neg_lo:[0,0,1] neg_hi:[0,0,1]
	v_pk_fma_f32 v[2:3], v[190:191], v[2:3], v[20:21] op_sel:[0,0,1] op_sel_hi:[0,1,0]
	v_mov_b32_e32 v23, v3
	v_mov_b32_e32 v2, v10
	v_mov_b32_e32 v3, v42
	v_pk_add_f32 v[2:3], v[2:3], v[8:9]
	v_mov_b32_e32 v42, v11
	v_pk_mul_f32 v[4:5], v[192:193], v[2:3] op_sel:[1,0]
	s_nop 0
	v_pk_fma_f32 v[8:9], v[190:191], v[2:3], v[4:5] op_sel:[1,0,1] op_sel_hi:[1,1,0] neg_lo:[0,0,1] neg_hi:[0,0,1]
	v_pk_fma_f32 v[2:3], v[190:191], v[2:3], v[4:5] op_sel:[1,0,1] op_sel_hi:[1,1,0]
	s_nop 0
	v_mov_b32_e32 v9, v3
	v_pk_add_f32 v[2:3], v[42:43], v[8:9]
	s_nop 0
	v_pk_mul_f32 v[4:5], v[192:193], v[2:3] op_sel:[1,0]
	s_nop 0
	v_pk_fma_f32 v[8:9], v[190:191], v[2:3], v[4:5] op_sel:[1,0,1] op_sel_hi:[1,1,0] neg_lo:[0,0,1] neg_hi:[0,0,1]
	v_pk_fma_f32 v[2:3], v[190:191], v[2:3], v[4:5] op_sel:[1,0,1] op_sel_hi:[1,1,0]
	s_nop 0
	v_mov_b32_e32 v9, v3
	v_mov_b32_e32 v2, v12
	v_mov_b32_e32 v3, v44
	v_pk_add_f32 v[2:3], v[2:3], v[8:9]
	v_mov_b32_e32 v44, v13
	v_pk_mul_f32 v[4:5], v[192:193], v[2:3] op_sel:[1,0]
	s_nop 0
	v_pk_fma_f32 v[8:9], v[190:191], v[2:3], v[4:5] op_sel:[1,0,1] op_sel_hi:[1,1,0] neg_lo:[0,0,1] neg_hi:[0,0,1]
	v_pk_fma_f32 v[2:3], v[190:191], v[2:3], v[4:5] op_sel:[1,0,1] op_sel_hi:[1,1,0]
	v_pk_add_f32 v[4:5], v[58:59], v[22:23]
	v_mov_b32_e32 v9, v3
	v_pk_add_f32 v[2:3], v[44:45], v[8:9]
	v_pk_mul_f32 v[8:9], v[192:193], v[4:5] op_sel_hi:[0,1]
	v_pk_fma_f32 v[10:11], v[190:191], v[4:5], v[8:9] op_sel:[0,0,1] op_sel_hi:[1,1,0] neg_lo:[0,0,1] neg_hi:[0,0,1]
	v_pk_fma_f32 v[4:5], v[190:191], v[4:5], v[8:9] op_sel:[0,0,1] op_sel_hi:[0,1,0]
	v_mov_b32_e32 v11, v5
	v_mov_b32_e32 v4, v28
	v_mov_b32_e32 v5, v60
	v_pk_add_f32 v[4:5], v[4:5], v[10:11]
	v_mov_b32_e32 v60, v29
	v_pk_mul_f32 v[8:9], v[192:193], v[4:5] op_sel_hi:[0,1]
	v_pk_fma_f32 v[10:11], v[190:191], v[4:5], v[8:9] op_sel:[0,0,1] op_sel_hi:[1,1,0] neg_lo:[0,0,1] neg_hi:[0,0,1]
	v_pk_fma_f32 v[4:5], v[190:191], v[4:5], v[8:9] op_sel:[0,0,1] op_sel_hi:[0,1,0]
	v_mov_b32_e32 v11, v5
	v_pk_add_f32 v[4:5], v[60:61], v[10:11]
	s_nop 0
	v_pk_mul_f32 v[8:9], v[192:193], v[4:5] op_sel_hi:[0,1]
	v_pk_fma_f32 v[10:11], v[190:191], v[4:5], v[8:9] op_sel:[0,0,1] op_sel_hi:[1,1,0] neg_lo:[0,0,1] neg_hi:[0,0,1]
	v_pk_fma_f32 v[4:5], v[190:191], v[4:5], v[8:9] op_sel:[0,0,1] op_sel_hi:[0,1,0]
	v_mov_b32_e32 v11, v5
	v_mov_b32_e32 v4, v30
	v_mov_b32_e32 v5, v62
	v_pk_add_f32 v[4:5], v[4:5], v[10:11]
	v_pk_mul_f32 v[8:9], v[192:193], v[2:3] op_sel:[1,0]
	s_nop 0
	v_pk_fma_f32 v[10:11], v[190:191], v[2:3], v[8:9] op_sel:[1,0,1] op_sel_hi:[1,1,0] neg_lo:[0,0,1] neg_hi:[0,0,1]
	v_pk_fma_f32 v[2:3], v[190:191], v[2:3], v[8:9] op_sel:[1,0,1] op_sel_hi:[1,1,0]
	v_mul_f32_e32 v8, v190, v4
	v_fma_f32 v8, -v192, v5, v8
	v_pk_mul_f32 v[4:5], v[16:17], v[4:5]
	v_add_f32_e32 v8, v31, v8
	v_add_f32_e32 v4, v4, v5
	v_add_f32_e32 v4, v63, v4
	v_pk_mul_f32 v[4:5], v[16:17], v[4:5] op_sel_hi:[1,0]
	v_mov_b32_e32 v11, v3
	v_pk_fma_f32 v[12:13], v[190:191], v[8:9], v[4:5] neg_lo:[0,0,1] neg_hi:[0,0,1]
	v_pk_fma_f32 v[4:5], v[0:1], v[8:9], v[4:5] op_sel_hi:[1,0,1]
	v_mov_b32_e32 v2, v14
	v_mov_b32_e32 v13, v5
	v_mov_b32_e32 v4, v80
	v_mov_b32_e32 v5, v112
	v_mov_b32_e32 v3, v46
	v_pk_add_f32 v[4:5], v[12:13], v[4:5]
	v_pk_add_f32 v[2:3], v[2:3], v[10:11]
	v_pk_mul_f32 v[8:9], v[192:193], v[4:5] op_sel_hi:[0,1]
	v_pk_mul_f32 v[10:11], v[192:193], v[2:3] op_sel:[1,0]
	v_pk_fma_f32 v[12:13], v[190:191], v[4:5], v[8:9] op_sel:[0,0,1] op_sel_hi:[1,1,0] neg_lo:[0,0,1] neg_hi:[0,0,1]
	v_pk_fma_f32 v[4:5], v[190:191], v[4:5], v[8:9] op_sel:[0,0,1] op_sel_hi:[0,1,0]
	v_mov_b32_e32 v13, v5
	v_pk_fma_f32 v[4:5], v[190:191], v[2:3], v[10:11] op_sel:[1,0,1] op_sel_hi:[1,1,0] neg_lo:[0,0,1] neg_hi:[0,0,1]
	v_pk_fma_f32 v[2:3], v[190:191], v[2:3], v[10:11] op_sel:[1,0,1] op_sel_hi:[1,1,0]
	v_mov_b32_e32 v46, v15
	v_mov_b32_e32 v5, v3
	v_pk_add_f32 v[2:3], v[46:47], v[4:5]
	v_mov_b32_e32 v112, v81
	v_pk_mul_f32 v[4:5], v[192:193], v[2:3] op_sel:[1,0]
	s_nop 0
	v_pk_fma_f32 v[8:9], v[190:191], v[2:3], v[4:5] op_sel:[1,0,1] op_sel_hi:[1,1,0] neg_lo:[0,0,1] neg_hi:[0,0,1]
	v_pk_fma_f32 v[2:3], v[190:191], v[2:3], v[4:5] op_sel:[1,0,1] op_sel_hi:[1,1,0]
	s_nop 0
	v_mov_b32_e32 v9, v3
	v_mov_b32_e32 v2, v64
	v_mov_b32_e32 v3, v96
	v_pk_add_f32 v[2:3], v[8:9], v[2:3]
	v_mov_b32_e32 v96, v65
	v_pk_mul_f32 v[4:5], v[192:193], v[2:3] op_sel:[1,0]
	s_nop 0
	v_pk_fma_f32 v[8:9], v[190:191], v[2:3], v[4:5] op_sel:[1,0,1] op_sel_hi:[1,1,0] neg_lo:[0,0,1] neg_hi:[0,0,1]
	v_pk_fma_f32 v[2:3], v[190:191], v[2:3], v[4:5] op_sel:[1,0,1] op_sel_hi:[1,1,0]
	s_nop 0
	v_mov_b32_e32 v9, v3
	v_pk_add_f32 v[2:3], v[112:113], v[12:13]
	s_nop 0
	v_pk_mul_f32 v[4:5], v[192:193], v[2:3] op_sel_hi:[0,1]
	v_pk_fma_f32 v[10:11], v[190:191], v[2:3], v[4:5] op_sel:[0,0,1] op_sel_hi:[1,1,0] neg_lo:[0,0,1] neg_hi:[0,0,1]
	v_pk_fma_f32 v[2:3], v[190:191], v[2:3], v[4:5] op_sel:[0,0,1] op_sel_hi:[0,1,0]
	v_mov_b32_e32 v11, v3
	v_mov_b32_e32 v2, v82
	v_mov_b32_e32 v3, v114
	v_pk_add_f32 v[2:3], v[2:3], v[10:11]
	v_mov_b32_e32 v114, v83
	v_pk_mul_f32 v[4:5], v[192:193], v[2:3] op_sel_hi:[0,1]
	v_pk_fma_f32 v[10:11], v[190:191], v[2:3], v[4:5] op_sel:[0,0,1] op_sel_hi:[1,1,0] neg_lo:[0,0,1] neg_hi:[0,0,1]
	v_pk_fma_f32 v[2:3], v[190:191], v[2:3], v[4:5] op_sel:[0,0,1] op_sel_hi:[0,1,0]
	v_mov_b32_e32 v11, v3
	v_pk_add_f32 v[2:3], v[114:115], v[10:11]
	s_nop 0
	v_pk_mul_f32 v[4:5], v[192:193], v[2:3] op_sel_hi:[0,1]
	v_pk_fma_f32 v[10:11], v[190:191], v[2:3], v[4:5] op_sel:[0,0,1] op_sel_hi:[1,1,0] neg_lo:[0,0,1] neg_hi:[0,0,1]
	v_pk_fma_f32 v[2:3], v[190:191], v[2:3], v[4:5] op_sel:[0,0,1] op_sel_hi:[0,1,0]
	v_mov_b32_e32 v11, v3
	v_mov_b32_e32 v2, v84
	v_mov_b32_e32 v3, v116
	v_pk_add_f32 v[2:3], v[2:3], v[10:11]
	v_mov_b32_e32 v116, v85
	v_mul_f32_e32 v4, v192, v3
	v_pk_fma_f32 v[0:1], v[0:1], v[2:3], v[4:5] op_sel_hi:[1,1,0] neg_lo:[0,0,1] neg_hi:[0,0,1]
	v_mul_f32_e32 v4, v192, v2
	v_pk_fma_f32 v[2:3], v[16:17], v[2:3], v[4:5] op_sel_hi:[1,1,0]
	v_pk_add_f32 v[4:5], v[96:97], v[8:9]
	v_mov_b32_e32 v1, v3
	v_pk_mul_f32 v[8:9], v[192:193], v[4:5] op_sel:[1,0]
	v_pk_add_f32 v[0:1], v[116:117], v[0:1]
	v_pk_fma_f32 v[10:11], v[190:191], v[4:5], v[8:9] op_sel:[1,0,1] op_sel_hi:[1,1,0] neg_lo:[0,0,1] neg_hi:[0,0,1]
	v_pk_fma_f32 v[4:5], v[190:191], v[4:5], v[8:9] op_sel:[1,0,1] op_sel_hi:[1,1,0]
	s_nop 0
	v_mov_b32_e32 v11, v5
	v_mov_b32_e32 v4, v66
	v_mov_b32_e32 v5, v98
	v_pk_add_f32 v[4:5], v[4:5], v[10:11]
	v_mov_b32_e32 v98, v67
	v_pk_mul_f32 v[8:9], v[192:193], v[4:5] op_sel:[1,0]
	s_nop 0
	v_pk_fma_f32 v[10:11], v[190:191], v[4:5], v[8:9] op_sel:[1,0,1] op_sel_hi:[1,1,0] neg_lo:[0,0,1] neg_hi:[0,0,1]
	v_pk_fma_f32 v[4:5], v[190:191], v[4:5], v[8:9] op_sel:[1,0,1] op_sel_hi:[1,1,0]
	s_nop 0
	v_mov_b32_e32 v11, v5
	v_pk_add_f32 v[4:5], v[98:99], v[10:11]
	s_nop 0
	v_pk_mul_f32 v[8:9], v[192:193], v[4:5] op_sel:[1,0]
	s_nop 0
	v_pk_fma_f32 v[10:11], v[190:191], v[4:5], v[8:9] op_sel:[1,0,1] op_sel_hi:[1,1,0] neg_lo:[0,0,1] neg_hi:[0,0,1]
	v_pk_fma_f32 v[4:5], v[190:191], v[4:5], v[8:9] op_sel:[1,0,1] op_sel_hi:[1,1,0]
	s_nop 0
	v_mov_b32_e32 v11, v5
	v_mov_b32_e32 v4, v68
	v_mov_b32_e32 v5, v100
	v_pk_add_f32 v[4:5], v[4:5], v[10:11]
	v_mov_b32_e32 v100, v69
	v_mul_f32_e32 v2, v193, v5
	v_pk_fma_f32 v[6:7], v[6:7], v[4:5], v[2:3] op_sel_hi:[1,1,0] neg_lo:[0,0,1] neg_hi:[0,0,1]
	v_mul_f32_e32 v2, v193, v4
	v_pk_fma_f32 v[4:5], v[18:19], v[4:5], v[2:3] op_sel_hi:[1,1,0]
	v_pk_mul_f32 v[2:3], v[192:193], v[0:1] op_sel_hi:[0,1]
	v_pk_fma_f32 v[8:9], v[190:191], v[0:1], v[2:3] op_sel:[0,0,1] op_sel_hi:[1,1,0] neg_lo:[0,0,1] neg_hi:[0,0,1]
	v_pk_fma_f32 v[0:1], v[190:191], v[0:1], v[2:3] op_sel:[0,0,1] op_sel_hi:[0,1,0]
	v_mov_b32_e32 v9, v1
	v_mov_b32_e32 v0, v86
	v_mov_b32_e32 v1, v118
	v_pk_add_f32 v[0:1], v[0:1], v[8:9]
	v_mov_b32_e32 v118, v87
	v_pk_mul_f32 v[2:3], v[192:193], v[0:1] op_sel_hi:[0,1]
	v_pk_fma_f32 v[8:9], v[190:191], v[0:1], v[2:3] op_sel:[0,0,1] op_sel_hi:[1,1,0] neg_lo:[0,0,1] neg_hi:[0,0,1]
	v_pk_fma_f32 v[0:1], v[190:191], v[0:1], v[2:3] op_sel:[0,0,1] op_sel_hi:[0,1,0]
	v_mov_b32_e32 v9, v1
	v_pk_add_f32 v[0:1], v[118:119], v[8:9]
	v_mov_b32_e32 v7, v5
	v_pk_mul_f32 v[2:3], v[192:193], v[0:1] op_sel_hi:[0,1]
	v_pk_fma_f32 v[8:9], v[190:191], v[0:1], v[2:3] op_sel:[0,0,1] op_sel_hi:[1,1,0] neg_lo:[0,0,1] neg_hi:[0,0,1]
	v_pk_fma_f32 v[0:1], v[190:191], v[0:1], v[2:3] op_sel:[0,0,1] op_sel_hi:[0,1,0]
	v_pk_add_f32 v[2:3], v[100:101], v[6:7]
	v_mov_b32_e32 v9, v1
	v_pk_mul_f32 v[4:5], v[192:193], v[2:3] op_sel:[1,0]
	v_mov_b32_e32 v0, v88
	v_pk_fma_f32 v[6:7], v[190:191], v[2:3], v[4:5] op_sel:[1,0,1] op_sel_hi:[1,1,0] neg_lo:[0,0,1] neg_hi:[0,0,1]
	v_pk_fma_f32 v[2:3], v[190:191], v[2:3], v[4:5] op_sel:[1,0,1] op_sel_hi:[1,1,0]
	v_mov_b32_e32 v1, v120
	v_mov_b32_e32 v7, v3
	v_mov_b32_e32 v2, v70
	v_mov_b32_e32 v3, v102
	v_pk_add_f32 v[2:3], v[2:3], v[6:7]
	v_mov_b32_e32 v102, v71
	v_pk_mul_f32 v[4:5], v[192:193], v[2:3] op_sel:[1,0]
	v_pk_add_f32 v[0:1], v[0:1], v[8:9]
	v_pk_fma_f32 v[6:7], v[190:191], v[2:3], v[4:5] op_sel:[1,0,1] op_sel_hi:[1,1,0] neg_lo:[0,0,1] neg_hi:[0,0,1]
	v_pk_fma_f32 v[2:3], v[190:191], v[2:3], v[4:5] op_sel:[1,0,1] op_sel_hi:[1,1,0]
	v_mov_b32_e32 v120, v89
	v_mov_b32_e32 v7, v3
	v_pk_add_f32 v[2:3], v[102:103], v[6:7]
	s_nop 0
	v_pk_mul_f32 v[4:5], v[192:193], v[2:3] op_sel:[1,0]
	s_nop 0
	v_pk_fma_f32 v[6:7], v[190:191], v[2:3], v[4:5] op_sel:[1,0,1] op_sel_hi:[1,1,0] neg_lo:[0,0,1] neg_hi:[0,0,1]
	v_pk_fma_f32 v[2:3], v[190:191], v[2:3], v[4:5] op_sel:[1,0,1] op_sel_hi:[1,1,0]
	v_pk_mul_f32 v[4:5], v[192:193], v[0:1] op_sel_hi:[0,1]
	v_mov_b32_e32 v7, v3
	v_mov_b32_e32 v2, v72
	v_mov_b32_e32 v3, v104
	v_pk_add_f32 v[2:3], v[2:3], v[6:7]
	v_pk_fma_f32 v[6:7], v[190:191], v[0:1], v[4:5] op_sel:[0,0,1] op_sel_hi:[1,1,0] neg_lo:[0,0,1] neg_hi:[0,0,1]
	v_pk_fma_f32 v[0:1], v[190:191], v[0:1], v[4:5] op_sel:[0,0,1] op_sel_hi:[0,1,0]
	v_mov_b32_e32 v7, v1
	v_pk_add_f32 v[0:1], v[120:121], v[6:7]
	v_mov_b32_e32 v104, v73
	v_pk_mul_f32 v[4:5], v[192:193], v[0:1] op_sel_hi:[0,1]
	v_pk_fma_f32 v[6:7], v[190:191], v[0:1], v[4:5] op_sel:[0,0,1] op_sel_hi:[1,1,0] neg_lo:[0,0,1] neg_hi:[0,0,1]
	v_pk_fma_f32 v[0:1], v[190:191], v[0:1], v[4:5] op_sel:[0,0,1] op_sel_hi:[0,1,0]
	v_mov_b32_e32 v7, v1
	v_mov_b32_e32 v0, v90
	v_mov_b32_e32 v1, v122
	v_pk_add_f32 v[0:1], v[0:1], v[6:7]
	v_mov_b32_e32 v122, v91
	v_pk_mul_f32 v[4:5], v[192:193], v[0:1] op_sel_hi:[0,1]
	v_pk_fma_f32 v[6:7], v[190:191], v[0:1], v[4:5] op_sel:[0,0,1] op_sel_hi:[1,1,0] neg_lo:[0,0,1] neg_hi:[0,0,1]
	v_pk_fma_f32 v[0:1], v[190:191], v[0:1], v[4:5] op_sel:[0,0,1] op_sel_hi:[0,1,0]
	v_mov_b32_e32 v7, v1
	v_pk_add_f32 v[0:1], v[122:123], v[6:7]
	s_nop 0
	v_pk_mul_f32 v[4:5], v[192:193], v[0:1] op_sel_hi:[0,1]
	v_pk_fma_f32 v[6:7], v[190:191], v[0:1], v[4:5] op_sel:[0,0,1] op_sel_hi:[1,1,0] neg_lo:[0,0,1] neg_hi:[0,0,1]
	v_pk_fma_f32 v[0:1], v[190:191], v[0:1], v[4:5] op_sel:[0,0,1] op_sel_hi:[0,1,0]
	v_mov_b32_e32 v7, v1
	v_pk_mul_f32 v[0:1], v[192:193], v[2:3] op_sel:[1,0]
	s_nop 0
	v_pk_fma_f32 v[4:5], v[190:191], v[2:3], v[0:1] op_sel:[1,0,1] op_sel_hi:[1,1,0] neg_lo:[0,0,1] neg_hi:[0,0,1]
	v_pk_fma_f32 v[0:1], v[190:191], v[2:3], v[0:1] op_sel:[1,0,1] op_sel_hi:[1,1,0]
	s_nop 0
	v_mov_b32_e32 v5, v1
	v_pk_add_f32 v[0:1], v[104:105], v[4:5]
	s_nop 0
	v_pk_mul_f32 v[2:3], v[192:193], v[0:1] op_sel:[1,0]
	s_nop 0
	v_pk_fma_f32 v[4:5], v[190:191], v[0:1], v[2:3] op_sel:[1,0,1] op_sel_hi:[1,1,0] neg_lo:[0,0,1] neg_hi:[0,0,1]
	v_pk_fma_f32 v[0:1], v[190:191], v[0:1], v[2:3] op_sel:[1,0,1] op_sel_hi:[1,1,0]
	s_nop 0
	v_mov_b32_e32 v5, v1
	v_mov_b32_e32 v0, v74
	v_mov_b32_e32 v1, v106
	v_pk_add_f32 v[0:1], v[0:1], v[4:5]
	v_mov_b32_e32 v106, v75
	v_pk_mul_f32 v[2:3], v[192:193], v[0:1] op_sel:[1,0]
	s_nop 0
	v_pk_fma_f32 v[4:5], v[190:191], v[0:1], v[2:3] op_sel:[1,0,1] op_sel_hi:[1,1,0] neg_lo:[0,0,1] neg_hi:[0,0,1]
	v_pk_fma_f32 v[0:1], v[190:191], v[0:1], v[2:3] op_sel:[1,0,1] op_sel_hi:[1,1,0]
	s_nop 0
	v_mov_b32_e32 v5, v1
	v_pk_add_f32 v[0:1], v[106:107], v[4:5]
	s_nop 0
	v_pk_mul_f32 v[2:3], v[192:193], v[0:1] op_sel:[1,0]
	s_nop 0
	v_pk_fma_f32 v[4:5], v[190:191], v[0:1], v[2:3] op_sel:[1,0,1] op_sel_hi:[1,1,0] neg_lo:[0,0,1] neg_hi:[0,0,1]
	v_pk_fma_f32 v[0:1], v[190:191], v[0:1], v[2:3] op_sel:[1,0,1] op_sel_hi:[1,1,0]
	s_nop 0
	v_mov_b32_e32 v5, v1
	v_mov_b32_e32 v0, v92
	v_mov_b32_e32 v1, v124
	v_pk_add_f32 v[0:1], v[0:1], v[6:7]
	v_mov_b32_e32 v124, v93
	v_pk_mul_f32 v[2:3], v[192:193], v[0:1] op_sel_hi:[0,1]
	v_pk_fma_f32 v[6:7], v[190:191], v[0:1], v[2:3] op_sel:[0,0,1] op_sel_hi:[1,1,0] neg_lo:[0,0,1] neg_hi:[0,0,1]
	v_pk_fma_f32 v[0:1], v[190:191], v[0:1], v[2:3] op_sel:[0,0,1] op_sel_hi:[0,1,0]
	v_mov_b32_e32 v7, v1
	v_pk_add_f32 v[0:1], v[124:125], v[6:7]
	s_nop 0
	v_pk_mul_f32 v[2:3], v[192:193], v[0:1] op_sel_hi:[0,1]
	v_pk_fma_f32 v[6:7], v[190:191], v[0:1], v[2:3] op_sel:[0,0,1] op_sel_hi:[1,1,0] neg_lo:[0,0,1] neg_hi:[0,0,1]
	v_pk_fma_f32 v[0:1], v[190:191], v[0:1], v[2:3] op_sel:[0,0,1] op_sel_hi:[0,1,0]
	v_mov_b32_e32 v7, v1
	v_mov_b32_e32 v0, v94
	v_mov_b32_e32 v1, v126
	v_pk_add_f32 v[0:1], v[0:1], v[6:7]
	v_mov_b32_e32 v126, v95
	v_pk_mul_f32 v[2:3], v[192:193], v[0:1] op_sel_hi:[0,1]
	v_pk_fma_f32 v[6:7], v[190:191], v[0:1], v[2:3] op_sel:[0,0,1] op_sel_hi:[1,1,0] neg_lo:[0,0,1] neg_hi:[0,0,1]
	v_pk_fma_f32 v[0:1], v[190:191], v[0:1], v[2:3] op_sel:[0,0,1] op_sel_hi:[0,1,0]
	v_mov_b32_e32 v2, v76
	v_mov_b32_e32 v3, v108
	v_pk_add_f32 v[2:3], v[2:3], v[4:5]
	v_mov_b32_e32 v7, v1
	v_pk_mul_f32 v[4:5], v[192:193], v[2:3] op_sel:[1,0]
	v_pk_add_f32 v[0:1], v[126:127], v[6:7]
	v_pk_fma_f32 v[6:7], v[190:191], v[2:3], v[4:5] op_sel:[1,0,1] op_sel_hi:[1,1,0] neg_lo:[0,0,1] neg_hi:[0,0,1]
	v_pk_fma_f32 v[2:3], v[190:191], v[2:3], v[4:5] op_sel:[1,0,1] op_sel_hi:[1,1,0]
	v_mov_b32_e32 v108, v77
	v_mov_b32_e32 v7, v3
	v_pk_add_f32 v[2:3], v[108:109], v[6:7]
	s_nop 0
	v_pk_mul_f32 v[4:5], v[192:193], v[2:3] op_sel:[1,0]
	s_nop 0
	v_pk_fma_f32 v[6:7], v[190:191], v[2:3], v[4:5] op_sel:[1,0,1] op_sel_hi:[1,1,0] neg_lo:[0,0,1] neg_hi:[0,0,1]
	v_pk_fma_f32 v[2:3], v[190:191], v[2:3], v[4:5] op_sel:[1,0,1] op_sel_hi:[1,1,0]
	s_nop 0
	v_mov_b32_e32 v7, v3
	v_mov_b32_e32 v2, v78
	v_mov_b32_e32 v3, v110
	v_pk_add_f32 v[2:3], v[2:3], v[6:7]
	v_mov_b32_e32 v110, v79
	v_pk_mul_f32 v[4:5], v[192:193], v[2:3] op_sel:[1,0]
	s_nop 0
	v_pk_fma_f32 v[6:7], v[190:191], v[2:3], v[4:5] op_sel:[1,0,1] op_sel_hi:[1,1,0] neg_lo:[0,0,1] neg_hi:[0,0,1]
	v_pk_fma_f32 v[2:3], v[190:191], v[2:3], v[4:5] op_sel:[1,0,1] op_sel_hi:[1,1,0]
	s_nop 0
	v_mov_b32_e32 v7, v3
	v_pk_add_f32 v[2:3], v[110:111], v[6:7]
	ds_write_b128 v198, v[0:3]
	s_waitcnt lgkmcnt(0)
	s_barrier
	s_cbranch_vccnz .LBB0_164
	v_pk_add_f32 v[2:3], v[190:191], v[190:191]
	v_pk_mul_f32 v[0:1], v[192:193], v[192:193]
	v_pk_mul_f32 v[2:3], v[192:193], v[2:3]
	v_pk_fma_f32 v[0:1], v[190:191], v[190:191], v[0:1] neg_lo:[0,0,1] neg_hi:[0,0,1]
	v_pk_mul_f32 v[4:5], v[2:3], v[2:3]
	s_andn2_b64 vcc, exec, s[36:37]
	v_pk_fma_f32 v[4:5], v[0:1], v[0:1], v[4:5] neg_lo:[0,0,1] neg_hi:[0,0,1]
	v_pk_add_f32 v[0:1], v[0:1], v[0:1]
	s_nop 0
	v_pk_mul_f32 v[0:1], v[2:3], v[0:1]
	s_nop 0
	v_pk_mul_f32 v[2:3], v[0:1], v[0:1]
	s_nop 0
	v_pk_fma_f32 v[2:3], v[4:5], v[4:5], v[2:3] neg_lo:[0,0,1] neg_hi:[0,0,1]
	v_pk_add_f32 v[4:5], v[4:5], v[4:5]
	s_nop 0
	v_pk_mul_f32 v[0:1], v[0:1], v[4:5]
	s_nop 0
	v_pk_mul_f32 v[4:5], v[0:1], v[0:1]
	s_nop 0
	v_pk_fma_f32 v[4:5], v[2:3], v[2:3], v[4:5] neg_lo:[0,0,1] neg_hi:[0,0,1]
	v_pk_add_f32 v[2:3], v[2:3], v[2:3]
	v_pk_add_f32 v[6:7], v[4:5], v[4:5]
	v_pk_mul_f32 v[2:3], v[0:1], v[2:3]
	s_nop 0
	v_pk_mul_f32 v[0:1], v[2:3], v[2:3]
	v_pk_mul_f32 v[2:3], v[2:3], v[6:7]
	v_pk_fma_f32 v[0:1], v[4:5], v[4:5], v[0:1] neg_lo:[0,0,1] neg_hi:[0,0,1]
	ds_read_b128 v[4:7], v196
	v_pk_mul_f32 v[10:11], v[192:193], v[2:3]
	v_pk_mul_f32 v[8:9], v[192:193], v[0:1]
	v_pk_fma_f32 v[10:11], v[190:191], v[0:1], v[10:11] neg_lo:[0,0,1] neg_hi:[0,0,1]
	v_pk_fma_f32 v[8:9], v[190:191], v[2:3], v[8:9]
	v_pk_mul_f32 v[10:11], v[10:11], 0 op_sel_hi:[1,0]
	s_nop 0
	v_pk_fma_f32 v[12:13], v[8:9], 0, v[10:11] op_sel_hi:[1,0,1] neg_lo:[1,0,0] neg_hi:[1,0,0]
	v_pk_fma_f32 v[8:9], v[8:9], 0, v[10:11] op_sel_hi:[1,0,1]
	s_waitcnt lgkmcnt(0)
	v_mov_b32_e32 v10, v4
	v_mov_b32_e32 v11, v6
	v_mov_b32_e32 v6, v5
	v_pk_add_f32 v[48:49], v[12:13], v[10:11]
	v_pk_add_f32 v[50:51], v[8:9], v[6:7]
	s_cbranch_vccnz .LBB0_168
	s_andn2_b64 vcc, exec, s[38:39]
	s_mov_b32 s2, 1
	s_cbranch_vccnz .LBB0_165
	s_mov_b32 s2, 0
	v_mov_b32_e32 v4, v203

.LBB0_185:
	s_or_b64 exec, exec, s[2:3]
	s_lshl_b32 s24, s14, 2
	v_lshl_add_u64 v[0:1], v[160:161], 0, s[24:25]
	s_waitcnt vmcnt(0)
	global_load_dwordx4 v[96:99], v[0:1], off
	global_load_dwordx4 v[100:103], v[0:1], off offset:32
	s_lshl_b32 s2, s66, 7
	s_and_b32 s2, s2, 0xffffe000
	v_or3_b32 v120, s2, v197, v155
	v_ashrrev_i32_e32 v121, 31, v120
	v_lshl_add_u64 v[0:1], v[168:169], 0, v[120:121]
	v_lshl_add_u64 v[2:3], v[166:167], 0, v[120:121]
	v_lshl_add_u64 v[4:5], v[164:165], 0, v[120:121]
	v_lshl_add_u64 v[6:7], v[162:163], 0, v[120:121]
	v_cndmask_b32_e64 v1, v1, 0, s[10:11]
	v_cndmask_b32_e64 v0, v0, v154, s[10:11]
	v_cndmask_b32_e64 v3, v3, 0, s[8:9]
	v_cndmask_b32_e64 v2, v2, v154, s[8:9]
	v_cndmask_b32_e64 v5, v5, 0, s[6:7]
	v_cndmask_b32_e64 v4, v4, v154, s[6:7]
	v_cndmask_b32_e64 v7, v7, 0, s[4:5]
	v_cndmask_b32_e64 v6, v6, v154, s[4:5]
	v_lshlrev_b64 v[0:1], 11, v[0:1]
	v_mov_b32_e32 v185, v149
	v_lshlrev_b64 v[2:3], 11, v[2:3]
	v_lshlrev_b64 v[4:5], 11, v[4:5]
	v_lshlrev_b64 v[6:7], 11, v[6:7]
	v_lshl_add_u64 v[0:1], s[84:85], 0, v[0:1]
	v_lshl_add_u64 v[2:3], s[84:85], 0, v[2:3]
	v_lshl_add_u64 v[4:5], s[84:85], 0, v[4:5]
	v_lshl_add_u64 v[6:7], s[84:85], 0, v[6:7]
	v_lshl_add_u64 v[0:1], v[0:1], 0, v[184:185]
	v_lshl_add_u64 v[2:3], v[2:3], 0, v[184:185]
	v_lshl_add_u64 v[4:5], v[4:5], 0, v[184:185]
	v_lshl_add_u64 v[6:7], v[6:7], 0, v[184:185]
	s_lshl_b32 s24, s14, 1
	s_cmp_lt_u32 s66, 64
	s_cselect_b64 s[2:3], -1, 0
	v_lshl_add_u64 v[126:127], v[170:171], 0, s[24:25]
	v_lshl_add_u64 v[184:185], s[84:85], 0, v[184:185]
	s_and_b64 s[50:51], s[2:3], s[12:13]
	s_mov_b32 s24, s28
	s_waitcnt vmcnt(0)
	global_load_dwordx4 v[112:115], v[0:1], off
	global_load_dwordx4 v[116:119], v[2:3], off
	global_load_dwordx4 v[104:107], v[4:5], off
	global_load_dwordx4 v[108:111], v[6:7], off
	v_add_u32_e32 v0, s15, v205
	v_ashrrev_i32_e32 v1, 31, v0
	v_lshl_add_u64 v[122:123], s[42:43], 0, v[0:1]
	v_lshl_add_u64 v[124:125], s[44:45], 0, v[0:1]
	v_mov_b32_e32 v240, 0xbdd2d3e7
	s_waitcnt vmcnt(0)
	s_branch .LBB0_188

.LBB0_188:
	s_waitcnt vmcnt(9)
	v_mfma_f32_32x32x16_bf16 v[16:31], v[108:111], v[132:135], 0
	v_mov_b32_e32 v33, v51
	v_mul_f32_e64 v34, v174, v32
	v_mul_f32_e64 v35, v175, v33
	v_add_u32_e32 v148, v200, v150
	v_sub_f32_e32 v33, v34, v35
	v_mov_b32_e32 v34, v51
	v_mov_b32_e32 v35, v32
	v_pk_mul_f32 v[50:51], v[176:177], v[50:51] op_sel_hi:[1,0]
	v_pk_mul_f32 v[52:53], v[174:175], v[34:35]
	v_pk_fma_f32 v[188:189], v[172:173], v[48:49], v[50:51] neg_lo:[0,0,1] neg_hi:[0,0,1]
	v_pk_fma_f32 v[48:49], v[172:173], v[48:49], v[50:51] op_sel_hi:[1,0,1]
	v_mfma_f32_32x32x16_bf16 v[0:15], v[108:111], v[128:131], 0
	v_add_f32_e32 v186, v33, v16
	v_add_f32_e32 v16, v52, v53
	v_mov_b32_e32 v189, v49
	ds_write_b128 v148, v[108:111] offset:8192
	s_cmp_gt_i32 s24, 0
	s_cselect_b64 s[2:3], -1, 0
	s_or_b64 s[14:15], s[2:3], s[50:51]
	v_mfma_f32_32x32x16_bf16 v[48:63], v[108:111], v[136:139], 0
	s_nop 3
	v_mov_b32_e32 v190, v0
	v_mfma_f32_32x32x16_bf16 v[32:47], v[108:111], v[140:143], 0
	s_nop 5
	v_mov_b32_e32 v191, v48
	v_add_f32_e64 v108, v188, v190
	v_add_f32_e64 v109, v189, v191
	v_mul_f32_e64 v110, v172, v108
	v_mul_f32_e64 v111, v173, v109
	v_sub_f32_e32 v0, v110, v111
	v_pk_mul_f32 v[110:111], v[176:177], v[108:109]
	v_add_f32_e32 v16, v16, v32
	v_add_f32_e32 v0, v1, v0
	v_add_f32_e32 v1, v110, v111
	v_add_f32_e32 v110, v49, v1
	v_pk_mul_f32 v[48:49], v[178:179], v[16:17] op_sel_hi:[1,0]
	v_mov_b32_e32 v32, v17
	v_pk_fma_f32 v[188:189], v[174:175], v[186:187], v[48:49] neg_lo:[0,0,1] neg_hi:[0,0,1]
	v_pk_fma_f32 v[48:49], v[174:175], v[186:187], v[48:49] op_sel_hi:[1,0,1]
	s_nop 0
	v_mov_b32_e32 v189, v49
	v_pk_add_f32 v[32:33], v[32:33], v[188:189]
	s_nop 0
	v_pk_mul_f32 v[48:49], v[174:175], v[32:33]
	s_nop 0
	v_sub_f32_e32 v1, v48, v49
	v_pk_mul_f32 v[48:49], v[178:179], v[32:33]
	v_add_f32_e32 v189, v18, v1
	v_add_f32_e32 v1, v48, v49
	v_pk_mul_f32 v[48:49], v[176:177], v[110:111] op_sel_hi:[1,0]
	v_add_f32_e32 v191, v34, v1
	v_pk_fma_f32 v[192:193], v[172:173], v[0:1], v[48:49] neg_lo:[0,0,1] neg_hi:[0,0,1]
	v_pk_fma_f32 v[48:49], v[172:173], v[0:1], v[48:49] op_sel_hi:[1,0,1]
	v_mul_f32_e32 v213, v174, v189
	v_mov_b32_e32 v193, v49
	v_mov_b32_e32 v48, v2
	v_mov_b32_e32 v49, v50
	v_pk_add_f32 v[192:193], v[48:49], v[192:193]
	v_mul_f32_e32 v215, v175, v191
	v_pk_mul_f32 v[48:49], v[172:173], v[192:193]
	v_mov_b32_e32 v18, v3
	v_mov_b32_e32 v212, v48
	v_mov_b32_e32 v214, v49
	v_pk_add_f32 v[48:49], v[212:213], v[214:215] neg_lo:[0,1] neg_hi:[0,1]
	v_mov_b32_e32 v190, v193
	v_pk_add_f32 v[2:3], v[18:19], v[48:49]
	v_pk_mul_f32 v[18:19], v[180:181], v[190:191]
	v_mov_b32_e32 v188, v192
	v_pk_fma_f32 v[18:19], v[182:183], v[188:189], v[18:19]
	v_mov_b32_e32 v34, v51
	v_pk_add_f32 v[18:19], v[34:35], v[18:19]
	v_mov_b32_e32 v48, v4
	v_pk_mul_f32 v[34:35], v[182:183], v[18:19]
	v_mov_b32_e32 v49, v20
	v_pk_fma_f32 v[34:35], v[180:181], v[2:3], v[34:35] neg_lo:[0,0,1] neg_hi:[0,0,1]
	v_mov_b32_e32 v50, v52
	v_pk_add_f32 v[34:35], v[48:49], v[34:35]
	v_pk_mul_f32 v[48:49], v[180:181], v[18:19]
	v_mov_b32_e32 v51, v36
	v_pk_fma_f32 v[48:49], v[182:183], v[2:3], v[48:49]
	v_mov_b32_e32 v20, v5
	v_pk_add_f32 v[212:213], v[50:51], v[48:49]
	v_mov_b32_e32 v36, v53
	v_pk_mul_f32 v[48:49], v[182:183], v[212:213]
	v_pk_mul_f32 v[50:51], v[180:181], v[212:213]
	v_pk_fma_f32 v[48:49], v[180:181], v[34:35], v[48:49] neg_lo:[0,0,1] neg_hi:[0,0,1]
	v_pk_fma_f32 v[50:51], v[182:183], v[34:35], v[50:51]
	v_pk_add_f32 v[4:5], v[20:21], v[48:49]
	v_pk_add_f32 v[20:21], v[36:37], v[50:51]
	v_mov_b32_e32 v48, v6
	v_pk_mul_f32 v[36:37], v[182:183], v[20:21]
	v_mov_b32_e32 v49, v22
	v_pk_fma_f32 v[36:37], v[180:181], v[4:5], v[36:37] neg_lo:[0,0,1] neg_hi:[0,0,1]
	v_mov_b32_e32 v50, v54
	v_pk_add_f32 v[36:37], v[48:49], v[36:37]
	v_pk_mul_f32 v[48:49], v[180:181], v[20:21]
	v_mov_b32_e32 v51, v38
	v_pk_fma_f32 v[48:49], v[182:183], v[4:5], v[48:49]
	v_mov_b32_e32 v22, v7
	v_pk_add_f32 v[52:53], v[50:51], v[48:49]
	v_mov_b32_e32 v38, v55
	v_pk_mul_f32 v[48:49], v[182:183], v[52:53]
	v_mov_b32_e32 v214, v8
	v_pk_fma_f32 v[48:49], v[180:181], v[36:37], v[48:49] neg_lo:[0,0,1] neg_hi:[0,0,1]
	v_mov_b32_e32 v215, v24
	v_pk_add_f32 v[6:7], v[22:23], v[48:49]
	v_pk_mul_f32 v[22:23], v[180:181], v[52:53]
	v_mov_b32_e32 v48, v56
	v_pk_fma_f32 v[22:23], v[182:183], v[36:37], v[22:23]
	v_mov_b32_e32 v49, v40
	v_pk_add_f32 v[22:23], v[38:39], v[22:23]
	v_mov_b32_e32 v24, v9
	v_pk_mul_f32 v[38:39], v[180:181], v[22:23]
	v_pk_mul_f32 v[54:55], v[182:183], v[22:23]
	v_pk_fma_f32 v[38:39], v[182:183], v[6:7], v[38:39]
	v_pk_fma_f32 v[54:55], v[180:181], v[6:7], v[54:55] neg_lo:[0,0,1] neg_hi:[0,0,1]
	v_pk_add_f32 v[38:39], v[48:49], v[38:39]
	v_pk_add_f32 v[54:55], v[214:215], v[54:55]
	v_pk_mul_f32 v[48:49], v[182:183], v[38:39]
	v_pk_mul_f32 v[50:51], v[180:181], v[38:39]
	v_pk_fma_f32 v[48:49], v[180:181], v[54:55], v[48:49] neg_lo:[0,0,1] neg_hi:[0,0,1]
	v_mov_b32_e32 v40, v57
	v_pk_add_f32 v[8:9], v[24:25], v[48:49]
	v_pk_fma_f32 v[24:25], v[182:183], v[54:55], v[50:51]
	v_mov_b32_e32 v48, v10
	v_pk_add_f32 v[24:25], v[40:41], v[24:25]
	v_mov_b32_e32 v49, v26
	v_pk_mul_f32 v[40:41], v[182:183], v[24:25]
	v_mov_b32_e32 v50, v58
	v_pk_fma_f32 v[40:41], v[180:181], v[8:9], v[40:41] neg_lo:[0,0,1] neg_hi:[0,0,1]
	v_mov_b32_e32 v51, v42
	v_pk_add_f32 v[40:41], v[48:49], v[40:41]
	v_pk_mul_f32 v[48:49], v[180:181], v[24:25]
	v_mov_b32_e32 v26, v11
	v_pk_fma_f32 v[48:49], v[182:183], v[8:9], v[48:49]
	v_mov_b32_e32 v42, v59
	v_pk_add_f32 v[56:57], v[50:51], v[48:49]
	v_mov_b32_e32 v50, v60
	v_pk_mul_f32 v[48:49], v[182:183], v[56:57]
	v_mov_b32_e32 v51, v44
	v_pk_fma_f32 v[48:49], v[180:181], v[40:41], v[48:49] neg_lo:[0,0,1] neg_hi:[0,0,1]
	v_mov_b32_e32 v44, v61
	v_pk_add_f32 v[10:11], v[26:27], v[48:49]
	v_pk_mul_f32 v[26:27], v[180:181], v[56:57]
	v_mov_b32_e32 v48, v12
	v_pk_fma_f32 v[26:27], v[182:183], v[40:41], v[26:27]
	v_mov_b32_e32 v49, v28
	v_pk_add_f32 v[26:27], v[42:43], v[26:27]
	v_mov_b32_e32 v28, v13
	v_pk_mul_f32 v[42:43], v[182:183], v[26:27]
	v_cvt_pk_bf16_f32 v0, v108, v0
	v_pk_fma_f32 v[42:43], v[180:181], v[10:11], v[42:43] neg_lo:[0,0,1] neg_hi:[0,0,1]
	v_cvt_pk_bf16_f32 v1, v192, v2
	v_pk_add_f32 v[42:43], v[48:49], v[42:43]
	v_pk_mul_f32 v[48:49], v[180:181], v[26:27]
	v_cvt_pk_bf16_f32 v2, v186, v32
	v_pk_fma_f32 v[48:49], v[182:183], v[10:11], v[48:49]
	v_cvt_pk_bf16_f32 v3, v189, v3
	v_pk_add_f32 v[58:59], v[50:51], v[48:49]
	v_mov_b32_e32 v50, v62
	v_pk_mul_f32 v[48:49], v[182:183], v[58:59]
	v_mov_b32_e32 v51, v46
	v_pk_fma_f32 v[48:49], v[180:181], v[42:43], v[48:49] neg_lo:[0,0,1] neg_hi:[0,0,1]
	v_mov_b32_e32 v46, v63
	v_pk_add_f32 v[12:13], v[28:29], v[48:49]
	v_pk_mul_f32 v[28:29], v[180:181], v[58:59]
	v_mov_b32_e32 v48, v14
	v_pk_fma_f32 v[28:29], v[182:183], v[42:43], v[28:29]
	v_mov_b32_e32 v49, v30
	v_pk_add_f32 v[28:29], v[44:45], v[28:29]
	v_mov_b32_e32 v30, v15
	v_pk_mul_f32 v[44:45], v[182:183], v[28:29]
	ds_write2st64_b64 v207, v[0:1], v[2:3] offset1:4
	v_pk_fma_f32 v[44:45], v[180:181], v[12:13], v[44:45] neg_lo:[0,0,1] neg_hi:[0,0,1]
	v_cvt_pk_bf16_f32 v0, v35, v5
	v_pk_add_f32 v[44:45], v[48:49], v[44:45]
	v_pk_mul_f32 v[48:49], v[180:181], v[28:29]
	v_cvt_pk_bf16_f32 v1, v37, v7
	v_pk_fma_f32 v[48:49], v[182:183], v[12:13], v[48:49]
	v_pk_mov_b32 v[2:3], v[192:193], v[18:19] op_sel:[1,0]
	v_pk_add_f32 v[60:61], v[50:51], v[48:49]
	v_cvt_pk_bf16_f32 v5, v56, v26
	v_pk_mul_f32 v[14:15], v[180:181], v[60:61]
	v_pk_mul_f32 v[48:49], v[182:183], v[60:61]
	v_pk_fma_f32 v[14:15], v[182:183], v[44:45], v[14:15]
	v_pk_fma_f32 v[48:49], v[180:181], v[44:45], v[48:49] neg_lo:[0,0,1] neg_hi:[0,0,1]
	v_pk_add_f32 v[50:51], v[46:47], v[14:15]
	v_cvt_pk_bf16_f32 v14, v34, v4
	v_cvt_pk_bf16_f32 v15, v36, v6
	v_pk_add_f32 v[48:49], v[30:31], v[48:49]
	v_cvt_pk_bf16_f32 v30, v54, v8
	v_cvt_pk_bf16_f32 v31, v40, v10
	ds_write2st64_b64 v208, v[14:15], v[0:1] offset1:4
	v_cvt_pk_bf16_f32 v0, v55, v9
	v_cvt_pk_bf16_f32 v1, v41, v11
	v_cvt_pk_bf16_f32 v46, v42, v12
	v_cvt_pk_bf16_f32 v47, v44, v48
	ds_write2st64_b64 v209, v[30:31], v[0:1] offset1:4
	v_cvt_pk_bf16_f32 v0, v43, v13
	v_cvt_pk_bf16_f32 v1, v45, v49
	ds_write2st64_b64 v210, v[46:47], v[0:1] offset1:4
	v_cvt_pk_bf16_f32 v0, v109, v110
	v_cvt_pk_bf16_f32 v1, v2, v3
	v_cvt_pk_bf16_f32 v8, v16, v33
	v_cvt_pk_bf16_f32 v9, v191, v19
	v_cvt_pk_bf16_f32 v2, v212, v20
	v_cvt_pk_bf16_f32 v3, v52, v22
	ds_write2st64_b64 v207, v[0:1], v[8:9] offset0:8 offset1:12
	v_cvt_pk_bf16_f32 v0, v213, v21
	v_cvt_pk_bf16_f32 v1, v53, v23
	v_cvt_pk_bf16_f32 v4, v38, v24
	ds_write2st64_b64 v208, v[2:3], v[0:1] offset0:8 offset1:12
	v_cvt_pk_bf16_f32 v0, v39, v25
	v_cvt_pk_bf16_f32 v1, v57, v27
	v_cvt_pk_bf16_f32 v6, v58, v28
	v_cvt_pk_bf16_f32 v7, v60, v50
	ds_write2st64_b64 v209, v[4:5], v[0:1] offset0:8 offset1:12
	v_cvt_pk_bf16_f32 v0, v59, v29
	v_cvt_pk_bf16_f32 v1, v61, v51
	ds_write2st64_b64 v210, v[6:7], v[0:1] offset0:8 offset1:12
	s_waitcnt lgkmcnt(0)
	ds_read_b64_tr_b16 v[0:1], v151 offset:0
	ds_read_b64_tr_b16 v[2:3], v199 offset:0
	ds_read_b64_tr_b16 v[28:29], v151 offset:1024
	ds_read_b64_tr_b16 v[30:31], v199 offset:1024
	ds_read_b64_tr_b16 v[24:25], v151 offset:2048
	ds_read_b64_tr_b16 v[26:27], v199 offset:2048
	ds_read_b64_tr_b16 v[20:21], v151 offset:3072
	ds_read_b64_tr_b16 v[22:23], v199 offset:3072
	ds_read_b64_tr_b16 v[16:17], v151 offset:4096
	ds_read_b64_tr_b16 v[18:19], v199 offset:4096
	ds_read_b64_tr_b16 v[44:45], v151 offset:5120
	ds_read_b64_tr_b16 v[46:47], v199 offset:5120
	ds_read_b64_tr_b16 v[40:41], v151 offset:6144
	ds_read_b64_tr_b16 v[42:43], v199 offset:6144
	ds_read_b64_tr_b16 v[52:53], v151 offset:7168
	ds_read_b64_tr_b16 v[54:55], v199 offset:7168
	s_waitcnt lgkmcnt(0)
	s_nop 0
	v_mfma_f32_32x32x16_bf16 v[0:15], v[68:71], v[0:3], 0
	v_mfma_f32_32x32x16_bf16 v[0:15], v[64:67], v[28:31], v[0:15]
	v_mfma_f32_32x32x16_bf16 v[0:15], v[76:79], v[24:27], v[0:15]
	v_mfma_f32_32x32x16_bf16 v[0:15], v[72:75], v[20:23], v[0:15]
	v_mfma_f32_32x32x16_bf16 v[0:15], v[84:87], v[16:19], v[0:15]
	v_mfma_f32_32x32x16_bf16 v[0:15], v[80:83], v[44:47], v[0:15]
	v_mfma_f32_32x32x16_bf16 v[0:15], v[92:95], v[40:43], v[0:15]
	v_mfma_f32_32x32x16_bf16 v[0:15], v[88:91], v[52:55], v[0:15]
	s_and_saveexec_b64 s[2:3], s[14:15]
	s_cbranch_execz .LBB0_190
	s_nop 7
	v_add_u32_e32 v16, v200, v146
	v_add_u32_e32 v16, 0x2000, v16
	ds_read2_b64 v[16:19], v16 offset1:2
	s_waitcnt lgkmcnt(0)
	v_lshlrev_b32_e32 v10, 16, v19
	v_and_b32_e32 v11, 0xffff0000, v19
	v_pk_fma_f32 v[6:7], v[102:103], v[10:11], v[6:7]
	v_mul_f32_e32 v10, v7, v7
	v_fmaak_f32 v10, v240, v10, 0xc0135761
	v_mul_f32_e32 v11, v6, v6
	v_mul_f32_e32 v10, v7, v10
	v_fmaak_f32 v11, v240, v11, 0xc0135761
	v_mul_f32_e32 v11, v6, v11
	v_exp_f32_e32 v10, v10
	v_exp_f32_e32 v11, v11
	v_add_f32_e32 v8, 1.0, v10
	v_rcp_f32_e32 v9, v8
	v_add_f32_e32 v8, 1.0, v11
	v_lshlrev_b32_e32 v10, 16, v18
	v_and_b32_e32 v11, 0xffff0000, v18
	v_pk_fma_f32 v[4:5], v[100:101], v[10:11], v[4:5]
	v_and_b32_e32 v13, 0xffff0000, v17
	v_mul_f32_e32 v10, v5, v5
	v_fmaak_f32 v10, v240, v10, 0xc0135761
	v_mul_f32_e32 v11, v4, v4
	v_mul_f32_e32 v10, v5, v10
	v_fmaak_f32 v11, v240, v11, 0xc0135761
	v_mul_f32_e32 v11, v4, v11
	v_exp_f32_e32 v10, v10
	v_exp_f32_e32 v12, v11
	v_and_b32_e32 v15, 0xffff0000, v16
	v_add_f32_e32 v10, 1.0, v10
	v_rcp_f32_e32 v11, v10
	v_add_f32_e32 v10, 1.0, v12
	v_lshlrev_b32_e32 v12, 16, v17
	v_pk_fma_f32 v[2:3], v[98:99], v[12:13], v[2:3]
	v_rcp_f32_e32 v8, v8
	v_mul_f32_e32 v12, v3, v3
	v_fmaak_f32 v12, v240, v12, 0xc0135761
	v_mul_f32_e32 v13, v2, v2
	v_mul_f32_e32 v12, v3, v12
	v_fmaak_f32 v13, v240, v13, 0xc0135761
	v_mul_f32_e32 v13, v2, v13
	v_exp_f32_e32 v12, v12
	v_exp_f32_e32 v14, v13
	v_rcp_f32_e32 v10, v10
	v_add_f32_e32 v12, 1.0, v12
	v_rcp_f32_e32 v13, v12
	v_add_f32_e32 v12, 1.0, v14
	v_lshlrev_b32_e32 v14, 16, v16
	v_pk_fma_f32 v[0:1], v[96:97], v[14:15], v[0:1]
	v_rcp_f32_e32 v12, v12
	v_mul_f32_e32 v14, v1, v1
	v_fmaak_f32 v14, v240, v14, 0xc0135761
	v_mul_f32_e32 v15, v0, v0
	v_mul_f32_e32 v14, v1, v14
	v_fmaak_f32 v15, v240, v15, 0xc0135761
	v_mul_f32_e32 v15, v0, v15
	v_exp_f32_e32 v14, v14
	v_exp_f32_e32 v16, v15
	s_cmp_eq_u32 s24, 0
	v_add_f32_e32 v14, 1.0, v14
	v_rcp_f32_e32 v15, v14
	v_add_f32_e32 v14, 1.0, v16
	v_rcp_f32_e32 v14, v14
	s_cselect_b64 vcc, -1, 0
	v_pk_mul_f32 v[6:7], v[6:7], v[8:9]
	v_cndmask_b32_e64 v9, v123, 0, vcc
	v_cndmask_b32_e32 v8, v122, v154, vcc
	v_pk_mul_f32 v[2:3], v[2:3], v[12:13]
	v_pk_mul_f32 v[0:1], v[0:1], v[14:15]
	v_lshlrev_b64 v[8:9], 11, v[8:9]
	v_pk_mul_f32 v[4:5], v[4:5], v[10:11]
	v_lshl_add_u64 v[8:9], v[126:127], 0, v[8:9]
	v_cvt_pk_bf16_f32 v0, v0, v1
	v_cvt_pk_bf16_f32 v1, v2, v3
	v_cvt_pk_bf16_f32 v2, v4, v5
	v_cvt_pk_bf16_f32 v3, v6, v7
	global_store_dwordx2 v[8:9], v[0:1], off
	global_store_dwordx2 v[8:9], v[2:3], off offset:16
.LBB0_190:
	s_or_b64 exec, exec, s[2:3]
	s_add_i32 s67, s24, 4
	s_min_i32 s2, s67, s23
	s_nop 0
	v_sub_co_u32_e64 v0, vcc, s2, 1
	v_ashrrev_i32_e32 v1, 31, v0
	v_lshl_add_u64 v[0:1], v[0:1], 4, v[120:121]
	v_cndmask_b32_e64 v1, v1, 0, vcc
	v_cndmask_b32_e32 v0, v0, v154, vcc
	v_lshlrev_b64 v[0:1], 11, v[0:1]
	v_lshl_add_u64 v[0:1], v[184:185], 0, v[0:1]
	global_load_dwordx4 v[108:111], v[0:1], off
	s_add_i32 s52, s24, 1
	s_cmp_ge_i32 s52, s22
	s_cbranch_scc1 .LBB0_195
	s_waitcnt vmcnt(9)
	v_mfma_f32_32x32x16_bf16 v[16:31], v[104:107], v[132:135], 0
	v_mov_b32_e32 v32, v49
	v_mov_b32_e32 v33, v51
	v_mul_f32_e64 v32, v174, v32
	v_mul_f32_e64 v33, v175, v33
	ds_write_b128 v148, v[104:107] offset:8192
	v_sub_f32_e32 v32, v32, v33
	v_mov_b32_e32 v33, v49
	s_cmp_gt_i32 s24, -1
	s_nop 3
	v_add_f32_e32 v186, v32, v16
	v_mov_b32_e32 v32, v51
	v_pk_mul_f32 v[50:51], v[176:177], v[50:51] op_sel_hi:[1,0]
	v_pk_mul_f32 v[52:53], v[174:175], v[32:33]
	v_pk_fma_f32 v[188:189], v[172:173], v[48:49], v[50:51] neg_lo:[0,0,1] neg_hi:[0,0,1]
	v_pk_fma_f32 v[48:49], v[172:173], v[48:49], v[50:51] op_sel_hi:[1,0,1]
	v_mfma_f32_32x32x16_bf16 v[0:15], v[104:107], v[128:131], 0
	v_add_f32_e32 v16, v53, v52
	v_mov_b32_e32 v189, v49
	s_cselect_b64 s[2:3], -1, 0
	s_or_b64 s[14:15], s[2:3], s[50:51]
	v_mfma_f32_32x32x16_bf16 v[48:63], v[104:107], v[136:139], 0
	s_nop 6
	v_mov_b32_e32 v190, v0
	v_mfma_f32_32x32x16_bf16 v[32:47], v[104:107], v[140:143], 0
	s_nop 2
	v_mov_b32_e32 v191, v48
	v_add_f32_e64 v104, v188, v190
	v_add_f32_e64 v105, v189, v191
	v_mul_f32_e64 v106, v172, v104
	v_mul_f32_e64 v107, v173, v105
	v_sub_f32_e32 v0, v106, v107
	v_pk_mul_f32 v[106:107], v[176:177], v[104:105]
	s_nop 1
	v_add_f32_e32 v16, v16, v32
	v_add_f32_e32 v0, v1, v0
	v_add_f32_e32 v1, v106, v107
	v_add_f32_e32 v106, v49, v1
	v_pk_mul_f32 v[48:49], v[178:179], v[16:17] op_sel_hi:[1,0]
	v_mov_b32_e32 v32, v17
	v_pk_fma_f32 v[188:189], v[174:175], v[186:187], v[48:49] neg_lo:[0,0,1] neg_hi:[0,0,1]
	v_pk_fma_f32 v[48:49], v[174:175], v[186:187], v[48:49] op_sel_hi:[1,0,1]
	s_nop 0
	v_mov_b32_e32 v189, v49
	v_pk_add_f32 v[32:33], v[32:33], v[188:189]
	s_nop 0
	v_pk_mul_f32 v[48:49], v[174:175], v[32:33]
	s_nop 0
	v_sub_f32_e32 v1, v48, v49
	v_pk_mul_f32 v[48:49], v[178:179], v[32:33]
	v_add_f32_e32 v189, v18, v1
	v_add_f32_e32 v1, v48, v49
	v_pk_mul_f32 v[48:49], v[176:177], v[106:107] op_sel_hi:[1,0]
	v_add_f32_e32 v191, v34, v1
	v_pk_fma_f32 v[192:193], v[172:173], v[0:1], v[48:49] neg_lo:[0,0,1] neg_hi:[0,0,1]
	v_pk_fma_f32 v[48:49], v[172:173], v[0:1], v[48:49] op_sel_hi:[1,0,1]
	v_mul_f32_e32 v213, v174, v189
	v_mov_b32_e32 v193, v49
	v_mov_b32_e32 v48, v2
	v_mov_b32_e32 v49, v50
	v_pk_add_f32 v[192:193], v[48:49], v[192:193]
	v_mul_f32_e32 v215, v175, v191
	v_pk_mul_f32 v[48:49], v[172:173], v[192:193]
	v_mov_b32_e32 v18, v3
	v_mov_b32_e32 v212, v48
	v_mov_b32_e32 v214, v49
	v_pk_add_f32 v[48:49], v[212:213], v[214:215] neg_lo:[0,1] neg_hi:[0,1]
	v_mov_b32_e32 v190, v193
	v_pk_add_f32 v[2:3], v[18:19], v[48:49]
	v_pk_mul_f32 v[18:19], v[180:181], v[190:191]
	v_mov_b32_e32 v188, v192
	v_pk_fma_f32 v[18:19], v[182:183], v[188:189], v[18:19]
	v_mov_b32_e32 v34, v51
	v_pk_add_f32 v[18:19], v[34:35], v[18:19]
	v_mov_b32_e32 v48, v4
	v_pk_mul_f32 v[34:35], v[182:183], v[18:19]
	v_mov_b32_e32 v49, v20
	v_pk_fma_f32 v[34:35], v[180:181], v[2:3], v[34:35] neg_lo:[0,0,1] neg_hi:[0,0,1]
	v_mov_b32_e32 v50, v52
	v_pk_add_f32 v[34:35], v[48:49], v[34:35]
	v_pk_mul_f32 v[48:49], v[180:181], v[18:19]
	v_mov_b32_e32 v51, v36
	v_pk_fma_f32 v[48:49], v[182:183], v[2:3], v[48:49]
	v_mov_b32_e32 v20, v5
	v_pk_add_f32 v[212:213], v[50:51], v[48:49]
	v_mov_b32_e32 v36, v53
	v_pk_mul_f32 v[48:49], v[182:183], v[212:213]
	v_pk_mul_f32 v[50:51], v[180:181], v[212:213]
	v_pk_fma_f32 v[48:49], v[180:181], v[34:35], v[48:49] neg_lo:[0,0,1] neg_hi:[0,0,1]
	v_pk_fma_f32 v[50:51], v[182:183], v[34:35], v[50:51]
	v_pk_add_f32 v[4:5], v[20:21], v[48:49]
	v_pk_add_f32 v[20:21], v[36:37], v[50:51]
	v_mov_b32_e32 v48, v6
	v_pk_mul_f32 v[36:37], v[182:183], v[20:21]
	v_mov_b32_e32 v49, v22
	v_pk_fma_f32 v[36:37], v[180:181], v[4:5], v[36:37] neg_lo:[0,0,1] neg_hi:[0,0,1]
	v_mov_b32_e32 v50, v54
	v_pk_add_f32 v[36:37], v[48:49], v[36:37]
	v_pk_mul_f32 v[48:49], v[180:181], v[20:21]
	v_mov_b32_e32 v51, v38
	v_pk_fma_f32 v[48:49], v[182:183], v[4:5], v[48:49]
	v_mov_b32_e32 v22, v7
	v_pk_add_f32 v[52:53], v[50:51], v[48:49]
	v_mov_b32_e32 v38, v55
	v_pk_mul_f32 v[48:49], v[182:183], v[52:53]
	v_mov_b32_e32 v214, v8
	v_pk_fma_f32 v[48:49], v[180:181], v[36:37], v[48:49] neg_lo:[0,0,1] neg_hi:[0,0,1]
	v_mov_b32_e32 v215, v24
	v_pk_add_f32 v[6:7], v[22:23], v[48:49]
	v_pk_mul_f32 v[22:23], v[180:181], v[52:53]
	v_mov_b32_e32 v48, v56
	v_pk_fma_f32 v[22:23], v[182:183], v[36:37], v[22:23]
	v_mov_b32_e32 v49, v40
	v_pk_add_f32 v[22:23], v[38:39], v[22:23]
	v_mov_b32_e32 v24, v9
	v_pk_mul_f32 v[38:39], v[180:181], v[22:23]
	v_pk_mul_f32 v[54:55], v[182:183], v[22:23]
	v_pk_fma_f32 v[38:39], v[182:183], v[6:7], v[38:39]
	v_pk_fma_f32 v[54:55], v[180:181], v[6:7], v[54:55] neg_lo:[0,0,1] neg_hi:[0,0,1]
	v_pk_add_f32 v[38:39], v[48:49], v[38:39]
	v_pk_add_f32 v[54:55], v[214:215], v[54:55]
	v_pk_mul_f32 v[48:49], v[182:183], v[38:39]
	v_pk_mul_f32 v[50:51], v[180:181], v[38:39]
	v_pk_fma_f32 v[48:49], v[180:181], v[54:55], v[48:49] neg_lo:[0,0,1] neg_hi:[0,0,1]
	v_mov_b32_e32 v40, v57
	v_pk_add_f32 v[8:9], v[24:25], v[48:49]
	v_pk_fma_f32 v[24:25], v[182:183], v[54:55], v[50:51]
	v_mov_b32_e32 v48, v10
	v_pk_add_f32 v[24:25], v[40:41], v[24:25]
	v_mov_b32_e32 v49, v26
	v_pk_mul_f32 v[40:41], v[182:183], v[24:25]
	v_mov_b32_e32 v50, v58
	v_pk_fma_f32 v[40:41], v[180:181], v[8:9], v[40:41] neg_lo:[0,0,1] neg_hi:[0,0,1]
	v_mov_b32_e32 v51, v42
	v_pk_add_f32 v[40:41], v[48:49], v[40:41]
	v_pk_mul_f32 v[48:49], v[180:181], v[24:25]
	v_mov_b32_e32 v26, v11
	v_pk_fma_f32 v[48:49], v[182:183], v[8:9], v[48:49]
	v_mov_b32_e32 v42, v59
	v_pk_add_f32 v[56:57], v[50:51], v[48:49]
	v_mov_b32_e32 v50, v60
	v_pk_mul_f32 v[48:49], v[182:183], v[56:57]
	v_mov_b32_e32 v51, v44
	v_pk_fma_f32 v[48:49], v[180:181], v[40:41], v[48:49] neg_lo:[0,0,1] neg_hi:[0,0,1]
	v_mov_b32_e32 v44, v61
	v_pk_add_f32 v[10:11], v[26:27], v[48:49]
	v_pk_mul_f32 v[26:27], v[180:181], v[56:57]
	v_mov_b32_e32 v48, v12
	v_pk_fma_f32 v[26:27], v[182:183], v[40:41], v[26:27]
	v_mov_b32_e32 v49, v28
	v_pk_add_f32 v[26:27], v[42:43], v[26:27]
	v_mov_b32_e32 v28, v13
	v_pk_mul_f32 v[42:43], v[182:183], v[26:27]
	v_cvt_pk_bf16_f32 v0, v104, v0
	v_pk_fma_f32 v[42:43], v[180:181], v[10:11], v[42:43] neg_lo:[0,0,1] neg_hi:[0,0,1]
	v_cvt_pk_bf16_f32 v1, v192, v2
	v_pk_add_f32 v[42:43], v[48:49], v[42:43]
	v_pk_mul_f32 v[48:49], v[180:181], v[26:27]
	v_cvt_pk_bf16_f32 v2, v186, v32
	v_pk_fma_f32 v[48:49], v[182:183], v[10:11], v[48:49]
	v_cvt_pk_bf16_f32 v3, v189, v3
	v_pk_add_f32 v[58:59], v[50:51], v[48:49]
	v_mov_b32_e32 v50, v62
	v_pk_mul_f32 v[48:49], v[182:183], v[58:59]
	v_mov_b32_e32 v51, v46
	v_pk_fma_f32 v[48:49], v[180:181], v[42:43], v[48:49] neg_lo:[0,0,1] neg_hi:[0,0,1]
	v_mov_b32_e32 v46, v63
	v_pk_add_f32 v[12:13], v[28:29], v[48:49]
	v_pk_mul_f32 v[28:29], v[180:181], v[58:59]
	v_mov_b32_e32 v48, v14
	v_pk_fma_f32 v[28:29], v[182:183], v[42:43], v[28:29]
	v_mov_b32_e32 v49, v30
	v_pk_add_f32 v[28:29], v[44:45], v[28:29]
	v_mov_b32_e32 v30, v15
	v_pk_mul_f32 v[44:45], v[182:183], v[28:29]
	ds_write2st64_b64 v207, v[0:1], v[2:3] offset1:4
	v_pk_fma_f32 v[44:45], v[180:181], v[12:13], v[44:45] neg_lo:[0,0,1] neg_hi:[0,0,1]
	v_cvt_pk_bf16_f32 v0, v35, v5
	v_pk_add_f32 v[44:45], v[48:49], v[44:45]
	v_pk_mul_f32 v[48:49], v[180:181], v[28:29]
	v_cvt_pk_bf16_f32 v1, v37, v7
	v_pk_fma_f32 v[48:49], v[182:183], v[12:13], v[48:49]
	v_pk_mov_b32 v[2:3], v[192:193], v[18:19] op_sel:[1,0]
	v_pk_add_f32 v[60:61], v[50:51], v[48:49]
	v_cvt_pk_bf16_f32 v5, v56, v26
	v_pk_mul_f32 v[14:15], v[180:181], v[60:61]
	v_pk_mul_f32 v[48:49], v[182:183], v[60:61]
	v_pk_fma_f32 v[14:15], v[182:183], v[44:45], v[14:15]
	v_pk_fma_f32 v[48:49], v[180:181], v[44:45], v[48:49] neg_lo:[0,0,1] neg_hi:[0,0,1]
	v_pk_add_f32 v[50:51], v[46:47], v[14:15]
	v_cvt_pk_bf16_f32 v14, v34, v4
	v_cvt_pk_bf16_f32 v15, v36, v6
	v_pk_add_f32 v[48:49], v[30:31], v[48:49]
	v_cvt_pk_bf16_f32 v30, v54, v8
	v_cvt_pk_bf16_f32 v31, v40, v10
	ds_write2st64_b64 v208, v[14:15], v[0:1] offset1:4
	v_cvt_pk_bf16_f32 v0, v55, v9
	v_cvt_pk_bf16_f32 v1, v41, v11
	v_cvt_pk_bf16_f32 v46, v42, v12
	v_cvt_pk_bf16_f32 v47, v44, v48
	ds_write2st64_b64 v209, v[30:31], v[0:1] offset1:4
	v_cvt_pk_bf16_f32 v0, v43, v13
	v_cvt_pk_bf16_f32 v1, v45, v49
	ds_write2st64_b64 v210, v[46:47], v[0:1] offset1:4
	v_cvt_pk_bf16_f32 v0, v105, v106
	v_cvt_pk_bf16_f32 v1, v2, v3
	v_cvt_pk_bf16_f32 v8, v16, v33
	v_cvt_pk_bf16_f32 v9, v191, v19
	v_cvt_pk_bf16_f32 v2, v212, v20
	v_cvt_pk_bf16_f32 v3, v52, v22
	ds_write2st64_b64 v207, v[0:1], v[8:9] offset0:8 offset1:12
	v_cvt_pk_bf16_f32 v0, v213, v21
	v_cvt_pk_bf16_f32 v1, v53, v23
	v_cvt_pk_bf16_f32 v4, v38, v24
	ds_write2st64_b64 v208, v[2:3], v[0:1] offset0:8 offset1:12
	v_cvt_pk_bf16_f32 v0, v39, v25
	v_cvt_pk_bf16_f32 v1, v57, v27
	v_cvt_pk_bf16_f32 v6, v58, v28
	v_cvt_pk_bf16_f32 v7, v60, v50
	ds_write2st64_b64 v209, v[4:5], v[0:1] offset0:8 offset1:12
	v_cvt_pk_bf16_f32 v0, v59, v29
	v_cvt_pk_bf16_f32 v1, v61, v51
	ds_write2st64_b64 v210, v[6:7], v[0:1] offset0:8 offset1:12
	s_waitcnt lgkmcnt(0)
	ds_read_b64_tr_b16 v[0:1], v151 offset:0
	ds_read_b64_tr_b16 v[2:3], v199 offset:0
	ds_read_b64_tr_b16 v[28:29], v151 offset:1024
	ds_read_b64_tr_b16 v[30:31], v199 offset:1024
	ds_read_b64_tr_b16 v[24:25], v151 offset:2048
	ds_read_b64_tr_b16 v[26:27], v199 offset:2048
	ds_read_b64_tr_b16 v[20:21], v151 offset:3072
	ds_read_b64_tr_b16 v[22:23], v199 offset:3072
	ds_read_b64_tr_b16 v[16:17], v151 offset:4096
	ds_read_b64_tr_b16 v[18:19], v199 offset:4096
	ds_read_b64_tr_b16 v[44:45], v151 offset:5120
	ds_read_b64_tr_b16 v[46:47], v199 offset:5120
	ds_read_b64_tr_b16 v[40:41], v151 offset:6144
	ds_read_b64_tr_b16 v[42:43], v199 offset:6144
	ds_read_b64_tr_b16 v[52:53], v151 offset:7168
	ds_read_b64_tr_b16 v[54:55], v199 offset:7168
	s_waitcnt lgkmcnt(0)
	s_nop 0
	v_mfma_f32_32x32x16_bf16 v[0:15], v[68:71], v[0:3], 0
	v_mfma_f32_32x32x16_bf16 v[0:15], v[64:67], v[28:31], v[0:15]
	v_mfma_f32_32x32x16_bf16 v[0:15], v[76:79], v[24:27], v[0:15]
	v_mfma_f32_32x32x16_bf16 v[0:15], v[72:75], v[20:23], v[0:15]
	v_mfma_f32_32x32x16_bf16 v[0:15], v[84:87], v[16:19], v[0:15]
	v_mfma_f32_32x32x16_bf16 v[0:15], v[80:83], v[44:47], v[0:15]
	v_mfma_f32_32x32x16_bf16 v[0:15], v[92:95], v[40:43], v[0:15]
	v_mfma_f32_32x32x16_bf16 v[0:15], v[88:91], v[52:55], v[0:15]
	s_and_saveexec_b64 s[2:3], s[14:15]
	s_cbranch_execz .LBB0_193
	s_nop 7
	v_add_u32_e32 v16, v200, v146
	v_add_u32_e32 v16, 0x2000, v16
	ds_read2_b64 v[16:19], v16 offset1:2
	s_waitcnt lgkmcnt(0)
	v_lshlrev_b32_e32 v10, 16, v19
	v_and_b32_e32 v11, 0xffff0000, v19
	v_pk_fma_f32 v[6:7], v[102:103], v[10:11], v[6:7]
	v_mul_f32_e32 v10, v7, v7
	v_fmaak_f32 v10, v240, v10, 0xc0135761
	v_mul_f32_e32 v11, v6, v6
	v_mul_f32_e32 v10, v7, v10
	v_fmaak_f32 v11, v240, v11, 0xc0135761
	v_mul_f32_e32 v11, v6, v11
	v_exp_f32_e32 v10, v10
	v_exp_f32_e32 v11, v11
	v_add_f32_e32 v8, 1.0, v10
	v_rcp_f32_e32 v9, v8
	v_add_f32_e32 v8, 1.0, v11
	v_lshlrev_b32_e32 v10, 16, v18
	v_and_b32_e32 v11, 0xffff0000, v18
	v_pk_fma_f32 v[4:5], v[100:101], v[10:11], v[4:5]
	v_and_b32_e32 v13, 0xffff0000, v17
	v_mul_f32_e32 v10, v5, v5
	v_fmaak_f32 v10, v240, v10, 0xc0135761
	v_mul_f32_e32 v11, v4, v4
	v_mul_f32_e32 v10, v5, v10
	v_fmaak_f32 v11, v240, v11, 0xc0135761
	v_mul_f32_e32 v11, v4, v11
	v_exp_f32_e32 v10, v10
	v_exp_f32_e32 v12, v11
	v_and_b32_e32 v15, 0xffff0000, v16
	v_add_f32_e32 v10, 1.0, v10
	v_rcp_f32_e32 v11, v10
	v_add_f32_e32 v10, 1.0, v12
	v_lshlrev_b32_e32 v12, 16, v17
	v_pk_fma_f32 v[2:3], v[98:99], v[12:13], v[2:3]
	v_rcp_f32_e32 v8, v8
	v_mul_f32_e32 v12, v3, v3
	v_fmaak_f32 v12, v240, v12, 0xc0135761
	v_mul_f32_e32 v13, v2, v2
	v_mul_f32_e32 v12, v3, v12
	v_fmaak_f32 v13, v240, v13, 0xc0135761
	v_mul_f32_e32 v13, v2, v13
	v_exp_f32_e32 v12, v12
	v_exp_f32_e32 v14, v13
	v_rcp_f32_e32 v10, v10
	v_add_f32_e32 v12, 1.0, v12
	v_rcp_f32_e32 v13, v12
	v_add_f32_e32 v12, 1.0, v14
	v_lshlrev_b32_e32 v14, 16, v16
	v_pk_fma_f32 v[0:1], v[96:97], v[14:15], v[0:1]
	v_rcp_f32_e32 v12, v12
	v_mul_f32_e32 v14, v1, v1
	v_fmaak_f32 v14, v240, v14, 0xc0135761
	v_mul_f32_e32 v15, v0, v0
	v_mul_f32_e32 v14, v1, v14
	v_fmaak_f32 v15, v240, v15, 0xc0135761
	v_mul_f32_e32 v15, v0, v15
	v_exp_f32_e32 v14, v14
	v_exp_f32_e32 v16, v15
	s_cmp_eq_u32 s24, -1
	v_add_f32_e32 v14, 1.0, v14
	v_rcp_f32_e32 v15, v14
	v_add_f32_e32 v14, 1.0, v16
	v_rcp_f32_e32 v14, v14
	s_cselect_b64 vcc, -1, 0
	v_pk_mul_f32 v[6:7], v[6:7], v[8:9]
	v_cndmask_b32_e64 v9, v125, 0, vcc
	v_cndmask_b32_e32 v8, v124, v154, vcc
	v_pk_mul_f32 v[2:3], v[2:3], v[12:13]
	v_pk_mul_f32 v[0:1], v[0:1], v[14:15]
	v_lshlrev_b64 v[8:9], 11, v[8:9]
	v_pk_mul_f32 v[4:5], v[4:5], v[10:11]
	v_lshl_add_u64 v[8:9], v[126:127], 0, v[8:9]
	v_cvt_pk_bf16_f32 v0, v0, v1
	v_cvt_pk_bf16_f32 v1, v2, v3
	v_cvt_pk_bf16_f32 v2, v4, v5
	v_cvt_pk_bf16_f32 v3, v6, v7
	global_store_dwordx2 v[8:9], v[0:1], off
	global_store_dwordx2 v[8:9], v[2:3], off offset:16

.LBB0_196:
	s_waitcnt vmcnt(9)
	v_mfma_f32_32x32x16_bf16 v[16:31], v[116:119], v[132:135], 0
	v_mov_b32_e32 v32, v49
	v_mov_b32_e32 v33, v51
	v_mul_f32_e64 v32, v174, v32
	v_mul_f32_e64 v33, v175, v33
	ds_write_b128 v148, v[116:119] offset:8192
	v_sub_f32_e32 v32, v32, v33
	v_mov_b32_e32 v33, v49
	s_cmp_gt_i32 s24, -2
	s_nop 3
	v_add_f32_e32 v186, v32, v16
	v_mov_b32_e32 v32, v51
	v_pk_mul_f32 v[50:51], v[176:177], v[50:51] op_sel_hi:[1,0]
	v_pk_mul_f32 v[52:53], v[174:175], v[32:33]
	v_pk_fma_f32 v[188:189], v[172:173], v[48:49], v[50:51] neg_lo:[0,0,1] neg_hi:[0,0,1]
	v_pk_fma_f32 v[48:49], v[172:173], v[48:49], v[50:51] op_sel_hi:[1,0,1]
	v_mfma_f32_32x32x16_bf16 v[0:15], v[116:119], v[128:131], 0
	v_add_f32_e32 v16, v52, v53
	v_mov_b32_e32 v189, v49
	s_cselect_b64 s[2:3], -1, 0
	s_or_b64 s[68:69], s[2:3], s[50:51]
	v_mfma_f32_32x32x16_bf16 v[48:63], v[116:119], v[136:139], 0
	s_nop 6
	v_mov_b32_e32 v190, v0
	v_mfma_f32_32x32x16_bf16 v[32:47], v[116:119], v[140:143], 0
	s_nop 2
	v_mov_b32_e32 v191, v48
	v_add_f32_e64 v116, v188, v190
	v_add_f32_e64 v117, v189, v191
	v_mul_f32_e64 v118, v172, v116
	v_mul_f32_e64 v119, v173, v117
	v_sub_f32_e32 v0, v118, v119
	v_pk_mul_f32 v[118:119], v[176:177], v[116:117]
	s_nop 1
	v_add_f32_e32 v16, v16, v32
	v_add_f32_e32 v0, v1, v0
	v_add_f32_e32 v1, v118, v119
	v_add_f32_e32 v118, v49, v1
	v_pk_mul_f32 v[48:49], v[178:179], v[16:17] op_sel_hi:[1,0]
	v_mov_b32_e32 v32, v17
	v_pk_fma_f32 v[188:189], v[174:175], v[186:187], v[48:49] neg_lo:[0,0,1] neg_hi:[0,0,1]
	v_pk_fma_f32 v[48:49], v[174:175], v[186:187], v[48:49] op_sel_hi:[1,0,1]
	s_nop 0
	v_mov_b32_e32 v189, v49
	v_pk_add_f32 v[32:33], v[32:33], v[188:189]
	s_nop 0
	v_pk_mul_f32 v[48:49], v[174:175], v[32:33]
	s_nop 0
	v_sub_f32_e32 v1, v48, v49
	v_pk_mul_f32 v[48:49], v[178:179], v[32:33]
	v_add_f32_e32 v189, v18, v1
	v_add_f32_e32 v1, v48, v49
	v_pk_mul_f32 v[48:49], v[176:177], v[118:119] op_sel_hi:[1,0]
	v_add_f32_e32 v191, v34, v1
	v_pk_fma_f32 v[192:193], v[172:173], v[0:1], v[48:49] neg_lo:[0,0,1] neg_hi:[0,0,1]
	v_pk_fma_f32 v[48:49], v[172:173], v[0:1], v[48:49] op_sel_hi:[1,0,1]
	v_mul_f32_e32 v213, v174, v189
	v_mov_b32_e32 v193, v49
	v_mov_b32_e32 v48, v2
	v_mov_b32_e32 v49, v50
	v_pk_add_f32 v[192:193], v[48:49], v[192:193]
	v_mul_f32_e32 v215, v175, v191
	v_pk_mul_f32 v[48:49], v[172:173], v[192:193]
	v_mov_b32_e32 v18, v3
	v_mov_b32_e32 v212, v48
	v_mov_b32_e32 v214, v49
	v_pk_add_f32 v[48:49], v[212:213], v[214:215] neg_lo:[0,1] neg_hi:[0,1]
	v_mov_b32_e32 v190, v193
	v_pk_add_f32 v[2:3], v[18:19], v[48:49]
	v_pk_mul_f32 v[18:19], v[180:181], v[190:191]
	v_mov_b32_e32 v188, v192
	v_pk_fma_f32 v[18:19], v[182:183], v[188:189], v[18:19]
	v_mov_b32_e32 v34, v51
	v_pk_add_f32 v[18:19], v[34:35], v[18:19]
	v_mov_b32_e32 v48, v52
	v_pk_mul_f32 v[34:35], v[180:181], v[18:19]
	v_mov_b32_e32 v49, v36
	v_pk_fma_f32 v[34:35], v[182:183], v[2:3], v[34:35]
	v_pk_mul_f32 v[212:213], v[182:183], v[18:19]
	v_pk_add_f32 v[34:35], v[48:49], v[34:35]
	v_pk_fma_f32 v[212:213], v[180:181], v[2:3], v[212:213] neg_lo:[0,0,1] neg_hi:[0,0,1]
	v_mov_b32_e32 v214, v4
	v_mov_b32_e32 v215, v20
	v_pk_mul_f32 v[48:49], v[182:183], v[34:35]
	v_pk_add_f32 v[212:213], v[214:215], v[212:213]
	v_pk_mul_f32 v[50:51], v[180:181], v[34:35]
	v_pk_fma_f32 v[48:49], v[180:181], v[212:213], v[48:49] neg_lo:[0,0,1] neg_hi:[0,0,1]
	v_mov_b32_e32 v20, v5
	v_pk_add_f32 v[4:5], v[20:21], v[48:49]
	v_pk_fma_f32 v[20:21], v[182:183], v[212:213], v[50:51]
	v_mov_b32_e32 v36, v53
	v_pk_add_f32 v[20:21], v[36:37], v[20:21]
	v_mov_b32_e32 v48, v6
	v_pk_mul_f32 v[36:37], v[182:183], v[20:21]
	v_mov_b32_e32 v49, v22
	v_pk_fma_f32 v[36:37], v[180:181], v[4:5], v[36:37] neg_lo:[0,0,1] neg_hi:[0,0,1]
	v_mov_b32_e32 v50, v54
	v_pk_add_f32 v[36:37], v[48:49], v[36:37]
	v_pk_mul_f32 v[48:49], v[180:181], v[20:21]
	v_mov_b32_e32 v51, v38
	v_pk_fma_f32 v[48:49], v[182:183], v[4:5], v[48:49]
	v_mov_b32_e32 v22, v7
	v_pk_add_f32 v[52:53], v[50:51], v[48:49]
	v_mov_b32_e32 v38, v55
	v_pk_mul_f32 v[48:49], v[182:183], v[52:53]
	v_mov_b32_e32 v50, v56
	v_pk_fma_f32 v[48:49], v[180:181], v[36:37], v[48:49] neg_lo:[0,0,1] neg_hi:[0,0,1]
	v_mov_b32_e32 v51, v40
	v_pk_add_f32 v[6:7], v[22:23], v[48:49]
	v_pk_mul_f32 v[22:23], v[180:181], v[52:53]
	v_mov_b32_e32 v48, v8
	v_pk_fma_f32 v[22:23], v[182:183], v[36:37], v[22:23]
	v_mov_b32_e32 v49, v24
	v_pk_add_f32 v[22:23], v[38:39], v[22:23]
	v_mov_b32_e32 v24, v9
	v_pk_mul_f32 v[38:39], v[182:183], v[22:23]
	v_mov_b32_e32 v40, v57
	v_pk_fma_f32 v[38:39], v[180:181], v[6:7], v[38:39] neg_lo:[0,0,1] neg_hi:[0,0,1]
	v_cvt_pk_bf16_f32 v0, v116, v0
	v_pk_add_f32 v[38:39], v[48:49], v[38:39]
	v_pk_mul_f32 v[48:49], v[180:181], v[22:23]
	v_cvt_pk_bf16_f32 v1, v192, v2
	v_pk_fma_f32 v[48:49], v[182:183], v[6:7], v[48:49]
	v_cvt_pk_bf16_f32 v2, v186, v32
	v_pk_add_f32 v[54:55], v[50:51], v[48:49]
	v_mov_b32_e32 v50, v58
	v_pk_mul_f32 v[48:49], v[182:183], v[54:55]
	v_mov_b32_e32 v51, v42
	v_pk_fma_f32 v[48:49], v[180:181], v[38:39], v[48:49] neg_lo:[0,0,1] neg_hi:[0,0,1]
	v_mov_b32_e32 v42, v59
	v_pk_add_f32 v[8:9], v[24:25], v[48:49]
	v_pk_mul_f32 v[24:25], v[180:181], v[54:55]
	v_mov_b32_e32 v48, v10
	v_pk_fma_f32 v[24:25], v[182:183], v[38:39], v[24:25]
	v_mov_b32_e32 v49, v26
	v_pk_add_f32 v[24:25], v[40:41], v[24:25]
	v_mov_b32_e32 v26, v11
	v_pk_mul_f32 v[40:41], v[182:183], v[24:25]
	v_cvt_pk_bf16_f32 v3, v189, v3
	v_pk_fma_f32 v[40:41], v[180:181], v[8:9], v[40:41] neg_lo:[0,0,1] neg_hi:[0,0,1]
	ds_write2st64_b64 v207, v[0:1], v[2:3] offset1:4
	v_pk_add_f32 v[40:41], v[48:49], v[40:41]
	v_pk_mul_f32 v[48:49], v[180:181], v[24:25]
	v_cvt_pk_bf16_f32 v0, v213, v5
	v_pk_fma_f32 v[48:49], v[182:183], v[8:9], v[48:49]
	v_cvt_pk_bf16_f32 v1, v37, v7
	v_pk_add_f32 v[56:57], v[50:51], v[48:49]
	v_mov_b32_e32 v50, v12
	v_pk_mul_f32 v[48:49], v[182:183], v[56:57]
	v_mov_b32_e32 v51, v28
	v_pk_fma_f32 v[48:49], v[180:181], v[40:41], v[48:49] neg_lo:[0,0,1] neg_hi:[0,0,1]
	v_mov_b32_e32 v28, v13
	v_pk_add_f32 v[10:11], v[26:27], v[48:49]
	v_pk_mul_f32 v[26:27], v[180:181], v[56:57]
	v_pk_mov_b32 v[2:3], v[192:193], v[18:19] op_sel:[1,0]
	v_pk_fma_f32 v[26:27], v[182:183], v[40:41], v[26:27]
	s_nop 0
	v_pk_add_f32 v[26:27], v[42:43], v[26:27]
	s_nop 0
	v_pk_mul_f32 v[42:43], v[182:183], v[26:27]
	v_pk_mul_f32 v[48:49], v[180:181], v[26:27]
	v_pk_fma_f32 v[42:43], v[180:181], v[10:11], v[42:43] neg_lo:[0,0,1] neg_hi:[0,0,1]
	v_pk_fma_f32 v[48:49], v[182:183], v[10:11], v[48:49]
	v_pk_add_f32 v[42:43], v[50:51], v[42:43]
	v_mov_b32_e32 v50, v60
	v_mov_b32_e32 v51, v44
	v_pk_add_f32 v[58:59], v[50:51], v[48:49]
	v_mov_b32_e32 v44, v61
	v_pk_mul_f32 v[48:49], v[182:183], v[58:59]
	v_mov_b32_e32 v50, v62
	v_pk_fma_f32 v[48:49], v[180:181], v[42:43], v[48:49] neg_lo:[0,0,1] neg_hi:[0,0,1]
	v_mov_b32_e32 v51, v46
	v_pk_add_f32 v[12:13], v[28:29], v[48:49]
	v_pk_mul_f32 v[28:29], v[180:181], v[58:59]
	v_mov_b32_e32 v48, v14
	v_pk_fma_f32 v[28:29], v[182:183], v[42:43], v[28:29]
	v_mov_b32_e32 v49, v30
	v_pk_add_f32 v[28:29], v[44:45], v[28:29]
	v_mov_b32_e32 v30, v15
	v_pk_mul_f32 v[44:45], v[182:183], v[28:29]
	v_mov_b32_e32 v46, v63
	v_pk_fma_f32 v[44:45], v[180:181], v[12:13], v[44:45] neg_lo:[0,0,1] neg_hi:[0,0,1]
	v_cvt_pk_bf16_f32 v5, v56, v26
	v_pk_add_f32 v[44:45], v[48:49], v[44:45]
	v_pk_mul_f32 v[48:49], v[180:181], v[28:29]
	s_nop 0
	v_pk_fma_f32 v[48:49], v[182:183], v[12:13], v[48:49]
	s_nop 0
	v_pk_add_f32 v[60:61], v[50:51], v[48:49]
	s_nop 0
	v_pk_mul_f32 v[14:15], v[180:181], v[60:61]
	v_pk_mul_f32 v[48:49], v[182:183], v[60:61]
	v_pk_fma_f32 v[14:15], v[182:183], v[44:45], v[14:15]
	v_pk_fma_f32 v[48:49], v[180:181], v[44:45], v[48:49] neg_lo:[0,0,1] neg_hi:[0,0,1]
	v_pk_add_f32 v[50:51], v[46:47], v[14:15]
	v_cvt_pk_bf16_f32 v14, v212, v4
	v_cvt_pk_bf16_f32 v15, v36, v6
	v_pk_add_f32 v[48:49], v[30:31], v[48:49]
	v_cvt_pk_bf16_f32 v30, v38, v8
	v_cvt_pk_bf16_f32 v31, v40, v10
	ds_write2st64_b64 v208, v[14:15], v[0:1] offset1:4
	v_cvt_pk_bf16_f32 v0, v39, v9
	v_cvt_pk_bf16_f32 v1, v41, v11
	v_cvt_pk_bf16_f32 v46, v42, v12
	v_cvt_pk_bf16_f32 v47, v44, v48
	ds_write2st64_b64 v209, v[30:31], v[0:1] offset1:4
	v_cvt_pk_bf16_f32 v0, v43, v13
	v_cvt_pk_bf16_f32 v1, v45, v49
	ds_write2st64_b64 v210, v[46:47], v[0:1] offset1:4
	v_cvt_pk_bf16_f32 v0, v117, v118
	v_cvt_pk_bf16_f32 v1, v2, v3
	v_cvt_pk_bf16_f32 v8, v16, v33
	v_cvt_pk_bf16_f32 v9, v191, v19
	v_cvt_pk_bf16_f32 v2, v34, v20
	v_cvt_pk_bf16_f32 v3, v52, v22
	ds_write2st64_b64 v207, v[0:1], v[8:9] offset0:8 offset1:12
	v_cvt_pk_bf16_f32 v0, v35, v21
	v_cvt_pk_bf16_f32 v1, v53, v23
	v_cvt_pk_bf16_f32 v4, v54, v24
	ds_write2st64_b64 v208, v[2:3], v[0:1] offset0:8 offset1:12
	v_cvt_pk_bf16_f32 v0, v55, v25
	v_cvt_pk_bf16_f32 v1, v57, v27
	v_cvt_pk_bf16_f32 v6, v58, v28
	v_cvt_pk_bf16_f32 v7, v60, v50
	ds_write2st64_b64 v209, v[4:5], v[0:1] offset0:8 offset1:12
	v_cvt_pk_bf16_f32 v0, v59, v29
	v_cvt_pk_bf16_f32 v1, v61, v51
	ds_write2st64_b64 v210, v[6:7], v[0:1] offset0:8 offset1:12
	s_waitcnt lgkmcnt(0)
	ds_read_b64_tr_b16 v[0:1], v151 offset:0
	ds_read_b64_tr_b16 v[2:3], v199 offset:0
	ds_read_b64_tr_b16 v[28:29], v151 offset:1024
	ds_read_b64_tr_b16 v[30:31], v199 offset:1024
	ds_read_b64_tr_b16 v[24:25], v151 offset:2048
	ds_read_b64_tr_b16 v[26:27], v199 offset:2048
	ds_read_b64_tr_b16 v[20:21], v151 offset:3072
	ds_read_b64_tr_b16 v[22:23], v199 offset:3072
	ds_read_b64_tr_b16 v[16:17], v151 offset:4096
	ds_read_b64_tr_b16 v[18:19], v199 offset:4096
	ds_read_b64_tr_b16 v[44:45], v151 offset:5120
	ds_read_b64_tr_b16 v[46:47], v199 offset:5120
	ds_read_b64_tr_b16 v[40:41], v151 offset:6144
	ds_read_b64_tr_b16 v[42:43], v199 offset:6144
	ds_read_b64_tr_b16 v[52:53], v151 offset:7168
	ds_read_b64_tr_b16 v[54:55], v199 offset:7168
	s_waitcnt lgkmcnt(0)
	s_nop 0
	v_mfma_f32_32x32x16_bf16 v[0:15], v[68:71], v[0:3], 0
	v_mfma_f32_32x32x16_bf16 v[0:15], v[64:67], v[28:31], v[0:15]
	v_mfma_f32_32x32x16_bf16 v[0:15], v[76:79], v[24:27], v[0:15]
	v_mfma_f32_32x32x16_bf16 v[0:15], v[72:75], v[20:23], v[0:15]
	v_mfma_f32_32x32x16_bf16 v[0:15], v[84:87], v[16:19], v[0:15]
	v_mfma_f32_32x32x16_bf16 v[0:15], v[80:83], v[44:47], v[0:15]
	v_mfma_f32_32x32x16_bf16 v[0:15], v[92:95], v[40:43], v[0:15]
	v_mfma_f32_32x32x16_bf16 v[0:15], v[88:91], v[52:55], v[0:15]
	s_and_saveexec_b64 s[2:3], s[68:69]
	s_cbranch_execz .LBB0_198
	s_nop 7
	v_add_u32_e32 v16, v200, v146
	v_add_u32_e32 v16, 0x2000, v16
	ds_read2_b64 v[16:19], v16 offset1:2
	s_waitcnt lgkmcnt(0)
	v_lshlrev_b32_e32 v10, 16, v19
	v_and_b32_e32 v11, 0xffff0000, v19
	v_pk_fma_f32 v[6:7], v[102:103], v[10:11], v[6:7]
	v_mul_f32_e32 v10, v7, v7
	v_fmaak_f32 v10, v240, v10, 0xc0135761
	v_mul_f32_e32 v11, v6, v6
	v_mul_f32_e32 v10, v7, v10
	v_fmaak_f32 v11, v240, v11, 0xc0135761
	v_mul_f32_e32 v11, v6, v11
	v_exp_f32_e32 v10, v10
	v_exp_f32_e32 v11, v11
	v_add_f32_e32 v8, 1.0, v10
	v_rcp_f32_e32 v9, v8
	v_add_f32_e32 v8, 1.0, v11
	v_lshlrev_b32_e32 v10, 16, v18
	v_and_b32_e32 v11, 0xffff0000, v18
	v_pk_fma_f32 v[4:5], v[100:101], v[10:11], v[4:5]
	v_and_b32_e32 v13, 0xffff0000, v17
	v_mul_f32_e32 v10, v5, v5
	v_fmaak_f32 v10, v240, v10, 0xc0135761
	v_mul_f32_e32 v11, v4, v4
	v_mul_f32_e32 v10, v5, v10
	v_fmaak_f32 v11, v240, v11, 0xc0135761
	v_mul_f32_e32 v11, v4, v11
	v_exp_f32_e32 v10, v10
	v_exp_f32_e32 v12, v11
	v_and_b32_e32 v15, 0xffff0000, v16
	v_add_f32_e32 v10, 1.0, v10
	v_rcp_f32_e32 v11, v10
	v_add_f32_e32 v10, 1.0, v12
	v_lshlrev_b32_e32 v12, 16, v17
	v_pk_fma_f32 v[2:3], v[98:99], v[12:13], v[2:3]
	v_rcp_f32_e32 v8, v8
	v_mul_f32_e32 v12, v3, v3
	v_fmaak_f32 v12, v240, v12, 0xc0135761
	v_mul_f32_e32 v13, v2, v2
	v_mul_f32_e32 v12, v3, v12
	v_fmaak_f32 v13, v240, v13, 0xc0135761
	v_mul_f32_e32 v13, v2, v13
	v_exp_f32_e32 v12, v12
	v_exp_f32_e32 v14, v13
	s_cmp_eq_u32 s24, -2
	v_add_f32_e32 v12, 1.0, v12
	v_rcp_f32_e32 v13, v12
	v_add_f32_e32 v12, 1.0, v14
	v_lshlrev_b32_e32 v14, 16, v16
	v_pk_fma_f32 v[0:1], v[96:97], v[14:15], v[0:1]
	v_rcp_f32_e32 v12, v12
	v_mul_f32_e32 v14, v1, v1
	v_fmaak_f32 v14, v240, v14, 0xc0135761
	v_mul_f32_e32 v15, v0, v0
	v_mul_f32_e32 v14, v1, v14
	v_fmaak_f32 v15, v240, v15, 0xc0135761
	v_mul_f32_e32 v15, v0, v15
	v_exp_f32_e32 v14, v14
	v_exp_f32_e32 v16, v15
	v_rcp_f32_e32 v10, v10
	v_add_f32_e32 v14, 1.0, v14
	v_rcp_f32_e32 v15, v14
	v_add_f32_e32 v14, 1.0, v16
	v_rcp_f32_e32 v14, v14
	s_cselect_b64 vcc, -1, 0
	s_ashr_i32 s53, s52, 31
	v_pk_mul_f32 v[6:7], v[6:7], v[8:9]
	v_lshl_add_u64 v[8:9], s[52:53], 4, v[120:121]
	v_cndmask_b32_e64 v9, v9, 0, vcc
	v_cndmask_b32_e32 v8, v8, v154, vcc
	v_pk_mul_f32 v[2:3], v[2:3], v[12:13]
	v_pk_mul_f32 v[0:1], v[0:1], v[14:15]
	v_lshlrev_b64 v[8:9], 11, v[8:9]
	v_pk_mul_f32 v[4:5], v[4:5], v[10:11]
	v_lshl_add_u64 v[8:9], v[126:127], 0, v[8:9]
	v_cvt_pk_bf16_f32 v0, v0, v1
	v_cvt_pk_bf16_f32 v1, v2, v3
	v_cvt_pk_bf16_f32 v2, v4, v5
	v_cvt_pk_bf16_f32 v3, v6, v7
	global_store_dwordx2 v[8:9], v[0:1], off
	global_store_dwordx2 v[8:9], v[2:3], off offset:16

.LBB0_199:
	s_waitcnt vmcnt(9)
	v_mfma_f32_32x32x16_bf16 v[16:31], v[112:115], v[132:135], 0
	v_mov_b32_e32 v32, v49
	v_mov_b32_e32 v33, v51
	v_mul_f32_e64 v32, v174, v32
	v_mul_f32_e64 v33, v175, v33
	ds_write_b128 v148, v[112:115] offset:8192
	v_sub_f32_e32 v32, v32, v33
	v_mov_b32_e32 v33, v49
	s_cmp_gt_i32 s24, -3
	s_nop 3
	v_add_f32_e32 v148, v32, v16
	v_mov_b32_e32 v32, v51
	v_pk_mul_f32 v[50:51], v[176:177], v[50:51] op_sel_hi:[1,0]
	v_pk_mul_f32 v[52:53], v[174:175], v[32:33]
	v_pk_fma_f32 v[186:187], v[172:173], v[48:49], v[50:51] neg_lo:[0,0,1] neg_hi:[0,0,1]
	v_pk_fma_f32 v[48:49], v[172:173], v[48:49], v[50:51] op_sel_hi:[1,0,1]
	v_mfma_f32_32x32x16_bf16 v[0:15], v[112:115], v[128:131], 0
	v_add_f32_e32 v16, v52, v53
	v_mov_b32_e32 v187, v49
	s_cselect_b64 s[2:3], -1, 0
	s_or_b64 s[52:53], s[2:3], s[50:51]
	v_mfma_f32_32x32x16_bf16 v[48:63], v[112:115], v[136:139], 0
	s_nop 6
	v_mov_b32_e32 v188, v0
	v_mfma_f32_32x32x16_bf16 v[32:47], v[112:115], v[140:143], 0
	s_nop 2
	v_mov_b32_e32 v189, v48
	v_add_f32_e64 v112, v186, v188
	v_add_f32_e64 v113, v187, v189
	v_mul_f32_e64 v114, v172, v112
	v_mul_f32_e64 v115, v173, v113
	v_sub_f32_e32 v0, v114, v115
	v_pk_mul_f32 v[114:115], v[176:177], v[112:113]
	s_nop 1
	v_add_f32_e32 v16, v16, v32
	v_add_f32_e32 v0, v1, v0
	v_add_f32_e32 v1, v114, v115
	v_add_f32_e32 v114, v49, v1
	v_pk_mul_f32 v[48:49], v[178:179], v[16:17] op_sel_hi:[1,0]
	v_mov_b32_e32 v32, v17
	v_pk_fma_f32 v[186:187], v[174:175], v[148:149], v[48:49] neg_lo:[0,0,1] neg_hi:[0,0,1]
	v_pk_fma_f32 v[48:49], v[174:175], v[148:149], v[48:49] op_sel_hi:[1,0,1]
	s_nop 0
	v_mov_b32_e32 v187, v49
	v_pk_add_f32 v[32:33], v[32:33], v[186:187]
	s_nop 0
	v_pk_mul_f32 v[48:49], v[174:175], v[32:33]
	s_nop 0
	v_sub_f32_e32 v1, v48, v49
	v_pk_mul_f32 v[48:49], v[178:179], v[32:33]
	v_add_f32_e32 v187, v18, v1
	v_add_f32_e32 v1, v48, v49
	v_pk_mul_f32 v[48:49], v[176:177], v[114:115] op_sel_hi:[1,0]
	v_add_f32_e32 v189, v34, v1
	v_pk_fma_f32 v[190:191], v[172:173], v[0:1], v[48:49] neg_lo:[0,0,1] neg_hi:[0,0,1]
	v_pk_fma_f32 v[48:49], v[172:173], v[0:1], v[48:49] op_sel_hi:[1,0,1]
	v_mul_f32_e32 v193, v174, v187
	v_mov_b32_e32 v191, v49
	v_mov_b32_e32 v48, v2
	v_mov_b32_e32 v49, v50
	v_pk_add_f32 v[190:191], v[48:49], v[190:191]
	v_mul_f32_e32 v213, v175, v189
	v_pk_mul_f32 v[48:49], v[172:173], v[190:191]
	v_mov_b32_e32 v18, v3
	v_mov_b32_e32 v192, v48
	v_mov_b32_e32 v212, v49
	v_pk_add_f32 v[48:49], v[192:193], v[212:213] neg_lo:[0,1] neg_hi:[0,1]
	v_mov_b32_e32 v188, v191
	v_pk_add_f32 v[2:3], v[18:19], v[48:49]
	v_pk_mul_f32 v[18:19], v[180:181], v[188:189]
	v_mov_b32_e32 v186, v190
	v_pk_fma_f32 v[18:19], v[182:183], v[186:187], v[18:19]
	v_mov_b32_e32 v34, v51
	v_pk_add_f32 v[18:19], v[34:35], v[18:19]
	v_mov_b32_e32 v48, v4
	v_pk_mul_f32 v[34:35], v[182:183], v[18:19]
	v_mov_b32_e32 v49, v20
	v_pk_fma_f32 v[34:35], v[180:181], v[2:3], v[34:35] neg_lo:[0,0,1] neg_hi:[0,0,1]
	v_mov_b32_e32 v50, v52
	v_pk_add_f32 v[34:35], v[48:49], v[34:35]
	v_pk_mul_f32 v[48:49], v[180:181], v[18:19]
	v_mov_b32_e32 v51, v36
	v_pk_fma_f32 v[48:49], v[182:183], v[2:3], v[48:49]
	v_mov_b32_e32 v20, v5
	v_pk_add_f32 v[192:193], v[50:51], v[48:49]
	v_mov_b32_e32 v36, v53
	v_pk_mul_f32 v[48:49], v[182:183], v[192:193]
	v_mov_b32_e32 v50, v54
	v_pk_fma_f32 v[48:49], v[180:181], v[34:35], v[48:49] neg_lo:[0,0,1] neg_hi:[0,0,1]
	v_mov_b32_e32 v51, v38
	v_pk_add_f32 v[4:5], v[20:21], v[48:49]
	v_pk_mul_f32 v[20:21], v[180:181], v[192:193]
	v_mov_b32_e32 v48, v6
	v_pk_fma_f32 v[20:21], v[182:183], v[34:35], v[20:21]
	v_mov_b32_e32 v49, v22
	v_pk_add_f32 v[20:21], v[36:37], v[20:21]
	v_mov_b32_e32 v22, v7
	v_pk_mul_f32 v[36:37], v[182:183], v[20:21]
	v_mov_b32_e32 v38, v55
	v_pk_fma_f32 v[36:37], v[180:181], v[4:5], v[36:37] neg_lo:[0,0,1] neg_hi:[0,0,1]
	v_cvt_pk_bf16_f32 v0, v112, v0
	v_pk_add_f32 v[36:37], v[48:49], v[36:37]
	v_pk_mul_f32 v[48:49], v[180:181], v[20:21]
	v_cvt_pk_bf16_f32 v1, v190, v2
	v_pk_fma_f32 v[48:49], v[182:183], v[4:5], v[48:49]
	v_cvt_pk_bf16_f32 v2, v148, v32
	v_pk_add_f32 v[52:53], v[50:51], v[48:49]
	v_mov_b32_e32 v50, v8
	v_pk_mul_f32 v[48:49], v[182:183], v[52:53]
	v_mov_b32_e32 v51, v24
	v_pk_fma_f32 v[48:49], v[180:181], v[36:37], v[48:49] neg_lo:[0,0,1] neg_hi:[0,0,1]
	v_mov_b32_e32 v24, v9
	v_pk_add_f32 v[6:7], v[22:23], v[48:49]
	v_pk_mul_f32 v[22:23], v[180:181], v[52:53]
	v_cvt_pk_bf16_f32 v3, v187, v3
	v_pk_fma_f32 v[22:23], v[182:183], v[36:37], v[22:23]
	ds_write2st64_b64 v207, v[0:1], v[2:3] offset1:4
	v_pk_add_f32 v[22:23], v[38:39], v[22:23]
	v_cvt_pk_bf16_f32 v0, v35, v5
	v_pk_mul_f32 v[38:39], v[182:183], v[22:23]
	v_pk_mul_f32 v[48:49], v[180:181], v[22:23]
	v_pk_fma_f32 v[38:39], v[180:181], v[6:7], v[38:39] neg_lo:[0,0,1] neg_hi:[0,0,1]
	v_pk_fma_f32 v[48:49], v[182:183], v[6:7], v[48:49]
	v_pk_add_f32 v[38:39], v[50:51], v[38:39]
	v_mov_b32_e32 v50, v56
	v_mov_b32_e32 v51, v40
	v_pk_add_f32 v[54:55], v[50:51], v[48:49]
	v_mov_b32_e32 v40, v57
	v_pk_mul_f32 v[48:49], v[182:183], v[54:55]
	v_mov_b32_e32 v50, v58
	v_pk_fma_f32 v[48:49], v[180:181], v[38:39], v[48:49] neg_lo:[0,0,1] neg_hi:[0,0,1]
	v_mov_b32_e32 v51, v42
	v_pk_add_f32 v[8:9], v[24:25], v[48:49]
	v_pk_mul_f32 v[24:25], v[180:181], v[54:55]
	v_mov_b32_e32 v48, v10
	v_pk_fma_f32 v[24:25], v[182:183], v[38:39], v[24:25]
	v_mov_b32_e32 v49, v26
	v_pk_add_f32 v[24:25], v[40:41], v[24:25]
	v_mov_b32_e32 v42, v59
	v_pk_mul_f32 v[40:41], v[182:183], v[24:25]
	v_mov_b32_e32 v26, v11
	v_pk_fma_f32 v[40:41], v[180:181], v[8:9], v[40:41] neg_lo:[0,0,1] neg_hi:[0,0,1]
	v_cvt_pk_bf16_f32 v1, v37, v7
	v_pk_add_f32 v[40:41], v[48:49], v[40:41]
	v_pk_mul_f32 v[48:49], v[180:181], v[24:25]
	v_pk_mov_b32 v[2:3], v[190:191], v[18:19] op_sel:[1,0]
	v_pk_fma_f32 v[48:49], v[182:183], v[8:9], v[48:49]
	s_nop 0
	v_pk_add_f32 v[56:57], v[50:51], v[48:49]
	s_nop 0
	v_pk_mul_f32 v[48:49], v[180:181], v[56:57]
	v_pk_mul_f32 v[58:59], v[182:183], v[56:57]
	v_pk_fma_f32 v[48:49], v[182:183], v[40:41], v[48:49]
	v_pk_fma_f32 v[58:59], v[180:181], v[40:41], v[58:59] neg_lo:[0,0,1] neg_hi:[0,0,1]
	v_pk_add_f32 v[42:43], v[42:43], v[48:49]
	v_pk_add_f32 v[10:11], v[26:27], v[58:59]
	v_pk_mul_f32 v[48:49], v[182:183], v[42:43]
	v_pk_mul_f32 v[50:51], v[180:181], v[42:43]
	v_pk_fma_f32 v[26:27], v[180:181], v[10:11], v[48:49] neg_lo:[0,0,1] neg_hi:[0,0,1]
	v_mov_b32_e32 v48, v12
	v_mov_b32_e32 v49, v28
	v_pk_add_f32 v[26:27], v[48:49], v[26:27]
	v_pk_fma_f32 v[48:49], v[182:183], v[10:11], v[50:51]
	v_mov_b32_e32 v50, v60
	v_mov_b32_e32 v51, v44
	v_pk_add_f32 v[58:59], v[50:51], v[48:49]
	v_mov_b32_e32 v28, v13
	v_pk_mul_f32 v[48:49], v[182:183], v[58:59]
	v_mov_b32_e32 v44, v61
	v_pk_fma_f32 v[48:49], v[180:181], v[26:27], v[48:49] neg_lo:[0,0,1] neg_hi:[0,0,1]
	v_mov_b32_e32 v50, v62
	v_pk_add_f32 v[12:13], v[28:29], v[48:49]
	v_pk_mul_f32 v[28:29], v[180:181], v[58:59]
	v_mov_b32_e32 v48, v14
	v_pk_fma_f32 v[28:29], v[182:183], v[26:27], v[28:29]
	v_mov_b32_e32 v49, v30
	v_pk_add_f32 v[28:29], v[44:45], v[28:29]
	v_mov_b32_e32 v51, v46
	v_pk_mul_f32 v[44:45], v[182:183], v[28:29]
	v_mov_b32_e32 v30, v15
	v_pk_fma_f32 v[44:45], v[180:181], v[12:13], v[44:45] neg_lo:[0,0,1] neg_hi:[0,0,1]
	v_mov_b32_e32 v46, v63
	v_pk_add_f32 v[44:45], v[48:49], v[44:45]
	v_pk_mul_f32 v[48:49], v[180:181], v[28:29]
	v_cvt_pk_bf16_f32 v5, v56, v42
	v_pk_fma_f32 v[48:49], v[182:183], v[12:13], v[48:49]
	s_nop 0
	v_pk_add_f32 v[60:61], v[50:51], v[48:49]
	s_nop 0
	v_pk_mul_f32 v[14:15], v[180:181], v[60:61]
	v_pk_mul_f32 v[48:49], v[182:183], v[60:61]
	v_pk_fma_f32 v[14:15], v[182:183], v[44:45], v[14:15]
	v_pk_fma_f32 v[48:49], v[180:181], v[44:45], v[48:49] neg_lo:[0,0,1] neg_hi:[0,0,1]
	v_pk_add_f32 v[50:51], v[46:47], v[14:15]
	v_cvt_pk_bf16_f32 v14, v34, v4
	v_cvt_pk_bf16_f32 v15, v36, v6
	v_pk_add_f32 v[48:49], v[30:31], v[48:49]
	v_cvt_pk_bf16_f32 v30, v38, v8
	v_cvt_pk_bf16_f32 v31, v40, v10
	ds_write2st64_b64 v208, v[14:15], v[0:1] offset1:4
	v_cvt_pk_bf16_f32 v0, v39, v9
	v_cvt_pk_bf16_f32 v1, v41, v11
	v_cvt_pk_bf16_f32 v46, v26, v12
	v_cvt_pk_bf16_f32 v47, v44, v48
	ds_write2st64_b64 v209, v[30:31], v[0:1] offset1:4
	v_cvt_pk_bf16_f32 v0, v27, v13
	v_cvt_pk_bf16_f32 v1, v45, v49
	ds_write2st64_b64 v210, v[46:47], v[0:1] offset1:4
	v_cvt_pk_bf16_f32 v0, v113, v114
	v_cvt_pk_bf16_f32 v1, v2, v3
	v_cvt_pk_bf16_f32 v8, v16, v33
	v_cvt_pk_bf16_f32 v9, v189, v19
	v_cvt_pk_bf16_f32 v2, v192, v20
	v_cvt_pk_bf16_f32 v3, v52, v22
	ds_write2st64_b64 v207, v[0:1], v[8:9] offset0:8 offset1:12
	v_cvt_pk_bf16_f32 v0, v193, v21
	v_cvt_pk_bf16_f32 v1, v53, v23
	v_cvt_pk_bf16_f32 v4, v54, v24
	ds_write2st64_b64 v208, v[2:3], v[0:1] offset0:8 offset1:12
	v_cvt_pk_bf16_f32 v0, v55, v25
	v_cvt_pk_bf16_f32 v1, v57, v43
	v_cvt_pk_bf16_f32 v6, v58, v28
	v_cvt_pk_bf16_f32 v7, v60, v50
	ds_write2st64_b64 v209, v[4:5], v[0:1] offset0:8 offset1:12
	v_cvt_pk_bf16_f32 v0, v59, v29
	v_cvt_pk_bf16_f32 v1, v61, v51
	ds_write2st64_b64 v210, v[6:7], v[0:1] offset0:8 offset1:12
	s_waitcnt lgkmcnt(0)
	ds_read_b64_tr_b16 v[0:1], v151 offset:0
	ds_read_b64_tr_b16 v[2:3], v199 offset:0
	ds_read_b64_tr_b16 v[28:29], v151 offset:1024
	ds_read_b64_tr_b16 v[30:31], v199 offset:1024
	ds_read_b64_tr_b16 v[24:25], v151 offset:2048
	ds_read_b64_tr_b16 v[26:27], v199 offset:2048
	ds_read_b64_tr_b16 v[20:21], v151 offset:3072
	ds_read_b64_tr_b16 v[22:23], v199 offset:3072
	ds_read_b64_tr_b16 v[16:17], v151 offset:4096
	ds_read_b64_tr_b16 v[18:19], v199 offset:4096
	ds_read_b64_tr_b16 v[44:45], v151 offset:5120
	ds_read_b64_tr_b16 v[46:47], v199 offset:5120
	ds_read_b64_tr_b16 v[40:41], v151 offset:6144
	ds_read_b64_tr_b16 v[42:43], v199 offset:6144
	ds_read_b64_tr_b16 v[52:53], v151 offset:7168
	ds_read_b64_tr_b16 v[54:55], v199 offset:7168
	s_waitcnt lgkmcnt(0)
	s_nop 0
	v_mfma_f32_32x32x16_bf16 v[0:15], v[68:71], v[0:3], 0
	v_mfma_f32_32x32x16_bf16 v[0:15], v[64:67], v[28:31], v[0:15]
	v_mfma_f32_32x32x16_bf16 v[0:15], v[76:79], v[24:27], v[0:15]
	v_mfma_f32_32x32x16_bf16 v[0:15], v[72:75], v[20:23], v[0:15]
	v_mfma_f32_32x32x16_bf16 v[0:15], v[84:87], v[16:19], v[0:15]
	v_mfma_f32_32x32x16_bf16 v[0:15], v[80:83], v[44:47], v[0:15]
	v_mfma_f32_32x32x16_bf16 v[0:15], v[92:95], v[40:43], v[0:15]
	v_mfma_f32_32x32x16_bf16 v[0:15], v[88:91], v[52:55], v[0:15]
	s_and_saveexec_b64 s[2:3], s[52:53]
	s_cbranch_execz .LBB0_186
	s_nop 7
	v_add_u32_e32 v16, v200, v146
	v_add_u32_e32 v16, 0x2000, v16
	ds_read2_b64 v[16:19], v16 offset1:2
	s_waitcnt lgkmcnt(0)
	v_lshlrev_b32_e32 v10, 16, v19
	v_and_b32_e32 v11, 0xffff0000, v19
	v_pk_fma_f32 v[6:7], v[102:103], v[10:11], v[6:7]
	v_mul_f32_e32 v10, v7, v7
	v_fmaak_f32 v10, v240, v10, 0xc0135761
	v_mul_f32_e32 v11, v6, v6
	v_mul_f32_e32 v10, v7, v10
	v_fmaak_f32 v11, v240, v11, 0xc0135761
	v_mul_f32_e32 v11, v6, v11
	v_exp_f32_e32 v10, v10
	v_exp_f32_e32 v11, v11
	v_add_f32_e32 v8, 1.0, v10
	v_rcp_f32_e32 v9, v8
	v_add_f32_e32 v8, 1.0, v11
	v_lshlrev_b32_e32 v10, 16, v18
	v_and_b32_e32 v11, 0xffff0000, v18
	v_pk_fma_f32 v[4:5], v[100:101], v[10:11], v[4:5]
	v_and_b32_e32 v13, 0xffff0000, v17
	v_mul_f32_e32 v10, v5, v5
	v_fmaak_f32 v10, v240, v10, 0xc0135761
	v_mul_f32_e32 v11, v4, v4
	v_mul_f32_e32 v10, v5, v10
	v_fmaak_f32 v11, v240, v11, 0xc0135761
	v_mul_f32_e32 v11, v4, v11
	v_exp_f32_e32 v10, v10
	v_exp_f32_e32 v12, v11
	v_and_b32_e32 v15, 0xffff0000, v16
	v_add_f32_e32 v10, 1.0, v10
	v_rcp_f32_e32 v11, v10
	v_add_f32_e32 v10, 1.0, v12
	v_lshlrev_b32_e32 v12, 16, v17
	v_pk_fma_f32 v[2:3], v[98:99], v[12:13], v[2:3]
	v_rcp_f32_e32 v8, v8
	v_mul_f32_e32 v12, v3, v3
	v_fmaak_f32 v12, v240, v12, 0xc0135761
	v_mul_f32_e32 v13, v2, v2
	v_mul_f32_e32 v12, v3, v12
	v_fmaak_f32 v13, v240, v13, 0xc0135761
	v_mul_f32_e32 v13, v2, v13
	v_exp_f32_e32 v12, v12
	v_exp_f32_e32 v14, v13
	s_cmp_eq_u32 s24, -3
	v_add_f32_e32 v12, 1.0, v12
	v_rcp_f32_e32 v13, v12
	v_add_f32_e32 v12, 1.0, v14
	v_lshlrev_b32_e32 v14, 16, v16
	v_pk_fma_f32 v[0:1], v[96:97], v[14:15], v[0:1]
	v_rcp_f32_e32 v12, v12
	v_mul_f32_e32 v14, v1, v1
	v_fmaak_f32 v14, v240, v14, 0xc0135761
	v_mul_f32_e32 v15, v0, v0
	v_mul_f32_e32 v14, v1, v14
	v_fmaak_f32 v15, v240, v15, 0xc0135761
	v_mul_f32_e32 v15, v0, v15
	v_exp_f32_e32 v14, v14
	v_exp_f32_e32 v16, v15
	v_rcp_f32_e32 v10, v10
	v_add_f32_e32 v14, 1.0, v14
	v_rcp_f32_e32 v15, v14
	v_add_f32_e32 v14, 1.0, v16
	v_rcp_f32_e32 v14, v14
	s_cselect_b64 vcc, -1, 0
	s_ashr_i32 s15, s14, 31
	v_pk_mul_f32 v[6:7], v[6:7], v[8:9]
	v_lshl_add_u64 v[8:9], s[14:15], 4, v[120:121]
	v_cndmask_b32_e64 v9, v9, 0, vcc
	v_cndmask_b32_e32 v8, v8, v154, vcc
	v_pk_mul_f32 v[2:3], v[2:3], v[12:13]
	v_pk_mul_f32 v[0:1], v[0:1], v[14:15]
	v_lshlrev_b64 v[8:9], 11, v[8:9]
	v_pk_mul_f32 v[4:5], v[4:5], v[10:11]
	v_lshl_add_u64 v[8:9], v[126:127], 0, v[8:9]
	v_cvt_pk_bf16_f32 v0, v0, v1
	v_cvt_pk_bf16_f32 v1, v2, v3
	v_cvt_pk_bf16_f32 v2, v4, v5
	v_cvt_pk_bf16_f32 v3, v6, v7
	global_store_dwordx2 v[8:9], v[0:1], off
	global_store_dwordx2 v[8:9], v[2:3], off offset:16
	s_branch .LBB0_186

.LBB0_966:
	s_or_b64 exec, exec, s[0:1]
	s_waitcnt lgkmcnt(0)
	s_barrier
	v_readlane_b32 s6, v248, 6
	v_readlane_b32 s7, v248, 7
	v_and_b32_e32 v16, 63, v194
	v_lshrrev_b32_e32 v18, 6, v194
	v_lshlrev_b32_e32 v17, 4, v16
	v_lshlrev_b32_e32 v16, 3, v16
	v_mov_b32_e32 v19, 0
	v_mov_b32_e32 v20, 0x4f800000
	v_mov_b32_e32 v21, 0x30800000
	v_readfirstlane_b32 s8, v18
	s_mov_b32 s9, s72
	s_add_u32 s10, s62, 0x2f10000
	s_addc_u32 s11, s63, 0
	s_add_u32 s12, s62, 0xc1800
	s_addc_u32 s13, s63, 0
	s_add_u32 s8, s8, s77
	s_cmp_lt_u32 s8, 0x8000
	s_cbranch_scc0 .LBB0_969
	global_load_dwordx4 v[0:3], v17, s[6:7]
	global_load_dwordx4 v[4:7], v17, s[6:7] offset:1024
	global_load_dwordx4 v[8:11], v17, s[6:7] offset:2048
	global_load_dwordx4 v[12:15], v17, s[6:7] offset:3072
	s_min_u32 s14, s8, 0x7fff
	s_lshl_b32 s15, s14, 3
	s_add_u32 s16, s12, s15
	s_addc_u32 s17, s13, 0
	s_lshl_b32 s15, s14, 11
	s_add_u32 s18, s10, s15
	s_addc_u32 s19, s11, 0
	global_load_dwordx2 v[24:25], v19, s[16:17]
	global_load_dwordx2 v[26:27], v16, s[18:19] nt
	global_load_dwordx2 v[28:29], v16, s[18:19] offset:512 nt
	global_load_dwordx2 v[30:31], v16, s[18:19] offset:1024 nt
	global_load_dwordx2 v[32:33], v16, s[18:19] offset:1536 nt
	s_mul_i32 s14, s9, 1
	s_add_u32 s14, s14, s8
	s_min_u32 s14, s14, 0x7fff
	s_lshl_b32 s15, s14, 3
	s_add_u32 s16, s12, s15
	s_addc_u32 s17, s13, 0
	s_lshl_b32 s15, s14, 11
	s_add_u32 s18, s10, s15
	s_addc_u32 s19, s11, 0
	global_load_dwordx2 v[34:35], v19, s[16:17]
	global_load_dwordx2 v[36:37], v16, s[18:19] nt
	global_load_dwordx2 v[38:39], v16, s[18:19] offset:512 nt
	global_load_dwordx2 v[40:41], v16, s[18:19] offset:1024 nt
	global_load_dwordx2 v[42:43], v16, s[18:19] offset:1536 nt
	s_mul_i32 s14, s9, 2
	s_add_u32 s14, s14, s8
	s_min_u32 s14, s14, 0x7fff
	s_lshl_b32 s15, s14, 3
	s_add_u32 s16, s12, s15
	s_addc_u32 s17, s13, 0
	s_lshl_b32 s15, s14, 11
	s_add_u32 s18, s10, s15
	s_addc_u32 s19, s11, 0
	global_load_dwordx2 v[44:45], v19, s[16:17]
	global_load_dwordx2 v[46:47], v16, s[18:19] nt
	global_load_dwordx2 v[48:49], v16, s[18:19] offset:512 nt
	global_load_dwordx2 v[50:51], v16, s[18:19] offset:1024 nt
	global_load_dwordx2 v[52:53], v16, s[18:19] offset:1536 nt
	s_mul_i32 s14, s9, 3
	s_add_u32 s14, s14, s8
	s_min_u32 s14, s14, 0x7fff
	s_lshl_b32 s15, s14, 3
	s_add_u32 s16, s12, s15
	s_addc_u32 s17, s13, 0
	s_lshl_b32 s15, s14, 11
	s_add_u32 s18, s10, s15
	s_addc_u32 s19, s11, 0
	global_load_dwordx2 v[54:55], v19, s[16:17]
	global_load_dwordx2 v[56:57], v16, s[18:19] nt
	global_load_dwordx2 v[58:59], v16, s[18:19] offset:512 nt
	global_load_dwordx2 v[60:61], v16, s[18:19] offset:1024 nt
	global_load_dwordx2 v[62:63], v16, s[18:19] offset:1536 nt
	s_waitcnt vmcnt(0)
.Lfin_loop:
	s_mul_i32 s22, s9, 7
	s_add_u32 s22, s22, s8
	s_cmp_lt_u32 s22, 0x8000
	s_cbranch_scc0 .Lfin_tail_a
	s_lshl_b32 s23, s9, 2
	s_add_u32 s8, s8, s23
	s_min_u32 s14, s8, 0x7fff
	s_lshl_b32 s15, s14, 3
	s_add_u32 s16, s12, s15
	s_addc_u32 s17, s13, 0
	s_lshl_b32 s15, s14, 11
	s_add_u32 s18, s10, s15
	s_addc_u32 s19, s11, 0
	global_load_dwordx2 v[64:65], v19, s[16:17]
	global_load_dwordx2 v[66:67], v16, s[18:19] nt
	global_load_dwordx2 v[68:69], v16, s[18:19] offset:512 nt
	global_load_dwordx2 v[70:71], v16, s[18:19] offset:1024 nt
	global_load_dwordx2 v[72:73], v16, s[18:19] offset:1536 nt
	s_mul_i32 s14, s9, 1
	s_add_u32 s14, s14, s8
	s_min_u32 s14, s14, 0x7fff
	s_lshl_b32 s15, s14, 3
	s_add_u32 s16, s12, s15
	s_addc_u32 s17, s13, 0
	s_lshl_b32 s15, s14, 11
	s_add_u32 s18, s10, s15
	s_addc_u32 s19, s11, 0
	global_load_dwordx2 v[74:75], v19, s[16:17]
	global_load_dwordx2 v[76:77], v16, s[18:19] nt
	global_load_dwordx2 v[78:79], v16, s[18:19] offset:512 nt
	global_load_dwordx2 v[80:81], v16, s[18:19] offset:1024 nt
	global_load_dwordx2 v[82:83], v16, s[18:19] offset:1536 nt
	s_mul_i32 s14, s9, 2
	s_add_u32 s14, s14, s8
	s_min_u32 s14, s14, 0x7fff
	s_lshl_b32 s15, s14, 3
	s_add_u32 s16, s12, s15
	s_addc_u32 s17, s13, 0
	s_lshl_b32 s15, s14, 11
	s_add_u32 s18, s10, s15
	s_addc_u32 s19, s11, 0
	global_load_dwordx2 v[84:85], v19, s[16:17]
	global_load_dwordx2 v[86:87], v16, s[18:19] nt
	global_load_dwordx2 v[88:89], v16, s[18:19] offset:512 nt
	global_load_dwordx2 v[90:91], v16, s[18:19] offset:1024 nt
	global_load_dwordx2 v[92:93], v16, s[18:19] offset:1536 nt
	s_mul_i32 s14, s9, 3
	s_add_u32 s14, s14, s8
	s_min_u32 s14, s14, 0x7fff
	s_lshl_b32 s15, s14, 3
	s_add_u32 s16, s12, s15
	s_addc_u32 s17, s13, 0
	s_lshl_b32 s15, s14, 11
	s_add_u32 s18, s10, s15
	s_addc_u32 s19, s11, 0
	global_load_dwordx2 v[94:95], v19, s[16:17]
	global_load_dwordx2 v[96:97], v16, s[18:19] nt
	global_load_dwordx2 v[98:99], v16, s[18:19] offset:512 nt
	global_load_dwordx2 v[100:101], v16, s[18:19] offset:1024 nt
	global_load_dwordx2 v[102:103], v16, s[18:19] offset:1536 nt
	s_sub_u32 s8, s8, s23
	s_waitcnt vmcnt(36)
	s_mov_b32 s14, s8
	s_lshl_b32 s15, s14, 12
	s_add_u32 s20, s60, s15
	s_addc_u32 s21, s61, 0
	v_cvt_f32_u32_e32 v104, v25
	v_cvt_f32_u32_e32 v105, v24
	v_fma_f32 v104, v104, v20, v105
	v_fmaak_f32 v104, v104, v21, 0x358637bd
	v_rsq_f32_e32 v104, v104
	v_lshlrev_b32_e32 v106, 16, v26
	v_and_b32_e32 v107, 0xffff0000, v26
	v_lshlrev_b32_e32 v108, 16, v27
	v_and_b32_e32 v109, 0xffff0000, v27
	v_pk_mul_f32 v[106:107], v[104:105], v[106:107] op_sel_hi:[0,1]
	v_pk_mul_f32 v[108:109], v[104:105], v[108:109] op_sel_hi:[0,1]
	v_pk_mul_f32 v[106:107], v[0:1], v[106:107]
	v_pk_mul_f32 v[108:109], v[2:3], v[108:109]
	global_store_dwordx4 v17, v[106:109], s[20:21] nt
	v_lshlrev_b32_e32 v110, 16, v28
	v_and_b32_e32 v111, 0xffff0000, v28
	v_lshlrev_b32_e32 v112, 16, v29
	v_and_b32_e32 v113, 0xffff0000, v29
	v_pk_mul_f32 v[110:111], v[104:105], v[110:111] op_sel_hi:[0,1]
	v_pk_mul_f32 v[112:113], v[104:105], v[112:113] op_sel_hi:[0,1]
	v_pk_mul_f32 v[110:111], v[4:5], v[110:111]
	v_pk_mul_f32 v[112:113], v[6:7], v[112:113]
	global_store_dwordx4 v17, v[110:113], s[20:21] offset:1024 nt
	v_lshlrev_b32_e32 v106, 16, v30
	v_and_b32_e32 v107, 0xffff0000, v30
	v_lshlrev_b32_e32 v108, 16, v31
	v_and_b32_e32 v109, 0xffff0000, v31
	v_pk_mul_f32 v[106:107], v[104:105], v[106:107] op_sel_hi:[0,1]
	v_pk_mul_f32 v[108:109], v[104:105], v[108:109] op_sel_hi:[0,1]
	v_pk_mul_f32 v[106:107], v[8:9], v[106:107]
	v_pk_mul_f32 v[108:109], v[10:11], v[108:109]
	global_store_dwordx4 v17, v[106:109], s[20:21] offset:2048 nt
	v_lshlrev_b32_e32 v110, 16, v32
	v_and_b32_e32 v111, 0xffff0000, v32
	v_lshlrev_b32_e32 v112, 16, v33
	v_and_b32_e32 v113, 0xffff0000, v33
	v_pk_mul_f32 v[110:111], v[104:105], v[110:111] op_sel_hi:[0,1]
	v_pk_mul_f32 v[112:113], v[104:105], v[112:113] op_sel_hi:[0,1]
	v_pk_mul_f32 v[110:111], v[12:13], v[110:111]
	v_pk_mul_f32 v[112:113], v[14:15], v[112:113]
	global_store_dwordx4 v17, v[110:113], s[20:21] offset:3072 nt
	s_mul_i32 s14, s9, 1
	s_add_u32 s14, s14, s8
	s_lshl_b32 s15, s14, 12
	s_add_u32 s20, s60, s15
	s_addc_u32 s21, s61, 0
	v_cvt_f32_u32_e32 v104, v35
	v_cvt_f32_u32_e32 v105, v34
	v_fma_f32 v104, v104, v20, v105
	v_fmaak_f32 v104, v104, v21, 0x358637bd
	v_rsq_f32_e32 v104, v104
	v_lshlrev_b32_e32 v106, 16, v36
	v_and_b32_e32 v107, 0xffff0000, v36
	v_lshlrev_b32_e32 v108, 16, v37
	v_and_b32_e32 v109, 0xffff0000, v37
	v_pk_mul_f32 v[106:107], v[104:105], v[106:107] op_sel_hi:[0,1]
	v_pk_mul_f32 v[108:109], v[104:105], v[108:109] op_sel_hi:[0,1]
	v_pk_mul_f32 v[106:107], v[0:1], v[106:107]
	v_pk_mul_f32 v[108:109], v[2:3], v[108:109]
	global_store_dwordx4 v17, v[106:109], s[20:21] nt
	v_lshlrev_b32_e32 v110, 16, v38
	v_and_b32_e32 v111, 0xffff0000, v38
	v_lshlrev_b32_e32 v112, 16, v39
	v_and_b32_e32 v113, 0xffff0000, v39
	v_pk_mul_f32 v[110:111], v[104:105], v[110:111] op_sel_hi:[0,1]
	v_pk_mul_f32 v[112:113], v[104:105], v[112:113] op_sel_hi:[0,1]
	v_pk_mul_f32 v[110:111], v[4:5], v[110:111]
	v_pk_mul_f32 v[112:113], v[6:7], v[112:113]
	global_store_dwordx4 v17, v[110:113], s[20:21] offset:1024 nt
	v_lshlrev_b32_e32 v106, 16, v40
	v_and_b32_e32 v107, 0xffff0000, v40
	v_lshlrev_b32_e32 v108, 16, v41
	v_and_b32_e32 v109, 0xffff0000, v41
	v_pk_mul_f32 v[106:107], v[104:105], v[106:107] op_sel_hi:[0,1]
	v_pk_mul_f32 v[108:109], v[104:105], v[108:109] op_sel_hi:[0,1]
	v_pk_mul_f32 v[106:107], v[8:9], v[106:107]
	v_pk_mul_f32 v[108:109], v[10:11], v[108:109]
	global_store_dwordx4 v17, v[106:109], s[20:21] offset:2048 nt
	v_lshlrev_b32_e32 v110, 16, v42
	v_and_b32_e32 v111, 0xffff0000, v42
	v_lshlrev_b32_e32 v112, 16, v43
	v_and_b32_e32 v113, 0xffff0000, v43
	v_pk_mul_f32 v[110:111], v[104:105], v[110:111] op_sel_hi:[0,1]
	v_pk_mul_f32 v[112:113], v[104:105], v[112:113] op_sel_hi:[0,1]
	v_pk_mul_f32 v[110:111], v[12:13], v[110:111]
	v_pk_mul_f32 v[112:113], v[14:15], v[112:113]
	global_store_dwordx4 v17, v[110:113], s[20:21] offset:3072 nt
	s_mul_i32 s14, s9, 2
	s_add_u32 s14, s14, s8
	s_lshl_b32 s15, s14, 12
	s_add_u32 s20, s60, s15
	s_addc_u32 s21, s61, 0
	v_cvt_f32_u32_e32 v104, v45
	v_cvt_f32_u32_e32 v105, v44
	v_fma_f32 v104, v104, v20, v105
	v_fmaak_f32 v104, v104, v21, 0x358637bd
	v_rsq_f32_e32 v104, v104
	v_lshlrev_b32_e32 v106, 16, v46
	v_and_b32_e32 v107, 0xffff0000, v46
	v_lshlrev_b32_e32 v108, 16, v47
	v_and_b32_e32 v109, 0xffff0000, v47
	v_pk_mul_f32 v[106:107], v[104:105], v[106:107] op_sel_hi:[0,1]
	v_pk_mul_f32 v[108:109], v[104:105], v[108:109] op_sel_hi:[0,1]
	v_pk_mul_f32 v[106:107], v[0:1], v[106:107]
	v_pk_mul_f32 v[108:109], v[2:3], v[108:109]
	global_store_dwordx4 v17, v[106:109], s[20:21] nt
	v_lshlrev_b32_e32 v110, 16, v48
	v_and_b32_e32 v111, 0xffff0000, v48
	v_lshlrev_b32_e32 v112, 16, v49
	v_and_b32_e32 v113, 0xffff0000, v49
	v_pk_mul_f32 v[110:111], v[104:105], v[110:111] op_sel_hi:[0,1]
	v_pk_mul_f32 v[112:113], v[104:105], v[112:113] op_sel_hi:[0,1]
	v_pk_mul_f32 v[110:111], v[4:5], v[110:111]
	v_pk_mul_f32 v[112:113], v[6:7], v[112:113]
	global_store_dwordx4 v17, v[110:113], s[20:21] offset:1024 nt
	v_lshlrev_b32_e32 v106, 16, v50
	v_and_b32_e32 v107, 0xffff0000, v50
	v_lshlrev_b32_e32 v108, 16, v51
	v_and_b32_e32 v109, 0xffff0000, v51
	v_pk_mul_f32 v[106:107], v[104:105], v[106:107] op_sel_hi:[0,1]
	v_pk_mul_f32 v[108:109], v[104:105], v[108:109] op_sel_hi:[0,1]
	v_pk_mul_f32 v[106:107], v[8:9], v[106:107]
	v_pk_mul_f32 v[108:109], v[10:11], v[108:109]
	global_store_dwordx4 v17, v[106:109], s[20:21] offset:2048 nt
	v_lshlrev_b32_e32 v110, 16, v52
	v_and_b32_e32 v111, 0xffff0000, v52
	v_lshlrev_b32_e32 v112, 16, v53
	v_and_b32_e32 v113, 0xffff0000, v53
	v_pk_mul_f32 v[110:111], v[104:105], v[110:111] op_sel_hi:[0,1]
	v_pk_mul_f32 v[112:113], v[104:105], v[112:113] op_sel_hi:[0,1]
	v_pk_mul_f32 v[110:111], v[12:13], v[110:111]
	v_pk_mul_f32 v[112:113], v[14:15], v[112:113]
	global_store_dwordx4 v17, v[110:113], s[20:21] offset:3072 nt
	s_mul_i32 s14, s9, 3
	s_add_u32 s14, s14, s8
	s_lshl_b32 s15, s14, 12
	s_add_u32 s20, s60, s15
	s_addc_u32 s21, s61, 0
	v_cvt_f32_u32_e32 v104, v55
	v_cvt_f32_u32_e32 v105, v54
	v_fma_f32 v104, v104, v20, v105
	v_fmaak_f32 v104, v104, v21, 0x358637bd
	v_rsq_f32_e32 v104, v104
	v_lshlrev_b32_e32 v106, 16, v56
	v_and_b32_e32 v107, 0xffff0000, v56
	v_lshlrev_b32_e32 v108, 16, v57
	v_and_b32_e32 v109, 0xffff0000, v57
	v_pk_mul_f32 v[106:107], v[104:105], v[106:107] op_sel_hi:[0,1]
	v_pk_mul_f32 v[108:109], v[104:105], v[108:109] op_sel_hi:[0,1]
	v_pk_mul_f32 v[106:107], v[0:1], v[106:107]
	v_pk_mul_f32 v[108:109], v[2:3], v[108:109]
	global_store_dwordx4 v17, v[106:109], s[20:21] nt
	v_lshlrev_b32_e32 v110, 16, v58
	v_and_b32_e32 v111, 0xffff0000, v58
	v_lshlrev_b32_e32 v112, 16, v59
	v_and_b32_e32 v113, 0xffff0000, v59
	v_pk_mul_f32 v[110:111], v[104:105], v[110:111] op_sel_hi:[0,1]
	v_pk_mul_f32 v[112:113], v[104:105], v[112:113] op_sel_hi:[0,1]
	v_pk_mul_f32 v[110:111], v[4:5], v[110:111]
	v_pk_mul_f32 v[112:113], v[6:7], v[112:113]
	global_store_dwordx4 v17, v[110:113], s[20:21] offset:1024 nt
	v_lshlrev_b32_e32 v106, 16, v60
	v_and_b32_e32 v107, 0xffff0000, v60
	v_lshlrev_b32_e32 v108, 16, v61
	v_and_b32_e32 v109, 0xffff0000, v61
	v_pk_mul_f32 v[106:107], v[104:105], v[106:107] op_sel_hi:[0,1]
	v_pk_mul_f32 v[108:109], v[104:105], v[108:109] op_sel_hi:[0,1]
	v_pk_mul_f32 v[106:107], v[8:9], v[106:107]
	v_pk_mul_f32 v[108:109], v[10:11], v[108:109]
	global_store_dwordx4 v17, v[106:109], s[20:21] offset:2048 nt
	v_lshlrev_b32_e32 v110, 16, v62
	v_and_b32_e32 v111, 0xffff0000, v62
	v_lshlrev_b32_e32 v112, 16, v63
	v_and_b32_e32 v113, 0xffff0000, v63
	v_pk_mul_f32 v[110:111], v[104:105], v[110:111] op_sel_hi:[0,1]
	v_pk_mul_f32 v[112:113], v[104:105], v[112:113] op_sel_hi:[0,1]
	v_pk_mul_f32 v[110:111], v[12:13], v[110:111]
	v_pk_mul_f32 v[112:113], v[14:15], v[112:113]
	global_store_dwordx4 v17, v[110:113], s[20:21] offset:3072 nt
	s_add_u32 s8, s8, s23
	s_mul_i32 s22, s9, 7
	s_add_u32 s22, s22, s8
	s_cmp_lt_u32 s22, 0x8000
	s_cbranch_scc0 .Lfin_tail_b
	s_lshl_b32 s23, s9, 2
	s_add_u32 s8, s8, s23
	s_min_u32 s14, s8, 0x7fff
	s_lshl_b32 s15, s14, 3
	s_add_u32 s16, s12, s15
	s_addc_u32 s17, s13, 0
	s_lshl_b32 s15, s14, 11
	s_add_u32 s18, s10, s15
	s_addc_u32 s19, s11, 0
	global_load_dwordx2 v[24:25], v19, s[16:17]
	global_load_dwordx2 v[26:27], v16, s[18:19] nt
	global_load_dwordx2 v[28:29], v16, s[18:19] offset:512 nt
	global_load_dwordx2 v[30:31], v16, s[18:19] offset:1024 nt
	global_load_dwordx2 v[32:33], v16, s[18:19] offset:1536 nt
	s_mul_i32 s14, s9, 1
	s_add_u32 s14, s14, s8
	s_min_u32 s14, s14, 0x7fff
	s_lshl_b32 s15, s14, 3
	s_add_u32 s16, s12, s15
	s_addc_u32 s17, s13, 0
	s_lshl_b32 s15, s14, 11
	s_add_u32 s18, s10, s15
	s_addc_u32 s19, s11, 0
	global_load_dwordx2 v[34:35], v19, s[16:17]
	global_load_dwordx2 v[36:37], v16, s[18:19] nt
	global_load_dwordx2 v[38:39], v16, s[18:19] offset:512 nt
	global_load_dwordx2 v[40:41], v16, s[18:19] offset:1024 nt
	global_load_dwordx2 v[42:43], v16, s[18:19] offset:1536 nt
	s_mul_i32 s14, s9, 2
	s_add_u32 s14, s14, s8
	s_min_u32 s14, s14, 0x7fff
	s_lshl_b32 s15, s14, 3
	s_add_u32 s16, s12, s15
	s_addc_u32 s17, s13, 0
	s_lshl_b32 s15, s14, 11
	s_add_u32 s18, s10, s15
	s_addc_u32 s19, s11, 0
	global_load_dwordx2 v[44:45], v19, s[16:17]
	global_load_dwordx2 v[46:47], v16, s[18:19] nt
	global_load_dwordx2 v[48:49], v16, s[18:19] offset:512 nt
	global_load_dwordx2 v[50:51], v16, s[18:19] offset:1024 nt
	global_load_dwordx2 v[52:53], v16, s[18:19] offset:1536 nt
	s_mul_i32 s14, s9, 3
	s_add_u32 s14, s14, s8
	s_min_u32 s14, s14, 0x7fff
	s_lshl_b32 s15, s14, 3
	s_add_u32 s16, s12, s15
	s_addc_u32 s17, s13, 0
	s_lshl_b32 s15, s14, 11
	s_add_u32 s18, s10, s15
	s_addc_u32 s19, s11, 0
	global_load_dwordx2 v[54:55], v19, s[16:17]
	global_load_dwordx2 v[56:57], v16, s[18:19] nt
	global_load_dwordx2 v[58:59], v16, s[18:19] offset:512 nt
	global_load_dwordx2 v[60:61], v16, s[18:19] offset:1024 nt
	global_load_dwordx2 v[62:63], v16, s[18:19] offset:1536 nt
	s_sub_u32 s8, s8, s23
	s_waitcnt vmcnt(36)
	s_mov_b32 s14, s8
	s_lshl_b32 s15, s14, 12
	s_add_u32 s20, s60, s15
	s_addc_u32 s21, s61, 0
	v_cvt_f32_u32_e32 v104, v65
	v_cvt_f32_u32_e32 v105, v64
	v_fma_f32 v104, v104, v20, v105
	v_fmaak_f32 v104, v104, v21, 0x358637bd
	v_rsq_f32_e32 v104, v104
	v_lshlrev_b32_e32 v106, 16, v66
	v_and_b32_e32 v107, 0xffff0000, v66
	v_lshlrev_b32_e32 v108, 16, v67
	v_and_b32_e32 v109, 0xffff0000, v67
	v_pk_mul_f32 v[106:107], v[104:105], v[106:107] op_sel_hi:[0,1]
	v_pk_mul_f32 v[108:109], v[104:105], v[108:109] op_sel_hi:[0,1]
	v_pk_mul_f32 v[106:107], v[0:1], v[106:107]
	v_pk_mul_f32 v[108:109], v[2:3], v[108:109]
	global_store_dwordx4 v17, v[106:109], s[20:21] nt
	v_lshlrev_b32_e32 v110, 16, v68
	v_and_b32_e32 v111, 0xffff0000, v68
	v_lshlrev_b32_e32 v112, 16, v69
	v_and_b32_e32 v113, 0xffff0000, v69
	v_pk_mul_f32 v[110:111], v[104:105], v[110:111] op_sel_hi:[0,1]
	v_pk_mul_f32 v[112:113], v[104:105], v[112:113] op_sel_hi:[0,1]
	v_pk_mul_f32 v[110:111], v[4:5], v[110:111]
	v_pk_mul_f32 v[112:113], v[6:7], v[112:113]
	global_store_dwordx4 v17, v[110:113], s[20:21] offset:1024 nt
	v_lshlrev_b32_e32 v106, 16, v70
	v_and_b32_e32 v107, 0xffff0000, v70
	v_lshlrev_b32_e32 v108, 16, v71
	v_and_b32_e32 v109, 0xffff0000, v71
	v_pk_mul_f32 v[106:107], v[104:105], v[106:107] op_sel_hi:[0,1]
	v_pk_mul_f32 v[108:109], v[104:105], v[108:109] op_sel_hi:[0,1]
	v_pk_mul_f32 v[106:107], v[8:9], v[106:107]
	v_pk_mul_f32 v[108:109], v[10:11], v[108:109]
	global_store_dwordx4 v17, v[106:109], s[20:21] offset:2048 nt
	v_lshlrev_b32_e32 v110, 16, v72
	v_and_b32_e32 v111, 0xffff0000, v72
	v_lshlrev_b32_e32 v112, 16, v73
	v_and_b32_e32 v113, 0xffff0000, v73
	v_pk_mul_f32 v[110:111], v[104:105], v[110:111] op_sel_hi:[0,1]
	v_pk_mul_f32 v[112:113], v[104:105], v[112:113] op_sel_hi:[0,1]
	v_pk_mul_f32 v[110:111], v[12:13], v[110:111]
	v_pk_mul_f32 v[112:113], v[14:15], v[112:113]
	global_store_dwordx4 v17, v[110:113], s[20:21] offset:3072 nt
	s_mul_i32 s14, s9, 1
	s_add_u32 s14, s14, s8
	s_lshl_b32 s15, s14, 12
	s_add_u32 s20, s60, s15
	s_addc_u32 s21, s61, 0
	v_cvt_f32_u32_e32 v104, v75
	v_cvt_f32_u32_e32 v105, v74
	v_fma_f32 v104, v104, v20, v105
	v_fmaak_f32 v104, v104, v21, 0x358637bd
	v_rsq_f32_e32 v104, v104
	v_lshlrev_b32_e32 v106, 16, v76
	v_and_b32_e32 v107, 0xffff0000, v76
	v_lshlrev_b32_e32 v108, 16, v77
	v_and_b32_e32 v109, 0xffff0000, v77
	v_pk_mul_f32 v[106:107], v[104:105], v[106:107] op_sel_hi:[0,1]
	v_pk_mul_f32 v[108:109], v[104:105], v[108:109] op_sel_hi:[0,1]
	v_pk_mul_f32 v[106:107], v[0:1], v[106:107]
	v_pk_mul_f32 v[108:109], v[2:3], v[108:109]
	global_store_dwordx4 v17, v[106:109], s[20:21] nt
	v_lshlrev_b32_e32 v110, 16, v78
	v_and_b32_e32 v111, 0xffff0000, v78
	v_lshlrev_b32_e32 v112, 16, v79
	v_and_b32_e32 v113, 0xffff0000, v79
	v_pk_mul_f32 v[110:111], v[104:105], v[110:111] op_sel_hi:[0,1]
	v_pk_mul_f32 v[112:113], v[104:105], v[112:113] op_sel_hi:[0,1]
	v_pk_mul_f32 v[110:111], v[4:5], v[110:111]
	v_pk_mul_f32 v[112:113], v[6:7], v[112:113]
	global_store_dwordx4 v17, v[110:113], s[20:21] offset:1024 nt
	v_lshlrev_b32_e32 v106, 16, v80
	v_and_b32_e32 v107, 0xffff0000, v80
	v_lshlrev_b32_e32 v108, 16, v81
	v_and_b32_e32 v109, 0xffff0000, v81
	v_pk_mul_f32 v[106:107], v[104:105], v[106:107] op_sel_hi:[0,1]
	v_pk_mul_f32 v[108:109], v[104:105], v[108:109] op_sel_hi:[0,1]
	v_pk_mul_f32 v[106:107], v[8:9], v[106:107]
	v_pk_mul_f32 v[108:109], v[10:11], v[108:109]
	global_store_dwordx4 v17, v[106:109], s[20:21] offset:2048 nt
	v_lshlrev_b32_e32 v110, 16, v82
	v_and_b32_e32 v111, 0xffff0000, v82
	v_lshlrev_b32_e32 v112, 16, v83
	v_and_b32_e32 v113, 0xffff0000, v83
	v_pk_mul_f32 v[110:111], v[104:105], v[110:111] op_sel_hi:[0,1]
	v_pk_mul_f32 v[112:113], v[104:105], v[112:113] op_sel_hi:[0,1]
	v_pk_mul_f32 v[110:111], v[12:13], v[110:111]
	v_pk_mul_f32 v[112:113], v[14:15], v[112:113]
	global_store_dwordx4 v17, v[110:113], s[20:21] offset:3072 nt
	s_mul_i32 s14, s9, 2
	s_add_u32 s14, s14, s8
	s_lshl_b32 s15, s14, 12
	s_add_u32 s20, s60, s15
	s_addc_u32 s21, s61, 0
	v_cvt_f32_u32_e32 v104, v85
	v_cvt_f32_u32_e32 v105, v84
	v_fma_f32 v104, v104, v20, v105
	v_fmaak_f32 v104, v104, v21, 0x358637bd
	v_rsq_f32_e32 v104, v104
	v_lshlrev_b32_e32 v106, 16, v86
	v_and_b32_e32 v107, 0xffff0000, v86
	v_lshlrev_b32_e32 v108, 16, v87
	v_and_b32_e32 v109, 0xffff0000, v87
	v_pk_mul_f32 v[106:107], v[104:105], v[106:107] op_sel_hi:[0,1]
	v_pk_mul_f32 v[108:109], v[104:105], v[108:109] op_sel_hi:[0,1]
	v_pk_mul_f32 v[106:107], v[0:1], v[106:107]
	v_pk_mul_f32 v[108:109], v[2:3], v[108:109]
	global_store_dwordx4 v17, v[106:109], s[20:21] nt
	v_lshlrev_b32_e32 v110, 16, v88
	v_and_b32_e32 v111, 0xffff0000, v88
	v_lshlrev_b32_e32 v112, 16, v89
	v_and_b32_e32 v113, 0xffff0000, v89
	v_pk_mul_f32 v[110:111], v[104:105], v[110:111] op_sel_hi:[0,1]
	v_pk_mul_f32 v[112:113], v[104:105], v[112:113] op_sel_hi:[0,1]
	v_pk_mul_f32 v[110:111], v[4:5], v[110:111]
	v_pk_mul_f32 v[112:113], v[6:7], v[112:113]
	global_store_dwordx4 v17, v[110:113], s[20:21] offset:1024 nt
	v_lshlrev_b32_e32 v106, 16, v90
	v_and_b32_e32 v107, 0xffff0000, v90
	v_lshlrev_b32_e32 v108, 16, v91
	v_and_b32_e32 v109, 0xffff0000, v91
	v_pk_mul_f32 v[106:107], v[104:105], v[106:107] op_sel_hi:[0,1]
	v_pk_mul_f32 v[108:109], v[104:105], v[108:109] op_sel_hi:[0,1]
	v_pk_mul_f32 v[106:107], v[8:9], v[106:107]
	v_pk_mul_f32 v[108:109], v[10:11], v[108:109]
	global_store_dwordx4 v17, v[106:109], s[20:21] offset:2048 nt
	v_lshlrev_b32_e32 v110, 16, v92
	v_and_b32_e32 v111, 0xffff0000, v92
	v_lshlrev_b32_e32 v112, 16, v93
	v_and_b32_e32 v113, 0xffff0000, v93
	v_pk_mul_f32 v[110:111], v[104:105], v[110:111] op_sel_hi:[0,1]
	v_pk_mul_f32 v[112:113], v[104:105], v[112:113] op_sel_hi:[0,1]
	v_pk_mul_f32 v[110:111], v[12:13], v[110:111]
	v_pk_mul_f32 v[112:113], v[14:15], v[112:113]
	global_store_dwordx4 v17, v[110:113], s[20:21] offset:3072 nt
	s_mul_i32 s14, s9, 3
	s_add_u32 s14, s14, s8
	s_lshl_b32 s15, s14, 12
	s_add_u32 s20, s60, s15
	s_addc_u32 s21, s61, 0
	v_cvt_f32_u32_e32 v104, v95
	v_cvt_f32_u32_e32 v105, v94
	v_fma_f32 v104, v104, v20, v105
	v_fmaak_f32 v104, v104, v21, 0x358637bd
	v_rsq_f32_e32 v104, v104
	v_lshlrev_b32_e32 v106, 16, v96
	v_and_b32_e32 v107, 0xffff0000, v96
	v_lshlrev_b32_e32 v108, 16, v97
	v_and_b32_e32 v109, 0xffff0000, v97
	v_pk_mul_f32 v[106:107], v[104:105], v[106:107] op_sel_hi:[0,1]
	v_pk_mul_f32 v[108:109], v[104:105], v[108:109] op_sel_hi:[0,1]
	v_pk_mul_f32 v[106:107], v[0:1], v[106:107]
	v_pk_mul_f32 v[108:109], v[2:3], v[108:109]
	global_store_dwordx4 v17, v[106:109], s[20:21] nt
	v_lshlrev_b32_e32 v110, 16, v98
	v_and_b32_e32 v111, 0xffff0000, v98
	v_lshlrev_b32_e32 v112, 16, v99
	v_and_b32_e32 v113, 0xffff0000, v99
	v_pk_mul_f32 v[110:111], v[104:105], v[110:111] op_sel_hi:[0,1]
	v_pk_mul_f32 v[112:113], v[104:105], v[112:113] op_sel_hi:[0,1]
	v_pk_mul_f32 v[110:111], v[4:5], v[110:111]
	v_pk_mul_f32 v[112:113], v[6:7], v[112:113]
	global_store_dwordx4 v17, v[110:113], s[20:21] offset:1024 nt
	v_lshlrev_b32_e32 v106, 16, v100
	v_and_b32_e32 v107, 0xffff0000, v100
	v_lshlrev_b32_e32 v108, 16, v101
	v_and_b32_e32 v109, 0xffff0000, v101
	v_pk_mul_f32 v[106:107], v[104:105], v[106:107] op_sel_hi:[0,1]
	v_pk_mul_f32 v[108:109], v[104:105], v[108:109] op_sel_hi:[0,1]
	v_pk_mul_f32 v[106:107], v[8:9], v[106:107]
	v_pk_mul_f32 v[108:109], v[10:11], v[108:109]
	global_store_dwordx4 v17, v[106:109], s[20:21] offset:2048 nt
	v_lshlrev_b32_e32 v110, 16, v102
	v_and_b32_e32 v111, 0xffff0000, v102
	v_lshlrev_b32_e32 v112, 16, v103
	v_and_b32_e32 v113, 0xffff0000, v103
	v_pk_mul_f32 v[110:111], v[104:105], v[110:111] op_sel_hi:[0,1]
	v_pk_mul_f32 v[112:113], v[104:105], v[112:113] op_sel_hi:[0,1]
	v_pk_mul_f32 v[110:111], v[12:13], v[110:111]
	v_pk_mul_f32 v[112:113], v[14:15], v[112:113]
	global_store_dwordx4 v17, v[110:113], s[20:21] offset:3072 nt
	s_add_u32 s8, s8, s23
	s_branch .Lfin_loop
.Lfin_tail_a:
	s_waitcnt vmcnt(0)
	s_mov_b32 s14, s8
	s_cmp_lt_u32 s14, 0x8000
	s_cbranch_scc0 .Lfin_skip_1
	s_lshl_b32 s15, s14, 12
	s_add_u32 s20, s60, s15
	s_addc_u32 s21, s61, 0
	v_cvt_f32_u32_e32 v104, v25
	v_cvt_f32_u32_e32 v105, v24
	v_fma_f32 v104, v104, v20, v105
	v_fmaak_f32 v104, v104, v21, 0x358637bd
	v_rsq_f32_e32 v104, v104
	v_lshlrev_b32_e32 v106, 16, v26
	v_and_b32_e32 v107, 0xffff0000, v26
	v_lshlrev_b32_e32 v108, 16, v27
	v_and_b32_e32 v109, 0xffff0000, v27
	v_pk_mul_f32 v[106:107], v[104:105], v[106:107] op_sel_hi:[0,1]
	v_pk_mul_f32 v[108:109], v[104:105], v[108:109] op_sel_hi:[0,1]
	v_pk_mul_f32 v[106:107], v[0:1], v[106:107]
	v_pk_mul_f32 v[108:109], v[2:3], v[108:109]
	global_store_dwordx4 v17, v[106:109], s[20:21] nt
	v_lshlrev_b32_e32 v110, 16, v28
	v_and_b32_e32 v111, 0xffff0000, v28
	v_lshlrev_b32_e32 v112, 16, v29
	v_and_b32_e32 v113, 0xffff0000, v29
	v_pk_mul_f32 v[110:111], v[104:105], v[110:111] op_sel_hi:[0,1]
	v_pk_mul_f32 v[112:113], v[104:105], v[112:113] op_sel_hi:[0,1]
	v_pk_mul_f32 v[110:111], v[4:5], v[110:111]
	v_pk_mul_f32 v[112:113], v[6:7], v[112:113]
	global_store_dwordx4 v17, v[110:113], s[20:21] offset:1024 nt
	v_lshlrev_b32_e32 v106, 16, v30
	v_and_b32_e32 v107, 0xffff0000, v30
	v_lshlrev_b32_e32 v108, 16, v31
	v_and_b32_e32 v109, 0xffff0000, v31
	v_pk_mul_f32 v[106:107], v[104:105], v[106:107] op_sel_hi:[0,1]
	v_pk_mul_f32 v[108:109], v[104:105], v[108:109] op_sel_hi:[0,1]
	v_pk_mul_f32 v[106:107], v[8:9], v[106:107]
	v_pk_mul_f32 v[108:109], v[10:11], v[108:109]
	global_store_dwordx4 v17, v[106:109], s[20:21] offset:2048 nt
	v_lshlrev_b32_e32 v110, 16, v32
	v_and_b32_e32 v111, 0xffff0000, v32
	v_lshlrev_b32_e32 v112, 16, v33
	v_and_b32_e32 v113, 0xffff0000, v33
	v_pk_mul_f32 v[110:111], v[104:105], v[110:111] op_sel_hi:[0,1]
	v_pk_mul_f32 v[112:113], v[104:105], v[112:113] op_sel_hi:[0,1]
	v_pk_mul_f32 v[110:111], v[12:13], v[110:111]
	v_pk_mul_f32 v[112:113], v[14:15], v[112:113]
	global_store_dwordx4 v17, v[110:113], s[20:21] offset:3072 nt
.Lfin_skip_1:
	s_mul_i32 s14, s9, 1
	s_add_u32 s14, s14, s8
	s_cmp_lt_u32 s14, 0x8000
	s_cbranch_scc0 .Lfin_skip_2
	s_lshl_b32 s15, s14, 12
	s_add_u32 s20, s60, s15
	s_addc_u32 s21, s61, 0
	v_cvt_f32_u32_e32 v104, v35
	v_cvt_f32_u32_e32 v105, v34
	v_fma_f32 v104, v104, v20, v105
	v_fmaak_f32 v104, v104, v21, 0x358637bd
	v_rsq_f32_e32 v104, v104
	v_lshlrev_b32_e32 v106, 16, v36
	v_and_b32_e32 v107, 0xffff0000, v36
	v_lshlrev_b32_e32 v108, 16, v37
	v_and_b32_e32 v109, 0xffff0000, v37
	v_pk_mul_f32 v[106:107], v[104:105], v[106:107] op_sel_hi:[0,1]
	v_pk_mul_f32 v[108:109], v[104:105], v[108:109] op_sel_hi:[0,1]
	v_pk_mul_f32 v[106:107], v[0:1], v[106:107]
	v_pk_mul_f32 v[108:109], v[2:3], v[108:109]
	global_store_dwordx4 v17, v[106:109], s[20:21] nt
	v_lshlrev_b32_e32 v110, 16, v38
	v_and_b32_e32 v111, 0xffff0000, v38
	v_lshlrev_b32_e32 v112, 16, v39
	v_and_b32_e32 v113, 0xffff0000, v39
	v_pk_mul_f32 v[110:111], v[104:105], v[110:111] op_sel_hi:[0,1]
	v_pk_mul_f32 v[112:113], v[104:105], v[112:113] op_sel_hi:[0,1]
	v_pk_mul_f32 v[110:111], v[4:5], v[110:111]
	v_pk_mul_f32 v[112:113], v[6:7], v[112:113]
	global_store_dwordx4 v17, v[110:113], s[20:21] offset:1024 nt
	v_lshlrev_b32_e32 v106, 16, v40
	v_and_b32_e32 v107, 0xffff0000, v40
	v_lshlrev_b32_e32 v108, 16, v41
	v_and_b32_e32 v109, 0xffff0000, v41
	v_pk_mul_f32 v[106:107], v[104:105], v[106:107] op_sel_hi:[0,1]
	v_pk_mul_f32 v[108:109], v[104:105], v[108:109] op_sel_hi:[0,1]
	v_pk_mul_f32 v[106:107], v[8:9], v[106:107]
	v_pk_mul_f32 v[108:109], v[10:11], v[108:109]
	global_store_dwordx4 v17, v[106:109], s[20:21] offset:2048 nt
	v_lshlrev_b32_e32 v110, 16, v42
	v_and_b32_e32 v111, 0xffff0000, v42
	v_lshlrev_b32_e32 v112, 16, v43
	v_and_b32_e32 v113, 0xffff0000, v43
	v_pk_mul_f32 v[110:111], v[104:105], v[110:111] op_sel_hi:[0,1]
	v_pk_mul_f32 v[112:113], v[104:105], v[112:113] op_sel_hi:[0,1]
	v_pk_mul_f32 v[110:111], v[12:13], v[110:111]
	v_pk_mul_f32 v[112:113], v[14:15], v[112:113]
	global_store_dwordx4 v17, v[110:113], s[20:21] offset:3072 nt
.Lfin_skip_2:
	s_mul_i32 s14, s9, 2
	s_add_u32 s14, s14, s8
	s_cmp_lt_u32 s14, 0x8000
	s_cbranch_scc0 .Lfin_skip_3
	s_lshl_b32 s15, s14, 12
	s_add_u32 s20, s60, s15
	s_addc_u32 s21, s61, 0
	v_cvt_f32_u32_e32 v104, v45
	v_cvt_f32_u32_e32 v105, v44
	v_fma_f32 v104, v104, v20, v105
	v_fmaak_f32 v104, v104, v21, 0x358637bd
	v_rsq_f32_e32 v104, v104
	v_lshlrev_b32_e32 v106, 16, v46
	v_and_b32_e32 v107, 0xffff0000, v46
	v_lshlrev_b32_e32 v108, 16, v47
	v_and_b32_e32 v109, 0xffff0000, v47
	v_pk_mul_f32 v[106:107], v[104:105], v[106:107] op_sel_hi:[0,1]
	v_pk_mul_f32 v[108:109], v[104:105], v[108:109] op_sel_hi:[0,1]
	v_pk_mul_f32 v[106:107], v[0:1], v[106:107]
	v_pk_mul_f32 v[108:109], v[2:3], v[108:109]
	global_store_dwordx4 v17, v[106:109], s[20:21] nt
	v_lshlrev_b32_e32 v110, 16, v48
	v_and_b32_e32 v111, 0xffff0000, v48
	v_lshlrev_b32_e32 v112, 16, v49
	v_and_b32_e32 v113, 0xffff0000, v49
	v_pk_mul_f32 v[110:111], v[104:105], v[110:111] op_sel_hi:[0,1]
	v_pk_mul_f32 v[112:113], v[104:105], v[112:113] op_sel_hi:[0,1]
	v_pk_mul_f32 v[110:111], v[4:5], v[110:111]
	v_pk_mul_f32 v[112:113], v[6:7], v[112:113]
	global_store_dwordx4 v17, v[110:113], s[20:21] offset:1024 nt
	v_lshlrev_b32_e32 v106, 16, v50
	v_and_b32_e32 v107, 0xffff0000, v50
	v_lshlrev_b32_e32 v108, 16, v51
	v_and_b32_e32 v109, 0xffff0000, v51
	v_pk_mul_f32 v[106:107], v[104:105], v[106:107] op_sel_hi:[0,1]
	v_pk_mul_f32 v[108:109], v[104:105], v[108:109] op_sel_hi:[0,1]
	v_pk_mul_f32 v[106:107], v[8:9], v[106:107]
	v_pk_mul_f32 v[108:109], v[10:11], v[108:109]
	global_store_dwordx4 v17, v[106:109], s[20:21] offset:2048 nt
	v_lshlrev_b32_e32 v110, 16, v52
	v_and_b32_e32 v111, 0xffff0000, v52
	v_lshlrev_b32_e32 v112, 16, v53
	v_and_b32_e32 v113, 0xffff0000, v53
	v_pk_mul_f32 v[110:111], v[104:105], v[110:111] op_sel_hi:[0,1]
	v_pk_mul_f32 v[112:113], v[104:105], v[112:113] op_sel_hi:[0,1]
	v_pk_mul_f32 v[110:111], v[12:13], v[110:111]
	v_pk_mul_f32 v[112:113], v[14:15], v[112:113]
	global_store_dwordx4 v17, v[110:113], s[20:21] offset:3072 nt
.Lfin_skip_3:
	s_mul_i32 s14, s9, 3
	s_add_u32 s14, s14, s8
	s_cmp_lt_u32 s14, 0x8000
	s_cbranch_scc0 .Lfin_skip_4
	s_lshl_b32 s15, s14, 12
	s_add_u32 s20, s60, s15
	s_addc_u32 s21, s61, 0
	v_cvt_f32_u32_e32 v104, v55
	v_cvt_f32_u32_e32 v105, v54
	v_fma_f32 v104, v104, v20, v105
	v_fmaak_f32 v104, v104, v21, 0x358637bd
	v_rsq_f32_e32 v104, v104
	v_lshlrev_b32_e32 v106, 16, v56
	v_and_b32_e32 v107, 0xffff0000, v56
	v_lshlrev_b32_e32 v108, 16, v57
	v_and_b32_e32 v109, 0xffff0000, v57
	v_pk_mul_f32 v[106:107], v[104:105], v[106:107] op_sel_hi:[0,1]
	v_pk_mul_f32 v[108:109], v[104:105], v[108:109] op_sel_hi:[0,1]
	v_pk_mul_f32 v[106:107], v[0:1], v[106:107]
	v_pk_mul_f32 v[108:109], v[2:3], v[108:109]
	global_store_dwordx4 v17, v[106:109], s[20:21] nt
	v_lshlrev_b32_e32 v110, 16, v58
	v_and_b32_e32 v111, 0xffff0000, v58
	v_lshlrev_b32_e32 v112, 16, v59
	v_and_b32_e32 v113, 0xffff0000, v59
	v_pk_mul_f32 v[110:111], v[104:105], v[110:111] op_sel_hi:[0,1]
	v_pk_mul_f32 v[112:113], v[104:105], v[112:113] op_sel_hi:[0,1]
	v_pk_mul_f32 v[110:111], v[4:5], v[110:111]
	v_pk_mul_f32 v[112:113], v[6:7], v[112:113]
	global_store_dwordx4 v17, v[110:113], s[20:21] offset:1024 nt
	v_lshlrev_b32_e32 v106, 16, v60
	v_and_b32_e32 v107, 0xffff0000, v60
	v_lshlrev_b32_e32 v108, 16, v61
	v_and_b32_e32 v109, 0xffff0000, v61
	v_pk_mul_f32 v[106:107], v[104:105], v[106:107] op_sel_hi:[0,1]
	v_pk_mul_f32 v[108:109], v[104:105], v[108:109] op_sel_hi:[0,1]
	v_pk_mul_f32 v[106:107], v[8:9], v[106:107]
	v_pk_mul_f32 v[108:109], v[10:11], v[108:109]
	global_store_dwordx4 v17, v[106:109], s[20:21] offset:2048 nt
	v_lshlrev_b32_e32 v110, 16, v62
	v_and_b32_e32 v111, 0xffff0000, v62
	v_lshlrev_b32_e32 v112, 16, v63
	v_and_b32_e32 v113, 0xffff0000, v63
	v_pk_mul_f32 v[110:111], v[104:105], v[110:111] op_sel_hi:[0,1]
	v_pk_mul_f32 v[112:113], v[104:105], v[112:113] op_sel_hi:[0,1]
	v_pk_mul_f32 v[110:111], v[12:13], v[110:111]
	v_pk_mul_f32 v[112:113], v[14:15], v[112:113]
	global_store_dwordx4 v17, v[110:113], s[20:21] offset:3072 nt
.Lfin_skip_4:
	s_lshl_b32 s23, s9, 2
	s_add_u32 s8, s8, s23
	s_branch .Lfin_slow
.Lfin_tail_b:
	s_waitcnt vmcnt(0)
	s_mov_b32 s14, s8
	s_cmp_lt_u32 s14, 0x8000
	s_cbranch_scc0 .Lfin_skip_5
	s_lshl_b32 s15, s14, 12
	s_add_u32 s20, s60, s15
	s_addc_u32 s21, s61, 0
	v_cvt_f32_u32_e32 v104, v65
	v_cvt_f32_u32_e32 v105, v64
	v_fma_f32 v104, v104, v20, v105
	v_fmaak_f32 v104, v104, v21, 0x358637bd
	v_rsq_f32_e32 v104, v104
	v_lshlrev_b32_e32 v106, 16, v66
	v_and_b32_e32 v107, 0xffff0000, v66
	v_lshlrev_b32_e32 v108, 16, v67
	v_and_b32_e32 v109, 0xffff0000, v67
	v_pk_mul_f32 v[106:107], v[104:105], v[106:107] op_sel_hi:[0,1]
	v_pk_mul_f32 v[108:109], v[104:105], v[108:109] op_sel_hi:[0,1]
	v_pk_mul_f32 v[106:107], v[0:1], v[106:107]
	v_pk_mul_f32 v[108:109], v[2:3], v[108:109]
	global_store_dwordx4 v17, v[106:109], s[20:21] nt
	v_lshlrev_b32_e32 v110, 16, v68
	v_and_b32_e32 v111, 0xffff0000, v68
	v_lshlrev_b32_e32 v112, 16, v69
	v_and_b32_e32 v113, 0xffff0000, v69
	v_pk_mul_f32 v[110:111], v[104:105], v[110:111] op_sel_hi:[0,1]
	v_pk_mul_f32 v[112:113], v[104:105], v[112:113] op_sel_hi:[0,1]
	v_pk_mul_f32 v[110:111], v[4:5], v[110:111]
	v_pk_mul_f32 v[112:113], v[6:7], v[112:113]
	global_store_dwordx4 v17, v[110:113], s[20:21] offset:1024 nt
	v_lshlrev_b32_e32 v106, 16, v70
	v_and_b32_e32 v107, 0xffff0000, v70
	v_lshlrev_b32_e32 v108, 16, v71
	v_and_b32_e32 v109, 0xffff0000, v71
	v_pk_mul_f32 v[106:107], v[104:105], v[106:107] op_sel_hi:[0,1]
	v_pk_mul_f32 v[108:109], v[104:105], v[108:109] op_sel_hi:[0,1]
	v_pk_mul_f32 v[106:107], v[8:9], v[106:107]
	v_pk_mul_f32 v[108:109], v[10:11], v[108:109]
	global_store_dwordx4 v17, v[106:109], s[20:21] offset:2048 nt
	v_lshlrev_b32_e32 v110, 16, v72
	v_and_b32_e32 v111, 0xffff0000, v72
	v_lshlrev_b32_e32 v112, 16, v73
	v_and_b32_e32 v113, 0xffff0000, v73
	v_pk_mul_f32 v[110:111], v[104:105], v[110:111] op_sel_hi:[0,1]
	v_pk_mul_f32 v[112:113], v[104:105], v[112:113] op_sel_hi:[0,1]
	v_pk_mul_f32 v[110:111], v[12:13], v[110:111]
	v_pk_mul_f32 v[112:113], v[14:15], v[112:113]
	global_store_dwordx4 v17, v[110:113], s[20:21] offset:3072 nt
.Lfin_skip_5:
	s_mul_i32 s14, s9, 1
	s_add_u32 s14, s14, s8
	s_cmp_lt_u32 s14, 0x8000
	s_cbranch_scc0 .Lfin_skip_6
	s_lshl_b32 s15, s14, 12
	s_add_u32 s20, s60, s15
	s_addc_u32 s21, s61, 0
	v_cvt_f32_u32_e32 v104, v75
	v_cvt_f32_u32_e32 v105, v74
	v_fma_f32 v104, v104, v20, v105
	v_fmaak_f32 v104, v104, v21, 0x358637bd
	v_rsq_f32_e32 v104, v104
	v_lshlrev_b32_e32 v106, 16, v76
	v_and_b32_e32 v107, 0xffff0000, v76
	v_lshlrev_b32_e32 v108, 16, v77
	v_and_b32_e32 v109, 0xffff0000, v77
	v_pk_mul_f32 v[106:107], v[104:105], v[106:107] op_sel_hi:[0,1]
	v_pk_mul_f32 v[108:109], v[104:105], v[108:109] op_sel_hi:[0,1]
	v_pk_mul_f32 v[106:107], v[0:1], v[106:107]
	v_pk_mul_f32 v[108:109], v[2:3], v[108:109]
	global_store_dwordx4 v17, v[106:109], s[20:21] nt
	v_lshlrev_b32_e32 v110, 16, v78
	v_and_b32_e32 v111, 0xffff0000, v78
	v_lshlrev_b32_e32 v112, 16, v79
	v_and_b32_e32 v113, 0xffff0000, v79
	v_pk_mul_f32 v[110:111], v[104:105], v[110:111] op_sel_hi:[0,1]
	v_pk_mul_f32 v[112:113], v[104:105], v[112:113] op_sel_hi:[0,1]
	v_pk_mul_f32 v[110:111], v[4:5], v[110:111]
	v_pk_mul_f32 v[112:113], v[6:7], v[112:113]
	global_store_dwordx4 v17, v[110:113], s[20:21] offset:1024 nt
	v_lshlrev_b32_e32 v106, 16, v80
	v_and_b32_e32 v107, 0xffff0000, v80
	v_lshlrev_b32_e32 v108, 16, v81
	v_and_b32_e32 v109, 0xffff0000, v81
	v_pk_mul_f32 v[106:107], v[104:105], v[106:107] op_sel_hi:[0,1]
	v_pk_mul_f32 v[108:109], v[104:105], v[108:109] op_sel_hi:[0,1]
	v_pk_mul_f32 v[106:107], v[8:9], v[106:107]
	v_pk_mul_f32 v[108:109], v[10:11], v[108:109]
	global_store_dwordx4 v17, v[106:109], s[20:21] offset:2048 nt
	v_lshlrev_b32_e32 v110, 16, v82
	v_and_b32_e32 v111, 0xffff0000, v82
	v_lshlrev_b32_e32 v112, 16, v83
	v_and_b32_e32 v113, 0xffff0000, v83
	v_pk_mul_f32 v[110:111], v[104:105], v[110:111] op_sel_hi:[0,1]
	v_pk_mul_f32 v[112:113], v[104:105], v[112:113] op_sel_hi:[0,1]
	v_pk_mul_f32 v[110:111], v[12:13], v[110:111]
	v_pk_mul_f32 v[112:113], v[14:15], v[112:113]
	global_store_dwordx4 v17, v[110:113], s[20:21] offset:3072 nt
.Lfin_skip_6:
	s_mul_i32 s14, s9, 2
	s_add_u32 s14, s14, s8
	s_cmp_lt_u32 s14, 0x8000
	s_cbranch_scc0 .Lfin_skip_7
	s_lshl_b32 s15, s14, 12
	s_add_u32 s20, s60, s15
	s_addc_u32 s21, s61, 0
	v_cvt_f32_u32_e32 v104, v85
	v_cvt_f32_u32_e32 v105, v84
	v_fma_f32 v104, v104, v20, v105
	v_fmaak_f32 v104, v104, v21, 0x358637bd
	v_rsq_f32_e32 v104, v104
	v_lshlrev_b32_e32 v106, 16, v86
	v_and_b32_e32 v107, 0xffff0000, v86
	v_lshlrev_b32_e32 v108, 16, v87
	v_and_b32_e32 v109, 0xffff0000, v87
	v_pk_mul_f32 v[106:107], v[104:105], v[106:107] op_sel_hi:[0,1]
	v_pk_mul_f32 v[108:109], v[104:105], v[108:109] op_sel_hi:[0,1]
	v_pk_mul_f32 v[106:107], v[0:1], v[106:107]
	v_pk_mul_f32 v[108:109], v[2:3], v[108:109]
	global_store_dwordx4 v17, v[106:109], s[20:21] nt
	v_lshlrev_b32_e32 v110, 16, v88
	v_and_b32_e32 v111, 0xffff0000, v88
	v_lshlrev_b32_e32 v112, 16, v89
	v_and_b32_e32 v113, 0xffff0000, v89
	v_pk_mul_f32 v[110:111], v[104:105], v[110:111] op_sel_hi:[0,1]
	v_pk_mul_f32 v[112:113], v[104:105], v[112:113] op_sel_hi:[0,1]
	v_pk_mul_f32 v[110:111], v[4:5], v[110:111]
	v_pk_mul_f32 v[112:113], v[6:7], v[112:113]
	global_store_dwordx4 v17, v[110:113], s[20:21] offset:1024 nt
	v_lshlrev_b32_e32 v106, 16, v90
	v_and_b32_e32 v107, 0xffff0000, v90
	v_lshlrev_b32_e32 v108, 16, v91
	v_and_b32_e32 v109, 0xffff0000, v91
	v_pk_mul_f32 v[106:107], v[104:105], v[106:107] op_sel_hi:[0,1]
	v_pk_mul_f32 v[108:109], v[104:105], v[108:109] op_sel_hi:[0,1]
	v_pk_mul_f32 v[106:107], v[8:9], v[106:107]
	v_pk_mul_f32 v[108:109], v[10:11], v[108:109]
	global_store_dwordx4 v17, v[106:109], s[20:21] offset:2048 nt
	v_lshlrev_b32_e32 v110, 16, v92
	v_and_b32_e32 v111, 0xffff0000, v92
	v_lshlrev_b32_e32 v112, 16, v93
	v_and_b32_e32 v113, 0xffff0000, v93
	v_pk_mul_f32 v[110:111], v[104:105], v[110:111] op_sel_hi:[0,1]
	v_pk_mul_f32 v[112:113], v[104:105], v[112:113] op_sel_hi:[0,1]
	v_pk_mul_f32 v[110:111], v[12:13], v[110:111]
	v_pk_mul_f32 v[112:113], v[14:15], v[112:113]
	global_store_dwordx4 v17, v[110:113], s[20:21] offset:3072 nt
.Lfin_skip_7:
	s_mul_i32 s14, s9, 3
	s_add_u32 s14, s14, s8
	s_cmp_lt_u32 s14, 0x8000
	s_cbranch_scc0 .Lfin_skip_8
	s_lshl_b32 s15, s14, 12
	s_add_u32 s20, s60, s15
	s_addc_u32 s21, s61, 0
	v_cvt_f32_u32_e32 v104, v95
	v_cvt_f32_u32_e32 v105, v94
	v_fma_f32 v104, v104, v20, v105
	v_fmaak_f32 v104, v104, v21, 0x358637bd
	v_rsq_f32_e32 v104, v104
	v_lshlrev_b32_e32 v106, 16, v96
	v_and_b32_e32 v107, 0xffff0000, v96
	v_lshlrev_b32_e32 v108, 16, v97
	v_and_b32_e32 v109, 0xffff0000, v97
	v_pk_mul_f32 v[106:107], v[104:105], v[106:107] op_sel_hi:[0,1]
	v_pk_mul_f32 v[108:109], v[104:105], v[108:109] op_sel_hi:[0,1]
	v_pk_mul_f32 v[106:107], v[0:1], v[106:107]
	v_pk_mul_f32 v[108:109], v[2:3], v[108:109]
	global_store_dwordx4 v17, v[106:109], s[20:21] nt
	v_lshlrev_b32_e32 v110, 16, v98
	v_and_b32_e32 v111, 0xffff0000, v98
	v_lshlrev_b32_e32 v112, 16, v99
	v_and_b32_e32 v113, 0xffff0000, v99
	v_pk_mul_f32 v[110:111], v[104:105], v[110:111] op_sel_hi:[0,1]
	v_pk_mul_f32 v[112:113], v[104:105], v[112:113] op_sel_hi:[0,1]
	v_pk_mul_f32 v[110:111], v[4:5], v[110:111]
	v_pk_mul_f32 v[112:113], v[6:7], v[112:113]
	global_store_dwordx4 v17, v[110:113], s[20:21] offset:1024 nt
	v_lshlrev_b32_e32 v106, 16, v100
	v_and_b32_e32 v107, 0xffff0000, v100
	v_lshlrev_b32_e32 v108, 16, v101
	v_and_b32_e32 v109, 0xffff0000, v101
	v_pk_mul_f32 v[106:107], v[104:105], v[106:107] op_sel_hi:[0,1]
	v_pk_mul_f32 v[108:109], v[104:105], v[108:109] op_sel_hi:[0,1]
	v_pk_mul_f32 v[106:107], v[8:9], v[106:107]
	v_pk_mul_f32 v[108:109], v[10:11], v[108:109]
	global_store_dwordx4 v17, v[106:109], s[20:21] offset:2048 nt
	v_lshlrev_b32_e32 v110, 16, v102
	v_and_b32_e32 v111, 0xffff0000, v102
	v_lshlrev_b32_e32 v112, 16, v103
	v_and_b32_e32 v113, 0xffff0000, v103
	v_pk_mul_f32 v[110:111], v[104:105], v[110:111] op_sel_hi:[0,1]
	v_pk_mul_f32 v[112:113], v[104:105], v[112:113] op_sel_hi:[0,1]
	v_pk_mul_f32 v[110:111], v[12:13], v[110:111]
	v_pk_mul_f32 v[112:113], v[14:15], v[112:113]
	global_store_dwordx4 v17, v[110:113], s[20:21] offset:3072 nt
.Lfin_skip_8:
	s_lshl_b32 s23, s9, 2
	s_add_u32 s8, s8, s23
.Lfin_slow:
	s_cmp_lt_u32 s8, 0x8000
	s_cbranch_scc0 .LBB0_969
	s_min_u32 s14, s8, 0x7fff
	s_lshl_b32 s15, s14, 3
	s_add_u32 s16, s12, s15
	s_addc_u32 s17, s13, 0
	s_lshl_b32 s15, s14, 11
	s_add_u32 s18, s10, s15
	s_addc_u32 s19, s11, 0
	global_load_dwordx2 v[24:25], v19, s[16:17]
	global_load_dwordx2 v[26:27], v16, s[18:19] nt
	global_load_dwordx2 v[28:29], v16, s[18:19] offset:512 nt
	global_load_dwordx2 v[30:31], v16, s[18:19] offset:1024 nt
	global_load_dwordx2 v[32:33], v16, s[18:19] offset:1536 nt
	s_mul_i32 s14, s9, 1
	s_add_u32 s14, s14, s8
	s_min_u32 s14, s14, 0x7fff
	s_lshl_b32 s15, s14, 3
	s_add_u32 s16, s12, s15
	s_addc_u32 s17, s13, 0
	s_lshl_b32 s15, s14, 11
	s_add_u32 s18, s10, s15
	s_addc_u32 s19, s11, 0
	global_load_dwordx2 v[34:35], v19, s[16:17]
	global_load_dwordx2 v[36:37], v16, s[18:19] nt
	global_load_dwordx2 v[38:39], v16, s[18:19] offset:512 nt
	global_load_dwordx2 v[40:41], v16, s[18:19] offset:1024 nt
	global_load_dwordx2 v[42:43], v16, s[18:19] offset:1536 nt
	s_mul_i32 s14, s9, 2
	s_add_u32 s14, s14, s8
	s_min_u32 s14, s14, 0x7fff
	s_lshl_b32 s15, s14, 3
	s_add_u32 s16, s12, s15
	s_addc_u32 s17, s13, 0
	s_lshl_b32 s15, s14, 11
	s_add_u32 s18, s10, s15
	s_addc_u32 s19, s11, 0
	global_load_dwordx2 v[44:45], v19, s[16:17]
	global_load_dwordx2 v[46:47], v16, s[18:19] nt
	global_load_dwordx2 v[48:49], v16, s[18:19] offset:512 nt
	global_load_dwordx2 v[50:51], v16, s[18:19] offset:1024 nt
	global_load_dwordx2 v[52:53], v16, s[18:19] offset:1536 nt
	s_mul_i32 s14, s9, 3
	s_add_u32 s14, s14, s8
	s_min_u32 s14, s14, 0x7fff
	s_lshl_b32 s15, s14, 3
	s_add_u32 s16, s12, s15
	s_addc_u32 s17, s13, 0
	s_lshl_b32 s15, s14, 11
	s_add_u32 s18, s10, s15
	s_addc_u32 s19, s11, 0
	global_load_dwordx2 v[54:55], v19, s[16:17]
	global_load_dwordx2 v[56:57], v16, s[18:19] nt
	global_load_dwordx2 v[58:59], v16, s[18:19] offset:512 nt
	global_load_dwordx2 v[60:61], v16, s[18:19] offset:1024 nt
	global_load_dwordx2 v[62:63], v16, s[18:19] offset:1536 nt
	s_branch .Lfin_tail_a

	.amdhsa_kernel _Z10s5yoco_fwd4Ptrs
		.amdhsa_group_segment_fixed_size 0
		.amdhsa_private_segment_fixed_size 0
		.amdhsa_kernarg_size 432
		.amdhsa_user_sgpr_count 2
		.amdhsa_user_sgpr_dispatch_ptr 0
		.amdhsa_user_sgpr_queue_ptr 0
		.amdhsa_user_sgpr_kernarg_segment_ptr 1
		.amdhsa_user_sgpr_dispatch_id 0
		.amdhsa_user_sgpr_kernarg_preload_length 0
		.amdhsa_user_sgpr_kernarg_preload_offset 0
		.amdhsa_user_sgpr_private_segment_size 0
		.amdhsa_uses_dynamic_stack 0
		.amdhsa_enable_private_segment 0
		.amdhsa_system_sgpr_workgroup_id_x 1
		.amdhsa_system_sgpr_workgroup_id_y 0
		.amdhsa_system_sgpr_workgroup_id_z 0
		.amdhsa_system_sgpr_workgroup_info 0
		.amdhsa_system_vgpr_workitem_id 2
		.amdhsa_next_free_vgpr 249
		.amdhsa_next_free_sgpr 102
		.amdhsa_accum_offset 252
		.amdhsa_reserve_vcc 1
		.amdhsa_float_round_mode_32 0
		.amdhsa_float_round_mode_16_64 0
		.amdhsa_float_denorm_mode_32 3
		.amdhsa_float_denorm_mode_16_64 3
		.amdhsa_dx10_clamp 1
		.amdhsa_ieee_mode 1
		.amdhsa_fp16_overflow 0
		.amdhsa_tg_split 0
		.amdhsa_exception_fp_ieee_invalid_op 0
		.amdhsa_exception_fp_denorm_src 0
		.amdhsa_exception_fp_ieee_div_zero 0
		.amdhsa_exception_fp_ieee_overflow 0
		.amdhsa_exception_fp_ieee_underflow 0
		.amdhsa_exception_fp_ieee_inexact 0
		.amdhsa_exception_int_div_zero 0
	.end_amdhsa_kernel

amdhsa.kernels:
  - .agpr_count:     0
    .args:
      - .offset:         0
        .size:           176
        .value_kind:     by_value
      - .offset:         176
        .size:           4
        .value_kind:     hidden_block_count_x
      - .offset:         180
        .size:           4
        .value_kind:     hidden_block_count_y
      - .offset:         184
        .size:           4
        .value_kind:     hidden_block_count_z
      - .offset:         188
        .size:           2
        .value_kind:     hidden_group_size_x
      - .offset:         190
        .size:           2
        .value_kind:     hidden_group_size_y
      - .offset:         192
        .size:           2
        .value_kind:     hidden_group_size_z
      - .offset:         194
        .size:           2
        .value_kind:     hidden_remainder_x
      - .offset:         196
        .size:           2
        .value_kind:     hidden_remainder_y
      - .offset:         198
        .size:           2
        .value_kind:     hidden_remainder_z
      - .offset:         216
        .size:           8
        .value_kind:     hidden_global_offset_x
      - .offset:         224
        .size:           8
        .value_kind:     hidden_global_offset_y
      - .offset:         232
        .size:           8
        .value_kind:     hidden_global_offset_z
      - .offset:         240
        .size:           2
        .value_kind:     hidden_grid_dims
      - .offset:         264
        .size:           8
        .value_kind:     hidden_multigrid_sync_arg
      - .offset:         296
        .size:           4
        .value_kind:     hidden_dynamic_lds_size
    .group_segment_fixed_size: 0
    .kernarg_segment_align: 8
    .kernarg_segment_size: 432
    .language:       OpenCL C
    .language_version:
      - 2
      - 0
    .max_flat_workgroup_size: 512
    .name:           _Z10s5yoco_fwd4Ptrs
    .private_segment_fixed_size: 0
    .sgpr_count:     108
    .sgpr_spill_count: 25
    .symbol:         _Z10s5yoco_fwd4Ptrs.kd
    .uniform_work_group_size: 1
    .uses_dynamic_stack: false
    .vgpr_count:     249
    .vgpr_spill_count: 0
    .wavefront_size: 64
